# hgrn_a/hgrn_c: lower-bound logit loads issued behind the batched input loads (no stall behind the previous unit's stores); WO/DOWN bf16 row stores widened to 16 bytes
# speedup vs baseline: 1.0586x; 1.0044x over previous
.Lgm1_loop:
	v_add_u32_e32 v248, s30, v155
	v_add_u32_e32 v249, s30, v160
	v_mfma_f32_16x16x32_bf16 v[128:131], v[212:215], v[186:189], v[128:131]
	ds_read_b128 v[0:3], v248
	v_mfma_f32_16x16x32_bf16 v[80:83], v[212:215], v[190:193], v[80:83]
	ds_read_b128 v[16:19], v249 offset:8192
	v_mfma_f32_16x16x32_bf16 v[108:111], v[212:215], v[194:197], v[108:111]
	ds_read_b128 v[4:7], v248 offset:1024
	v_mfma_f32_16x16x32_bf16 v[132:135], v[212:215], v[208:211], v[132:135]
	ds_read_b128 v[20:23], v249 offset:9216
	v_mfma_f32_16x16x32_bf16 v[120:123], v[216:219], v[186:189], v[120:123]
	ds_read_b128 v[8:11], v248 offset:2048
	v_mfma_f32_16x16x32_bf16 v[72:75], v[216:219], v[190:193], v[72:75]
	ds_read_b128 v[162:165], v249 offset:10240
	v_mfma_f32_16x16x32_bf16 v[112:115], v[216:219], v[194:197], v[112:115]
	ds_read_b128 v[12:15], v248 offset:3072
	v_mfma_f32_16x16x32_bf16 v[136:139], v[216:219], v[208:211], v[136:139]
	ds_read_b128 v[166:169], v249 offset:11264
	v_mfma_f32_16x16x32_bf16 v[104:107], v[220:223], v[186:189], v[104:107]
	ds_read_b128 v[170:173], v249 offset:12288
	v_mfma_f32_16x16x32_bf16 v[64:67], v[220:223], v[190:193], v[64:67]
	ds_read_b128 v[174:177], v249 offset:13312
	v_mfma_f32_16x16x32_bf16 v[116:119], v[220:223], v[194:197], v[116:119]
	ds_read_b128 v[178:181], v249 offset:14336
	v_mfma_f32_16x16x32_bf16 v[140:143], v[220:223], v[208:211], v[140:143]
	ds_read_b128 v[182:185], v249 offset:15360
	s_add_u32 m0, s25, s24
	v_mfma_f32_16x16x32_bf16 v[100:103], v[224:227], v[186:189], v[100:103]
	global_load_lds_dwordx4 v244, s[26:27]
	v_mfma_f32_16x16x32_bf16 v[60:63], v[224:227], v[190:193], v[60:63]
	v_mfma_f32_16x16x32_bf16 v[124:127], v[224:227], v[194:197], v[124:127]
	s_add_u32 m0, m0, 0x1000
	v_mfma_f32_16x16x32_bf16 v[144:147], v[224:227], v[208:211], v[144:147]
	global_load_lds_dwordx4 v245, s[26:27]
	v_mfma_f32_16x16x32_bf16 v[68:71], v[228:231], v[186:189], v[68:71]
	v_mfma_f32_16x16x32_bf16 v[36:39], v[228:231], v[190:193], v[36:39]
	s_add_u32 m0, m0, 0x1000
	v_mfma_f32_16x16x32_bf16 v[88:91], v[228:231], v[194:197], v[88:91]
	global_load_lds_dwordx4 v244, s[28:29]
	v_mfma_f32_16x16x32_bf16 v[76:79], v[228:231], v[208:211], v[76:79]
	v_mfma_f32_16x16x32_bf16 v[56:59], v[232:235], v[186:189], v[56:59]
	s_add_u32 m0, m0, 0x1000
	v_mfma_f32_16x16x32_bf16 v[32:35], v[232:235], v[190:193], v[32:35]
	global_load_lds_dwordx4 v245, s[28:29]
	v_mfma_f32_16x16x32_bf16 v[92:95], v[232:235], v[194:197], v[92:95]
	v_mfma_f32_16x16x32_bf16 v[52:55], v[232:235], v[208:211], v[52:55]
	s_add_u32 m0, m0, 0x1000
	v_mfma_f32_16x16x32_bf16 v[48:51], v[236:239], v[186:189], v[48:51]
	global_load_lds_dwordx4 v246, s[28:29]
	v_mfma_f32_16x16x32_bf16 v[28:31], v[236:239], v[190:193], v[28:31]
	v_mfma_f32_16x16x32_bf16 v[96:99], v[236:239], v[194:197], v[96:99]
	s_add_u32 m0, m0, 0x1000
	v_mfma_f32_16x16x32_bf16 v[44:47], v[236:239], v[208:211], v[44:47]
	global_load_lds_dwordx4 v247, s[28:29]
	v_mfma_f32_16x16x32_bf16 v[40:43], v[240:243], v[186:189], v[40:43]
	v_mfma_f32_16x16x32_bf16 v[24:27], v[240:243], v[190:193], v[24:27]
	v_mfma_f32_16x16x32_bf16 v[84:87], v[240:243], v[194:197], v[84:87]
	v_mfma_f32_16x16x32_bf16 v[148:151], v[240:243], v[208:211], v[148:151]
	s_add_u32 s26, s26, 64
	s_addc_u32 s27, s27, 0
	s_add_u32 s28, s28, 64
	s_addc_u32 s29, s29, 0
	s_add_u32 s25, s25, 24576
	s_cmp_eq_u32 s25, 73728
	s_cselect_b32 s25, 0, s25
	s_add_u32 s30, s30, 24576
	s_cmp_eq_u32 s30, 73728
	s_cselect_b32 s30, 0, s30
	s_waitcnt vmcnt(6)
	s_waitcnt lgkmcnt(0)
	s_barrier
	v_add_u32_e32 v248, s30, v155
	v_add_u32_e32 v249, s30, v160
	v_mfma_f32_16x16x32_bf16 v[128:131], v[16:19], v[0:3], v[128:131]
	ds_read_b128 v[186:189], v248
	v_mfma_f32_16x16x32_bf16 v[80:83], v[16:19], v[4:7], v[80:83]
	ds_read_b128 v[212:215], v249 offset:8192
	v_mfma_f32_16x16x32_bf16 v[108:111], v[16:19], v[8:11], v[108:111]
	ds_read_b128 v[190:193], v248 offset:1024
	v_mfma_f32_16x16x32_bf16 v[132:135], v[16:19], v[12:15], v[132:135]
	ds_read_b128 v[216:219], v249 offset:9216
	v_mfma_f32_16x16x32_bf16 v[120:123], v[20:23], v[0:3], v[120:123]
	ds_read_b128 v[194:197], v248 offset:2048
	v_mfma_f32_16x16x32_bf16 v[72:75], v[20:23], v[4:7], v[72:75]
	ds_read_b128 v[220:223], v249 offset:10240
	v_mfma_f32_16x16x32_bf16 v[112:115], v[20:23], v[8:11], v[112:115]
	ds_read_b128 v[208:211], v248 offset:3072
	v_mfma_f32_16x16x32_bf16 v[136:139], v[20:23], v[12:15], v[136:139]
	ds_read_b128 v[224:227], v249 offset:11264
	v_mfma_f32_16x16x32_bf16 v[104:107], v[162:165], v[0:3], v[104:107]
	ds_read_b128 v[228:231], v249 offset:12288
	v_mfma_f32_16x16x32_bf16 v[64:67], v[162:165], v[4:7], v[64:67]
	ds_read_b128 v[232:235], v249 offset:13312
	v_mfma_f32_16x16x32_bf16 v[116:119], v[162:165], v[8:11], v[116:119]
	ds_read_b128 v[236:239], v249 offset:14336
	v_mfma_f32_16x16x32_bf16 v[140:143], v[162:165], v[12:15], v[140:143]
	ds_read_b128 v[240:243], v249 offset:15360
	s_add_u32 m0, s25, s24
	v_mfma_f32_16x16x32_bf16 v[100:103], v[166:169], v[0:3], v[100:103]
	global_load_lds_dwordx4 v244, s[26:27]
	v_mfma_f32_16x16x32_bf16 v[60:63], v[166:169], v[4:7], v[60:63]
	v_mfma_f32_16x16x32_bf16 v[124:127], v[166:169], v[8:11], v[124:127]
	s_add_u32 m0, m0, 0x1000
	v_mfma_f32_16x16x32_bf16 v[144:147], v[166:169], v[12:15], v[144:147]
	global_load_lds_dwordx4 v245, s[26:27]
	v_mfma_f32_16x16x32_bf16 v[68:71], v[170:173], v[0:3], v[68:71]
	v_mfma_f32_16x16x32_bf16 v[36:39], v[170:173], v[4:7], v[36:39]
	s_add_u32 m0, m0, 0x1000
	v_mfma_f32_16x16x32_bf16 v[88:91], v[170:173], v[8:11], v[88:91]
	global_load_lds_dwordx4 v244, s[28:29]
	v_mfma_f32_16x16x32_bf16 v[76:79], v[170:173], v[12:15], v[76:79]
	v_mfma_f32_16x16x32_bf16 v[56:59], v[174:177], v[0:3], v[56:59]
	s_add_u32 m0, m0, 0x1000
	v_mfma_f32_16x16x32_bf16 v[32:35], v[174:177], v[4:7], v[32:35]
	global_load_lds_dwordx4 v245, s[28:29]
	v_mfma_f32_16x16x32_bf16 v[92:95], v[174:177], v[8:11], v[92:95]
	v_mfma_f32_16x16x32_bf16 v[52:55], v[174:177], v[12:15], v[52:55]
	s_add_u32 m0, m0, 0x1000
	v_mfma_f32_16x16x32_bf16 v[48:51], v[178:181], v[0:3], v[48:51]
	global_load_lds_dwordx4 v246, s[28:29]
	v_mfma_f32_16x16x32_bf16 v[28:31], v[178:181], v[4:7], v[28:31]
	v_mfma_f32_16x16x32_bf16 v[96:99], v[178:181], v[8:11], v[96:99]
	s_add_u32 m0, m0, 0x1000
	v_mfma_f32_16x16x32_bf16 v[44:47], v[178:181], v[12:15], v[44:47]
	global_load_lds_dwordx4 v247, s[28:29]
	v_mfma_f32_16x16x32_bf16 v[40:43], v[182:185], v[0:3], v[40:43]
	v_mfma_f32_16x16x32_bf16 v[24:27], v[182:185], v[4:7], v[24:27]
	v_mfma_f32_16x16x32_bf16 v[84:87], v[182:185], v[8:11], v[84:87]
	v_mfma_f32_16x16x32_bf16 v[148:151], v[182:185], v[12:15], v[148:151]
	s_add_u32 s26, s26, 64
	s_addc_u32 s27, s27, 0
	s_add_u32 s28, s28, 64
	s_addc_u32 s29, s29, 0
	s_add_u32 s25, s25, 24576
	s_cmp_eq_u32 s25, 73728
	s_cselect_b32 s25, 0, s25
	s_add_u32 s30, s30, 24576
	s_cmp_eq_u32 s30, 73728
	s_cselect_b32 s30, 0, s30
	s_waitcnt vmcnt(6)
	s_waitcnt lgkmcnt(0)
	s_barrier
	s_sub_u32 s31, s31, 1
	s_cmp_lg_u32 s31, 0
	s_cbranch_scc1 .Lgm1_loop
	v_add_u32_e32 v248, s30, v155
	v_add_u32_e32 v249, s30, v160
	v_mfma_f32_16x16x32_bf16 v[128:131], v[212:215], v[186:189], v[128:131]
	ds_read_b128 v[0:3], v248
	v_mfma_f32_16x16x32_bf16 v[80:83], v[212:215], v[190:193], v[80:83]
	ds_read_b128 v[16:19], v249 offset:8192
	v_mfma_f32_16x16x32_bf16 v[108:111], v[212:215], v[194:197], v[108:111]
	ds_read_b128 v[4:7], v248 offset:1024
	v_mfma_f32_16x16x32_bf16 v[132:135], v[212:215], v[208:211], v[132:135]
	ds_read_b128 v[20:23], v249 offset:9216
	v_mfma_f32_16x16x32_bf16 v[120:123], v[216:219], v[186:189], v[120:123]
	ds_read_b128 v[8:11], v248 offset:2048
	v_mfma_f32_16x16x32_bf16 v[72:75], v[216:219], v[190:193], v[72:75]
	ds_read_b128 v[162:165], v249 offset:10240
	v_mfma_f32_16x16x32_bf16 v[112:115], v[216:219], v[194:197], v[112:115]
	ds_read_b128 v[12:15], v248 offset:3072
	v_mfma_f32_16x16x32_bf16 v[136:139], v[216:219], v[208:211], v[136:139]
	ds_read_b128 v[166:169], v249 offset:11264
	v_mfma_f32_16x16x32_bf16 v[104:107], v[220:223], v[186:189], v[104:107]
	ds_read_b128 v[170:173], v249 offset:12288
	v_mfma_f32_16x16x32_bf16 v[64:67], v[220:223], v[190:193], v[64:67]
	ds_read_b128 v[174:177], v249 offset:13312
	v_mfma_f32_16x16x32_bf16 v[116:119], v[220:223], v[194:197], v[116:119]
	ds_read_b128 v[178:181], v249 offset:14336
	v_mfma_f32_16x16x32_bf16 v[140:143], v[220:223], v[208:211], v[140:143]
	ds_read_b128 v[182:185], v249 offset:15360
	s_add_u32 m0, s25, s24
	v_mfma_f32_16x16x32_bf16 v[100:103], v[224:227], v[186:189], v[100:103]
	global_load_lds_dwordx4 v244, s[26:27]
	v_mfma_f32_16x16x32_bf16 v[60:63], v[224:227], v[190:193], v[60:63]
	v_mfma_f32_16x16x32_bf16 v[124:127], v[224:227], v[194:197], v[124:127]
	s_add_u32 m0, m0, 0x1000
	v_mfma_f32_16x16x32_bf16 v[144:147], v[224:227], v[208:211], v[144:147]
	global_load_lds_dwordx4 v245, s[26:27]
	v_mfma_f32_16x16x32_bf16 v[68:71], v[228:231], v[186:189], v[68:71]
	v_mfma_f32_16x16x32_bf16 v[36:39], v[228:231], v[190:193], v[36:39]
	s_add_u32 m0, m0, 0x1000
	v_mfma_f32_16x16x32_bf16 v[88:91], v[228:231], v[194:197], v[88:91]
	global_load_lds_dwordx4 v244, s[28:29]
	v_mfma_f32_16x16x32_bf16 v[76:79], v[228:231], v[208:211], v[76:79]
	v_mfma_f32_16x16x32_bf16 v[56:59], v[232:235], v[186:189], v[56:59]
	s_add_u32 m0, m0, 0x1000
	v_mfma_f32_16x16x32_bf16 v[32:35], v[232:235], v[190:193], v[32:35]
	global_load_lds_dwordx4 v245, s[28:29]
	v_mfma_f32_16x16x32_bf16 v[92:95], v[232:235], v[194:197], v[92:95]
	v_mfma_f32_16x16x32_bf16 v[52:55], v[232:235], v[208:211], v[52:55]
	s_add_u32 m0, m0, 0x1000
	v_mfma_f32_16x16x32_bf16 v[48:51], v[236:239], v[186:189], v[48:51]
	global_load_lds_dwordx4 v246, s[28:29]
	v_mfma_f32_16x16x32_bf16 v[28:31], v[236:239], v[190:193], v[28:31]
	v_mfma_f32_16x16x32_bf16 v[96:99], v[236:239], v[194:197], v[96:99]
	s_add_u32 m0, m0, 0x1000
	v_mfma_f32_16x16x32_bf16 v[44:47], v[236:239], v[208:211], v[44:47]
	global_load_lds_dwordx4 v247, s[28:29]
	v_mfma_f32_16x16x32_bf16 v[40:43], v[240:243], v[186:189], v[40:43]
	v_mfma_f32_16x16x32_bf16 v[24:27], v[240:243], v[190:193], v[24:27]
	v_mfma_f32_16x16x32_bf16 v[84:87], v[240:243], v[194:197], v[84:87]
	v_mfma_f32_16x16x32_bf16 v[148:151], v[240:243], v[208:211], v[148:151]
	s_add_u32 s26, s26, 64
	s_addc_u32 s27, s27, 0
	s_add_u32 s28, s28, 64
	s_addc_u32 s29, s29, 0
	s_add_u32 s25, s25, 24576
	s_cmp_eq_u32 s25, 73728
	s_cselect_b32 s25, 0, s25
	s_add_u32 s30, s30, 24576
	s_cmp_eq_u32 s30, 73728
	s_cselect_b32 s30, 0, s30
	s_waitcnt vmcnt(6)
	s_waitcnt lgkmcnt(0)
	s_barrier
	v_add_u32_e32 v248, s30, v155
	v_add_u32_e32 v249, s30, v160
	v_mfma_f32_16x16x32_bf16 v[128:131], v[16:19], v[0:3], v[128:131]
	ds_read_b128 v[186:189], v248
	v_mfma_f32_16x16x32_bf16 v[80:83], v[16:19], v[4:7], v[80:83]
	ds_read_b128 v[212:215], v249 offset:8192
	v_mfma_f32_16x16x32_bf16 v[108:111], v[16:19], v[8:11], v[108:111]
	ds_read_b128 v[190:193], v248 offset:1024
	v_mfma_f32_16x16x32_bf16 v[132:135], v[16:19], v[12:15], v[132:135]
	ds_read_b128 v[216:219], v249 offset:9216
	v_mfma_f32_16x16x32_bf16 v[120:123], v[20:23], v[0:3], v[120:123]
	ds_read_b128 v[194:197], v248 offset:2048
	v_mfma_f32_16x16x32_bf16 v[72:75], v[20:23], v[4:7], v[72:75]
	ds_read_b128 v[220:223], v249 offset:10240
	v_mfma_f32_16x16x32_bf16 v[112:115], v[20:23], v[8:11], v[112:115]
	ds_read_b128 v[208:211], v248 offset:3072
	v_mfma_f32_16x16x32_bf16 v[136:139], v[20:23], v[12:15], v[136:139]
	ds_read_b128 v[224:227], v249 offset:11264
	v_mfma_f32_16x16x32_bf16 v[104:107], v[162:165], v[0:3], v[104:107]
	ds_read_b128 v[228:231], v249 offset:12288
	v_mfma_f32_16x16x32_bf16 v[64:67], v[162:165], v[4:7], v[64:67]
	ds_read_b128 v[232:235], v249 offset:13312
	v_mfma_f32_16x16x32_bf16 v[116:119], v[162:165], v[8:11], v[116:119]
	ds_read_b128 v[236:239], v249 offset:14336
	v_mfma_f32_16x16x32_bf16 v[140:143], v[162:165], v[12:15], v[140:143]
	ds_read_b128 v[240:243], v249 offset:15360
	v_mfma_f32_16x16x32_bf16 v[100:103], v[166:169], v[0:3], v[100:103]
	v_mfma_f32_16x16x32_bf16 v[60:63], v[166:169], v[4:7], v[60:63]
	v_mfma_f32_16x16x32_bf16 v[124:127], v[166:169], v[8:11], v[124:127]
	v_mfma_f32_16x16x32_bf16 v[144:147], v[166:169], v[12:15], v[144:147]
	v_mfma_f32_16x16x32_bf16 v[68:71], v[170:173], v[0:3], v[68:71]
	v_mfma_f32_16x16x32_bf16 v[36:39], v[170:173], v[4:7], v[36:39]
	v_mfma_f32_16x16x32_bf16 v[88:91], v[170:173], v[8:11], v[88:91]
	v_mfma_f32_16x16x32_bf16 v[76:79], v[170:173], v[12:15], v[76:79]
	v_mfma_f32_16x16x32_bf16 v[56:59], v[174:177], v[0:3], v[56:59]
	v_mfma_f32_16x16x32_bf16 v[32:35], v[174:177], v[4:7], v[32:35]
	v_mfma_f32_16x16x32_bf16 v[92:95], v[174:177], v[8:11], v[92:95]
	v_mfma_f32_16x16x32_bf16 v[52:55], v[174:177], v[12:15], v[52:55]
	v_mfma_f32_16x16x32_bf16 v[48:51], v[178:181], v[0:3], v[48:51]
	v_mfma_f32_16x16x32_bf16 v[28:31], v[178:181], v[4:7], v[28:31]
	v_mfma_f32_16x16x32_bf16 v[96:99], v[178:181], v[8:11], v[96:99]
	v_mfma_f32_16x16x32_bf16 v[44:47], v[178:181], v[12:15], v[44:47]
	v_mfma_f32_16x16x32_bf16 v[40:43], v[182:185], v[0:3], v[40:43]
	v_mfma_f32_16x16x32_bf16 v[24:27], v[182:185], v[4:7], v[24:27]
	v_mfma_f32_16x16x32_bf16 v[84:87], v[182:185], v[8:11], v[84:87]
	v_mfma_f32_16x16x32_bf16 v[148:151], v[182:185], v[12:15], v[148:151]
	s_add_u32 s30, s30, 24576
	s_cmp_eq_u32 s30, 73728
	s_cselect_b32 s30, 0, s30
	s_waitcnt vmcnt(0)
	s_waitcnt lgkmcnt(0)
	s_barrier
	v_add_u32_e32 v248, s30, v155
	v_add_u32_e32 v249, s30, v160
	v_mfma_f32_16x16x32_bf16 v[128:131], v[212:215], v[186:189], v[128:131]
	ds_read_b128 v[0:3], v248
	v_mfma_f32_16x16x32_bf16 v[80:83], v[212:215], v[190:193], v[80:83]
	ds_read_b128 v[16:19], v249 offset:8192
	v_mfma_f32_16x16x32_bf16 v[108:111], v[212:215], v[194:197], v[108:111]
	ds_read_b128 v[4:7], v248 offset:1024
	v_mfma_f32_16x16x32_bf16 v[132:135], v[212:215], v[208:211], v[132:135]
	ds_read_b128 v[20:23], v249 offset:9216
	v_mfma_f32_16x16x32_bf16 v[120:123], v[216:219], v[186:189], v[120:123]
	ds_read_b128 v[8:11], v248 offset:2048
	v_mfma_f32_16x16x32_bf16 v[72:75], v[216:219], v[190:193], v[72:75]
	ds_read_b128 v[162:165], v249 offset:10240
	v_mfma_f32_16x16x32_bf16 v[112:115], v[216:219], v[194:197], v[112:115]
	ds_read_b128 v[12:15], v248 offset:3072
	v_mfma_f32_16x16x32_bf16 v[136:139], v[216:219], v[208:211], v[136:139]
	ds_read_b128 v[166:169], v249 offset:11264
	v_mfma_f32_16x16x32_bf16 v[104:107], v[220:223], v[186:189], v[104:107]
	ds_read_b128 v[170:173], v249 offset:12288
	v_mfma_f32_16x16x32_bf16 v[64:67], v[220:223], v[190:193], v[64:67]
	ds_read_b128 v[174:177], v249 offset:13312
	v_mfma_f32_16x16x32_bf16 v[116:119], v[220:223], v[194:197], v[116:119]
	ds_read_b128 v[178:181], v249 offset:14336
	v_mfma_f32_16x16x32_bf16 v[140:143], v[220:223], v[208:211], v[140:143]
	ds_read_b128 v[182:185], v249 offset:15360
	v_mfma_f32_16x16x32_bf16 v[100:103], v[224:227], v[186:189], v[100:103]
	v_mfma_f32_16x16x32_bf16 v[60:63], v[224:227], v[190:193], v[60:63]
	v_mfma_f32_16x16x32_bf16 v[124:127], v[224:227], v[194:197], v[124:127]
	v_mfma_f32_16x16x32_bf16 v[144:147], v[224:227], v[208:211], v[144:147]
	v_mfma_f32_16x16x32_bf16 v[68:71], v[228:231], v[186:189], v[68:71]
	v_mfma_f32_16x16x32_bf16 v[36:39], v[228:231], v[190:193], v[36:39]
	v_mfma_f32_16x16x32_bf16 v[88:91], v[228:231], v[194:197], v[88:91]
	v_mfma_f32_16x16x32_bf16 v[76:79], v[228:231], v[208:211], v[76:79]
	v_mfma_f32_16x16x32_bf16 v[56:59], v[232:235], v[186:189], v[56:59]
	v_mfma_f32_16x16x32_bf16 v[32:35], v[232:235], v[190:193], v[32:35]
	v_mfma_f32_16x16x32_bf16 v[92:95], v[232:235], v[194:197], v[92:95]
	v_mfma_f32_16x16x32_bf16 v[52:55], v[232:235], v[208:211], v[52:55]
	v_mfma_f32_16x16x32_bf16 v[48:51], v[236:239], v[186:189], v[48:51]
	v_mfma_f32_16x16x32_bf16 v[28:31], v[236:239], v[190:193], v[28:31]
	v_mfma_f32_16x16x32_bf16 v[96:99], v[236:239], v[194:197], v[96:99]
	v_mfma_f32_16x16x32_bf16 v[44:47], v[236:239], v[208:211], v[44:47]
	v_mfma_f32_16x16x32_bf16 v[40:43], v[240:243], v[186:189], v[40:43]
	v_mfma_f32_16x16x32_bf16 v[24:27], v[240:243], v[190:193], v[24:27]
	v_mfma_f32_16x16x32_bf16 v[84:87], v[240:243], v[194:197], v[84:87]
	v_mfma_f32_16x16x32_bf16 v[148:151], v[240:243], v[208:211], v[148:151]
	s_add_u32 s30, s30, 24576
	s_cmp_eq_u32 s30, 73728
	s_cselect_b32 s30, 0, s30
	s_waitcnt lgkmcnt(0)
	s_barrier
	v_mfma_f32_16x16x32_bf16 v[128:131], v[16:19], v[0:3], v[128:131]
	v_mfma_f32_16x16x32_bf16 v[80:83], v[16:19], v[4:7], v[80:83]
	v_mfma_f32_16x16x32_bf16 v[108:111], v[16:19], v[8:11], v[108:111]
	v_mfma_f32_16x16x32_bf16 v[132:135], v[16:19], v[12:15], v[132:135]
	v_mfma_f32_16x16x32_bf16 v[120:123], v[20:23], v[0:3], v[120:123]
	v_mfma_f32_16x16x32_bf16 v[72:75], v[20:23], v[4:7], v[72:75]
	v_mfma_f32_16x16x32_bf16 v[112:115], v[20:23], v[8:11], v[112:115]
	v_mfma_f32_16x16x32_bf16 v[136:139], v[20:23], v[12:15], v[136:139]
	v_mfma_f32_16x16x32_bf16 v[104:107], v[162:165], v[0:3], v[104:107]
	v_mfma_f32_16x16x32_bf16 v[64:67], v[162:165], v[4:7], v[64:67]
	v_mfma_f32_16x16x32_bf16 v[116:119], v[162:165], v[8:11], v[116:119]
	v_mfma_f32_16x16x32_bf16 v[140:143], v[162:165], v[12:15], v[140:143]
	v_mfma_f32_16x16x32_bf16 v[100:103], v[166:169], v[0:3], v[100:103]
	v_mfma_f32_16x16x32_bf16 v[60:63], v[166:169], v[4:7], v[60:63]
	v_mfma_f32_16x16x32_bf16 v[124:127], v[166:169], v[8:11], v[124:127]
	v_mfma_f32_16x16x32_bf16 v[144:147], v[166:169], v[12:15], v[144:147]
	v_mfma_f32_16x16x32_bf16 v[68:71], v[170:173], v[0:3], v[68:71]
	v_mfma_f32_16x16x32_bf16 v[36:39], v[170:173], v[4:7], v[36:39]
	v_mfma_f32_16x16x32_bf16 v[88:91], v[170:173], v[8:11], v[88:91]
	v_mfma_f32_16x16x32_bf16 v[76:79], v[170:173], v[12:15], v[76:79]
	v_mfma_f32_16x16x32_bf16 v[56:59], v[174:177], v[0:3], v[56:59]
	v_mfma_f32_16x16x32_bf16 v[32:35], v[174:177], v[4:7], v[32:35]
	v_mfma_f32_16x16x32_bf16 v[92:95], v[174:177], v[8:11], v[92:95]
	v_mfma_f32_16x16x32_bf16 v[52:55], v[174:177], v[12:15], v[52:55]
	v_mfma_f32_16x16x32_bf16 v[48:51], v[178:181], v[0:3], v[48:51]
	v_mfma_f32_16x16x32_bf16 v[28:31], v[178:181], v[4:7], v[28:31]
	v_mfma_f32_16x16x32_bf16 v[96:99], v[178:181], v[8:11], v[96:99]
	v_mfma_f32_16x16x32_bf16 v[44:47], v[178:181], v[12:15], v[44:47]
	v_mfma_f32_16x16x32_bf16 v[40:43], v[182:185], v[0:3], v[40:43]
	v_mfma_f32_16x16x32_bf16 v[24:27], v[182:185], v[4:7], v[24:27]
	v_mfma_f32_16x16x32_bf16 v[84:87], v[182:185], v[8:11], v[84:87]
	v_mfma_f32_16x16x32_bf16 v[148:151], v[182:185], v[12:15], v[148:151]
	v_mov_b32 v250, v198
	s_nop 0
	v_and_b32_e32 v251, 15, v250
	v_bfe_u32 v156, v250, 4, 2
	v_bfe_u32 v157, v250, 6, 1
	v_bfe_u32 v158, v250, 7, 1
	v_lshl_add_u32 v158, v158, 6, s10
	v_add_u32_e32 v158, v158, v251
	v_lshl_add_u32 v157, v157, 7, s11
	v_lshl_add_u32 v159, v156, 2, v157
	v_lshlrev_b32_e32 v246, 2, v159
	v_lshl_add_u32 v244, v158, 12, v246
	v_lshlrev_b32_e32 v161, 1, v159
	v_lshl_add_u32 v245, v158, 11, v161
	v_and_b32_e32 v254, 1, v156
	v_mul_u32_u24_e32 v254, 24, v254
	v_add_u32_e32 v254, v254, v245
	v_lshrrev_b32_e32 v161, 6, v157
	v_lshlrev_b32_e32 v161, 2, v161
	v_lshl_add_u32 v247, v158, 6, v161
	v_xor_b32_e32 v248, 16, v200
	v_lshlrev_b32_e32 v248, 2, v248
	v_xor_b32_e32 v249, 32, v200
	v_lshlrev_b32_e32 v249, 2, v249
	s_mov_b32 s24, s6
	s_mov_b32 s25, s7
	s_mov_b32 s26, s78
	s_mov_b32 s27, s79
	v_readlane_b32 s28, v253, 21
	v_readlane_b32 s29, v253, 22
	s_mov_b32 s30, s94
	s_mov_b32 s31, s95
	global_load_dwordx4 v[208:211], v246, s[8:9]
	global_load_dwordx4 v[212:215], v246, s[8:9] offset:64
	global_load_dwordx4 v[216:219], v246, s[8:9] offset:128
	global_load_dwordx4 v[220:223], v246, s[8:9] offset:192
	global_load_dwordx4 v[224:227], v246, s[8:9] offset:256
	global_load_dwordx4 v[228:231], v246, s[8:9] offset:320
	global_load_dwordx4 v[232:235], v246, s[8:9] offset:384
	global_load_dwordx4 v[236:239], v246, s[8:9] offset:448
	global_load_dwordx4 v[0:3], v244, s[24:25]
	global_load_dwordx4 v[4:7], v244, s[24:25] offset:64
	global_load_dwordx4 v[8:11], v244, s[24:25] offset:128
	global_load_dwordx4 v[12:15], v244, s[24:25] offset:192
	global_load_dwordx4 v[16:19], v244, s[24:25] offset:256
	global_load_dwordx4 v[20:23], v244, s[24:25] offset:320
	global_load_dwordx4 v[162:165], v244, s[24:25] offset:384
	global_load_dwordx4 v[166:169], v244, s[24:25] offset:448
	s_add_u32 s24, s24, 0x10000
	s_addc_u32 s25, s25, 0
	global_load_dwordx4 v[170:173], v244, s[24:25]
	global_load_dwordx4 v[174:177], v244, s[24:25] offset:64
	global_load_dwordx4 v[178:181], v244, s[24:25] offset:128
	global_load_dwordx4 v[182:185], v244, s[24:25] offset:192
	global_load_dwordx4 v[186:189], v244, s[24:25] offset:256
	global_load_dwordx4 v[190:193], v244, s[24:25] offset:320
	global_load_dwordx4 v[194:197], v244, s[24:25] offset:384
	global_load_dwordx4 v[240:243], v244, s[24:25] offset:448
	s_add_u32 s24, s24, 0x10000
	s_addc_u32 s25, s25, 0
	s_waitcnt vmcnt(12)
	v_add_f32_e32 v0, v128, v0
	v_add_f32_e32 v1, v129, v1
	v_add_f32_e32 v2, v130, v2
	v_add_f32_e32 v3, v131, v3
	global_store_dwordx4 v244, v[0:3], s[26:27]
	v_mul_f32_e32 v158, v0, v0
	v_mul_f32_e32 v159, v1, v1
	v_mul_f32_e32 v250, v2, v2
	v_mul_f32_e32 v251, v3, v3
	v_add_f32_e32 v158, v158, v159
	v_add_f32_e32 v250, v250, v251
	v_add_f32_e32 v161, v158, v250
	v_mul_f32_e32 v156, v0, v208
	v_mul_f32_e32 v157, v1, v209
	v_mul_f32_e32 v158, v2, v210
	v_mul_f32_e32 v159, v3, v211
	v_cvt_pk_bf16_f32 v156, v156, v157
	v_cvt_pk_bf16_f32 v157, v158, v159
	v_add_f32_e32 v4, v120, v4
	v_add_f32_e32 v5, v121, v5
	v_add_f32_e32 v6, v122, v6
	v_add_f32_e32 v7, v123, v7
	global_store_dwordx4 v244, v[4:7], s[26:27] offset:64
	v_mul_f32_e32 v158, v4, v4
	v_mul_f32_e32 v159, v5, v5
	v_mul_f32_e32 v250, v6, v6
	v_mul_f32_e32 v251, v7, v7
	v_add_f32_e32 v158, v158, v159
	v_add_f32_e32 v250, v250, v251
	v_add_f32_e32 v158, v158, v250
	v_add_f32_e32 v161, v161, v158
	v_mul_f32_e32 v158, v4, v212
	v_mul_f32_e32 v159, v5, v213
	v_mul_f32_e32 v250, v6, v214
	v_mul_f32_e32 v251, v7, v215
	v_cvt_pk_bf16_f32 v158, v158, v159
	v_cvt_pk_bf16_f32 v159, v250, v251
	s_nop 1
	v_permlane16_swap_b32_e32 v156, v158
	v_permlane16_swap_b32_e32 v157, v159
	global_store_dwordx4 v254, v[156:159], s[28:29]
	v_add_f32_e32 v8, v104, v8
	v_add_f32_e32 v9, v105, v9
	v_add_f32_e32 v10, v106, v10
	v_add_f32_e32 v11, v107, v11
	global_store_dwordx4 v244, v[8:11], s[26:27] offset:128
	v_mul_f32_e32 v158, v8, v8
	v_mul_f32_e32 v159, v9, v9
	v_mul_f32_e32 v250, v10, v10
	v_mul_f32_e32 v251, v11, v11
	v_add_f32_e32 v158, v158, v159
	v_add_f32_e32 v250, v250, v251
	v_add_f32_e32 v158, v158, v250
	v_add_f32_e32 v161, v161, v158
	v_mul_f32_e32 v156, v8, v216
	v_mul_f32_e32 v157, v9, v217
	v_mul_f32_e32 v158, v10, v218
	v_mul_f32_e32 v159, v11, v219
	v_cvt_pk_bf16_f32 v156, v156, v157
	v_cvt_pk_bf16_f32 v157, v158, v159
	v_add_f32_e32 v12, v100, v12
	v_add_f32_e32 v13, v101, v13
	v_add_f32_e32 v14, v102, v14
	v_add_f32_e32 v15, v103, v15
	global_store_dwordx4 v244, v[12:15], s[26:27] offset:192
	v_mul_f32_e32 v158, v12, v12
	v_mul_f32_e32 v159, v13, v13
	v_mul_f32_e32 v250, v14, v14
	v_mul_f32_e32 v251, v15, v15
	v_add_f32_e32 v158, v158, v159
	v_add_f32_e32 v250, v250, v251
	v_add_f32_e32 v158, v158, v250
	v_add_f32_e32 v161, v161, v158
	v_mul_f32_e32 v158, v12, v220
	v_mul_f32_e32 v159, v13, v221
	v_mul_f32_e32 v250, v14, v222
	v_mul_f32_e32 v251, v15, v223
	v_cvt_pk_bf16_f32 v158, v158, v159
	v_cvt_pk_bf16_f32 v159, v250, v251
	s_nop 1
	v_permlane16_swap_b32_e32 v156, v158
	v_permlane16_swap_b32_e32 v157, v159
	global_store_dwordx4 v254, v[156:159], s[28:29] offset:64
	ds_bpermute_b32 v158, v248, v161
	s_waitcnt lgkmcnt(0)
	v_add_f32_e32 v161, v161, v158
	ds_bpermute_b32 v158, v249, v161
	s_waitcnt lgkmcnt(0)
	v_add_f32_e32 v161, v161, v158
	global_store_dword v247, v161, s[30:31]
	global_load_dwordx4 v[0:3], v244, s[24:25]
	global_load_dwordx4 v[4:7], v244, s[24:25] offset:64
	global_load_dwordx4 v[8:11], v244, s[24:25] offset:128
	global_load_dwordx4 v[12:15], v244, s[24:25] offset:192
	s_waitcnt vmcnt(19)
	v_add_f32_e32 v16, v68, v16
	v_add_f32_e32 v17, v69, v17
	v_add_f32_e32 v18, v70, v18
	v_add_f32_e32 v19, v71, v19
	global_store_dwordx4 v244, v[16:19], s[26:27] offset:256
	v_mul_f32_e32 v158, v16, v16
	v_mul_f32_e32 v159, v17, v17
	v_mul_f32_e32 v250, v18, v18
	v_mul_f32_e32 v251, v19, v19
	v_add_f32_e32 v158, v158, v159
	v_add_f32_e32 v250, v250, v251
	v_add_f32_e32 v161, v158, v250
	v_mul_f32_e32 v156, v16, v224
	v_mul_f32_e32 v157, v17, v225
	v_mul_f32_e32 v158, v18, v226
	v_mul_f32_e32 v159, v19, v227
	v_cvt_pk_bf16_f32 v156, v156, v157
	v_cvt_pk_bf16_f32 v157, v158, v159
	v_add_f32_e32 v20, v56, v20
	v_add_f32_e32 v21, v57, v21
	v_add_f32_e32 v22, v58, v22
	v_add_f32_e32 v23, v59, v23
	global_store_dwordx4 v244, v[20:23], s[26:27] offset:320
	v_mul_f32_e32 v158, v20, v20
	v_mul_f32_e32 v159, v21, v21
	v_mul_f32_e32 v250, v22, v22
	v_mul_f32_e32 v251, v23, v23
	v_add_f32_e32 v158, v158, v159
	v_add_f32_e32 v250, v250, v251
	v_add_f32_e32 v158, v158, v250
	v_add_f32_e32 v161, v161, v158
	v_mul_f32_e32 v158, v20, v228
	v_mul_f32_e32 v159, v21, v229
	v_mul_f32_e32 v250, v22, v230
	v_mul_f32_e32 v251, v23, v231
	v_cvt_pk_bf16_f32 v158, v158, v159
	v_cvt_pk_bf16_f32 v159, v250, v251
	s_nop 1
	v_permlane16_swap_b32_e32 v156, v158
	v_permlane16_swap_b32_e32 v157, v159
	global_store_dwordx4 v254, v[156:159], s[28:29] offset:128
	v_add_f32_e32 v162, v48, v162
	v_add_f32_e32 v163, v49, v163
	v_add_f32_e32 v164, v50, v164
	v_add_f32_e32 v165, v51, v165
	global_store_dwordx4 v244, v[162:165], s[26:27] offset:384
	v_mul_f32_e32 v158, v162, v162
	v_mul_f32_e32 v159, v163, v163
	v_mul_f32_e32 v250, v164, v164
	v_mul_f32_e32 v251, v165, v165
	v_add_f32_e32 v158, v158, v159
	v_add_f32_e32 v250, v250, v251
	v_add_f32_e32 v158, v158, v250
	v_add_f32_e32 v161, v161, v158
	v_mul_f32_e32 v156, v162, v232
	v_mul_f32_e32 v157, v163, v233
	v_mul_f32_e32 v158, v164, v234
	v_mul_f32_e32 v159, v165, v235
	v_cvt_pk_bf16_f32 v156, v156, v157
	v_cvt_pk_bf16_f32 v157, v158, v159
	v_add_f32_e32 v166, v40, v166
	v_add_f32_e32 v167, v41, v167
	v_add_f32_e32 v168, v42, v168
	v_add_f32_e32 v169, v43, v169
	global_store_dwordx4 v244, v[166:169], s[26:27] offset:448
	v_mul_f32_e32 v158, v166, v166
	v_mul_f32_e32 v159, v167, v167
	v_mul_f32_e32 v250, v168, v168
	v_mul_f32_e32 v251, v169, v169
	v_add_f32_e32 v158, v158, v159
	v_add_f32_e32 v250, v250, v251
	v_add_f32_e32 v158, v158, v250
	v_add_f32_e32 v161, v161, v158
	v_mul_f32_e32 v158, v166, v236
	v_mul_f32_e32 v159, v167, v237
	v_mul_f32_e32 v250, v168, v238
	v_mul_f32_e32 v251, v169, v239
	v_cvt_pk_bf16_f32 v158, v158, v159
	v_cvt_pk_bf16_f32 v159, v250, v251
	s_nop 1
	v_permlane16_swap_b32_e32 v156, v158
	v_permlane16_swap_b32_e32 v157, v159
	global_store_dwordx4 v254, v[156:159], s[28:29] offset:192
	ds_bpermute_b32 v158, v248, v161
	s_waitcnt lgkmcnt(0)
	v_add_f32_e32 v161, v161, v158
	ds_bpermute_b32 v158, v249, v161
	s_waitcnt lgkmcnt(0)
	v_add_f32_e32 v161, v161, v158
	global_store_dword v247, v161, s[30:31] offset:4
	s_add_u32 s26, s26, 0x10000
	s_addc_u32 s27, s27, 0
	s_add_u32 s28, s28, 0x8000
	s_addc_u32 s29, s29, 0
	s_add_u32 s30, s30, 0x400
	s_addc_u32 s31, s31, 0
	global_load_dwordx4 v[16:19], v244, s[24:25] offset:256
	global_load_dwordx4 v[20:23], v244, s[24:25] offset:320
	global_load_dwordx4 v[162:165], v244, s[24:25] offset:384
	global_load_dwordx4 v[166:169], v244, s[24:25] offset:448
	s_add_u32 s24, s24, 0x10000
	s_addc_u32 s25, s25, 0
	s_waitcnt vmcnt(26)
	v_add_f32_e32 v170, v80, v170
	v_add_f32_e32 v171, v81, v171
	v_add_f32_e32 v172, v82, v172
	v_add_f32_e32 v173, v83, v173
	global_store_dwordx4 v244, v[170:173], s[26:27]
	v_mul_f32_e32 v158, v170, v170
	v_mul_f32_e32 v159, v171, v171
	v_mul_f32_e32 v250, v172, v172
	v_mul_f32_e32 v251, v173, v173
	v_add_f32_e32 v158, v158, v159
	v_add_f32_e32 v250, v250, v251
	v_add_f32_e32 v161, v158, v250
	v_mul_f32_e32 v156, v170, v208
	v_mul_f32_e32 v157, v171, v209
	v_mul_f32_e32 v158, v172, v210
	v_mul_f32_e32 v159, v173, v211
	v_cvt_pk_bf16_f32 v156, v156, v157
	v_cvt_pk_bf16_f32 v157, v158, v159
	v_add_f32_e32 v174, v72, v174
	v_add_f32_e32 v175, v73, v175
	v_add_f32_e32 v176, v74, v176
	v_add_f32_e32 v177, v75, v177
	global_store_dwordx4 v244, v[174:177], s[26:27] offset:64
	v_mul_f32_e32 v158, v174, v174
	v_mul_f32_e32 v159, v175, v175
	v_mul_f32_e32 v250, v176, v176
	v_mul_f32_e32 v251, v177, v177
	v_add_f32_e32 v158, v158, v159
	v_add_f32_e32 v250, v250, v251
	v_add_f32_e32 v158, v158, v250
	v_add_f32_e32 v161, v161, v158
	v_mul_f32_e32 v158, v174, v212
	v_mul_f32_e32 v159, v175, v213
	v_mul_f32_e32 v250, v176, v214
	v_mul_f32_e32 v251, v177, v215
	v_cvt_pk_bf16_f32 v158, v158, v159
	v_cvt_pk_bf16_f32 v159, v250, v251
	s_nop 1
	v_permlane16_swap_b32_e32 v156, v158
	v_permlane16_swap_b32_e32 v157, v159
	global_store_dwordx4 v254, v[156:159], s[28:29]
	v_add_f32_e32 v178, v64, v178
	v_add_f32_e32 v179, v65, v179
	v_add_f32_e32 v180, v66, v180
	v_add_f32_e32 v181, v67, v181
	global_store_dwordx4 v244, v[178:181], s[26:27] offset:128
	v_mul_f32_e32 v158, v178, v178
	v_mul_f32_e32 v159, v179, v179
	v_mul_f32_e32 v250, v180, v180
	v_mul_f32_e32 v251, v181, v181
	v_add_f32_e32 v158, v158, v159
	v_add_f32_e32 v250, v250, v251
	v_add_f32_e32 v158, v158, v250
	v_add_f32_e32 v161, v161, v158
	v_mul_f32_e32 v156, v178, v216
	v_mul_f32_e32 v157, v179, v217
	v_mul_f32_e32 v158, v180, v218
	v_mul_f32_e32 v159, v181, v219
	v_cvt_pk_bf16_f32 v156, v156, v157
	v_cvt_pk_bf16_f32 v157, v158, v159
	v_add_f32_e32 v182, v60, v182
	v_add_f32_e32 v183, v61, v183
	v_add_f32_e32 v184, v62, v184
	v_add_f32_e32 v185, v63, v185
	global_store_dwordx4 v244, v[182:185], s[26:27] offset:192
	v_mul_f32_e32 v158, v182, v182
	v_mul_f32_e32 v159, v183, v183
	v_mul_f32_e32 v250, v184, v184
	v_mul_f32_e32 v251, v185, v185
	v_add_f32_e32 v158, v158, v159
	v_add_f32_e32 v250, v250, v251
	v_add_f32_e32 v158, v158, v250
	v_add_f32_e32 v161, v161, v158
	v_mul_f32_e32 v158, v182, v220
	v_mul_f32_e32 v159, v183, v221
	v_mul_f32_e32 v250, v184, v222
	v_mul_f32_e32 v251, v185, v223
	v_cvt_pk_bf16_f32 v158, v158, v159
	v_cvt_pk_bf16_f32 v159, v250, v251
	s_nop 1
	v_permlane16_swap_b32_e32 v156, v158
	v_permlane16_swap_b32_e32 v157, v159
	global_store_dwordx4 v254, v[156:159], s[28:29] offset:64
	ds_bpermute_b32 v158, v248, v161
	s_waitcnt lgkmcnt(0)
	v_add_f32_e32 v161, v161, v158
	ds_bpermute_b32 v158, v249, v161
	s_waitcnt lgkmcnt(0)
	v_add_f32_e32 v161, v161, v158
	global_store_dword v247, v161, s[30:31]
	global_load_dwordx4 v[170:173], v244, s[24:25]
	global_load_dwordx4 v[174:177], v244, s[24:25] offset:64
	global_load_dwordx4 v[178:181], v244, s[24:25] offset:128
	global_load_dwordx4 v[182:185], v244, s[24:25] offset:192
	s_waitcnt vmcnt(33)
	v_add_f32_e32 v186, v36, v186
	v_add_f32_e32 v187, v37, v187
	v_add_f32_e32 v188, v38, v188
	v_add_f32_e32 v189, v39, v189
	global_store_dwordx4 v244, v[186:189], s[26:27] offset:256
	v_mul_f32_e32 v158, v186, v186
	v_mul_f32_e32 v159, v187, v187
	v_mul_f32_e32 v250, v188, v188
	v_mul_f32_e32 v251, v189, v189
	v_add_f32_e32 v158, v158, v159
	v_add_f32_e32 v250, v250, v251
	v_add_f32_e32 v161, v158, v250
	v_mul_f32_e32 v156, v186, v224
	v_mul_f32_e32 v157, v187, v225
	v_mul_f32_e32 v158, v188, v226
	v_mul_f32_e32 v159, v189, v227
	v_cvt_pk_bf16_f32 v156, v156, v157
	v_cvt_pk_bf16_f32 v157, v158, v159
	v_add_f32_e32 v190, v32, v190
	v_add_f32_e32 v191, v33, v191
	v_add_f32_e32 v192, v34, v192
	v_add_f32_e32 v193, v35, v193
	global_store_dwordx4 v244, v[190:193], s[26:27] offset:320
	v_mul_f32_e32 v158, v190, v190
	v_mul_f32_e32 v159, v191, v191
	v_mul_f32_e32 v250, v192, v192
	v_mul_f32_e32 v251, v193, v193
	v_add_f32_e32 v158, v158, v159
	v_add_f32_e32 v250, v250, v251
	v_add_f32_e32 v158, v158, v250
	v_add_f32_e32 v161, v161, v158
	v_mul_f32_e32 v158, v190, v228
	v_mul_f32_e32 v159, v191, v229
	v_mul_f32_e32 v250, v192, v230
	v_mul_f32_e32 v251, v193, v231
	v_cvt_pk_bf16_f32 v158, v158, v159
	v_cvt_pk_bf16_f32 v159, v250, v251
	s_nop 1
	v_permlane16_swap_b32_e32 v156, v158
	v_permlane16_swap_b32_e32 v157, v159
	global_store_dwordx4 v254, v[156:159], s[28:29] offset:128
	v_add_f32_e32 v194, v28, v194
	v_add_f32_e32 v195, v29, v195
	v_add_f32_e32 v196, v30, v196
	v_add_f32_e32 v197, v31, v197
	global_store_dwordx4 v244, v[194:197], s[26:27] offset:384
	v_mul_f32_e32 v158, v194, v194
	v_mul_f32_e32 v159, v195, v195
	v_mul_f32_e32 v250, v196, v196
	v_mul_f32_e32 v251, v197, v197
	v_add_f32_e32 v158, v158, v159
	v_add_f32_e32 v250, v250, v251
	v_add_f32_e32 v158, v158, v250
	v_add_f32_e32 v161, v161, v158
	v_mul_f32_e32 v156, v194, v232
	v_mul_f32_e32 v157, v195, v233
	v_mul_f32_e32 v158, v196, v234
	v_mul_f32_e32 v159, v197, v235
	v_cvt_pk_bf16_f32 v156, v156, v157
	v_cvt_pk_bf16_f32 v157, v158, v159
	v_add_f32_e32 v240, v24, v240
	v_add_f32_e32 v241, v25, v241
	v_add_f32_e32 v242, v26, v242
	v_add_f32_e32 v243, v27, v243
	global_store_dwordx4 v244, v[240:243], s[26:27] offset:448
	v_mul_f32_e32 v158, v240, v240
	v_mul_f32_e32 v159, v241, v241
	v_mul_f32_e32 v250, v242, v242
	v_mul_f32_e32 v251, v243, v243
	v_add_f32_e32 v158, v158, v159
	v_add_f32_e32 v250, v250, v251
	v_add_f32_e32 v158, v158, v250
	v_add_f32_e32 v161, v161, v158
	v_mul_f32_e32 v158, v240, v236
	v_mul_f32_e32 v159, v241, v237
	v_mul_f32_e32 v250, v242, v238
	v_mul_f32_e32 v251, v243, v239
	v_cvt_pk_bf16_f32 v158, v158, v159
	v_cvt_pk_bf16_f32 v159, v250, v251
	s_nop 1
	v_permlane16_swap_b32_e32 v156, v158
	v_permlane16_swap_b32_e32 v157, v159
	global_store_dwordx4 v254, v[156:159], s[28:29] offset:192
	ds_bpermute_b32 v158, v248, v161
	s_waitcnt lgkmcnt(0)
	v_add_f32_e32 v161, v161, v158
	ds_bpermute_b32 v158, v249, v161
	s_waitcnt lgkmcnt(0)
	v_add_f32_e32 v161, v161, v158
	global_store_dword v247, v161, s[30:31] offset:4
	s_add_u32 s26, s26, 0x10000
	s_addc_u32 s27, s27, 0
	s_add_u32 s28, s28, 0x8000
	s_addc_u32 s29, s29, 0
	s_add_u32 s30, s30, 0x400
	s_addc_u32 s31, s31, 0
	global_load_dwordx4 v[186:189], v244, s[24:25] offset:256
	global_load_dwordx4 v[190:193], v244, s[24:25] offset:320
	global_load_dwordx4 v[194:197], v244, s[24:25] offset:384
	global_load_dwordx4 v[240:243], v244, s[24:25] offset:448
	s_add_u32 s24, s24, 0x10000
	s_addc_u32 s25, s25, 0
	s_waitcnt vmcnt(33)
	v_add_f32_e32 v0, v108, v0
	v_add_f32_e32 v1, v109, v1
	v_add_f32_e32 v2, v110, v2
	v_add_f32_e32 v3, v111, v3
	global_store_dwordx4 v244, v[0:3], s[26:27]
	v_mul_f32_e32 v158, v0, v0
	v_mul_f32_e32 v159, v1, v1
	v_mul_f32_e32 v250, v2, v2
	v_mul_f32_e32 v251, v3, v3
	v_add_f32_e32 v158, v158, v159
	v_add_f32_e32 v250, v250, v251
	v_add_f32_e32 v161, v158, v250
	v_mul_f32_e32 v156, v0, v208
	v_mul_f32_e32 v157, v1, v209
	v_mul_f32_e32 v158, v2, v210
	v_mul_f32_e32 v159, v3, v211
	v_cvt_pk_bf16_f32 v156, v156, v157
	v_cvt_pk_bf16_f32 v157, v158, v159
	v_add_f32_e32 v4, v112, v4
	v_add_f32_e32 v5, v113, v5
	v_add_f32_e32 v6, v114, v6
	v_add_f32_e32 v7, v115, v7
	global_store_dwordx4 v244, v[4:7], s[26:27] offset:64
	v_mul_f32_e32 v158, v4, v4
	v_mul_f32_e32 v159, v5, v5
	v_mul_f32_e32 v250, v6, v6
	v_mul_f32_e32 v251, v7, v7
	v_add_f32_e32 v158, v158, v159
	v_add_f32_e32 v250, v250, v251
	v_add_f32_e32 v158, v158, v250
	v_add_f32_e32 v161, v161, v158
	v_mul_f32_e32 v158, v4, v212
	v_mul_f32_e32 v159, v5, v213
	v_mul_f32_e32 v250, v6, v214
	v_mul_f32_e32 v251, v7, v215
	v_cvt_pk_bf16_f32 v158, v158, v159
	v_cvt_pk_bf16_f32 v159, v250, v251
	s_nop 1
	v_permlane16_swap_b32_e32 v156, v158
	v_permlane16_swap_b32_e32 v157, v159
	global_store_dwordx4 v254, v[156:159], s[28:29]
	v_add_f32_e32 v8, v116, v8
	v_add_f32_e32 v9, v117, v9
	v_add_f32_e32 v10, v118, v10
	v_add_f32_e32 v11, v119, v11
	global_store_dwordx4 v244, v[8:11], s[26:27] offset:128
	v_mul_f32_e32 v158, v8, v8
	v_mul_f32_e32 v159, v9, v9
	v_mul_f32_e32 v250, v10, v10
	v_mul_f32_e32 v251, v11, v11
	v_add_f32_e32 v158, v158, v159
	v_add_f32_e32 v250, v250, v251
	v_add_f32_e32 v158, v158, v250
	v_add_f32_e32 v161, v161, v158
	v_mul_f32_e32 v156, v8, v216
	v_mul_f32_e32 v157, v9, v217
	v_mul_f32_e32 v158, v10, v218
	v_mul_f32_e32 v159, v11, v219
	v_cvt_pk_bf16_f32 v156, v156, v157
	v_cvt_pk_bf16_f32 v157, v158, v159
	v_add_f32_e32 v12, v124, v12
	v_add_f32_e32 v13, v125, v13
	v_add_f32_e32 v14, v126, v14
	v_add_f32_e32 v15, v127, v15
	global_store_dwordx4 v244, v[12:15], s[26:27] offset:192
	v_mul_f32_e32 v158, v12, v12
	v_mul_f32_e32 v159, v13, v13
	v_mul_f32_e32 v250, v14, v14
	v_mul_f32_e32 v251, v15, v15
	v_add_f32_e32 v158, v158, v159
	v_add_f32_e32 v250, v250, v251
	v_add_f32_e32 v158, v158, v250
	v_add_f32_e32 v161, v161, v158
	v_mul_f32_e32 v158, v12, v220
	v_mul_f32_e32 v159, v13, v221
	v_mul_f32_e32 v250, v14, v222
	v_mul_f32_e32 v251, v15, v223
	v_cvt_pk_bf16_f32 v158, v158, v159
	v_cvt_pk_bf16_f32 v159, v250, v251
	s_nop 1
	v_permlane16_swap_b32_e32 v156, v158
	v_permlane16_swap_b32_e32 v157, v159
	global_store_dwordx4 v254, v[156:159], s[28:29] offset:64
	ds_bpermute_b32 v158, v248, v161
	s_waitcnt lgkmcnt(0)
	v_add_f32_e32 v161, v161, v158
	ds_bpermute_b32 v158, v249, v161
	s_waitcnt lgkmcnt(0)
	v_add_f32_e32 v161, v161, v158
	global_store_dword v247, v161, s[30:31]
	s_waitcnt vmcnt(29)
	v_add_f32_e32 v16, v88, v16
	v_add_f32_e32 v17, v89, v17
	v_add_f32_e32 v18, v90, v18
	v_add_f32_e32 v19, v91, v19
	global_store_dwordx4 v244, v[16:19], s[26:27] offset:256
	v_mul_f32_e32 v158, v16, v16
	v_mul_f32_e32 v159, v17, v17
	v_mul_f32_e32 v250, v18, v18
	v_mul_f32_e32 v251, v19, v19
	v_add_f32_e32 v158, v158, v159
	v_add_f32_e32 v250, v250, v251
	v_add_f32_e32 v161, v158, v250
	v_mul_f32_e32 v156, v16, v224
	v_mul_f32_e32 v157, v17, v225
	v_mul_f32_e32 v158, v18, v226
	v_mul_f32_e32 v159, v19, v227
	v_cvt_pk_bf16_f32 v156, v156, v157
	v_cvt_pk_bf16_f32 v157, v158, v159
	v_add_f32_e32 v20, v92, v20
	v_add_f32_e32 v21, v93, v21
	v_add_f32_e32 v22, v94, v22
	v_add_f32_e32 v23, v95, v23
	global_store_dwordx4 v244, v[20:23], s[26:27] offset:320
	v_mul_f32_e32 v158, v20, v20
	v_mul_f32_e32 v159, v21, v21
	v_mul_f32_e32 v250, v22, v22
	v_mul_f32_e32 v251, v23, v23
	v_add_f32_e32 v158, v158, v159
	v_add_f32_e32 v250, v250, v251
	v_add_f32_e32 v158, v158, v250
	v_add_f32_e32 v161, v161, v158
	v_mul_f32_e32 v158, v20, v228
	v_mul_f32_e32 v159, v21, v229
	v_mul_f32_e32 v250, v22, v230
	v_mul_f32_e32 v251, v23, v231
	v_cvt_pk_bf16_f32 v158, v158, v159
	v_cvt_pk_bf16_f32 v159, v250, v251
	s_nop 1
	v_permlane16_swap_b32_e32 v156, v158
	v_permlane16_swap_b32_e32 v157, v159
	global_store_dwordx4 v254, v[156:159], s[28:29] offset:128
	v_add_f32_e32 v162, v96, v162
	v_add_f32_e32 v163, v97, v163
	v_add_f32_e32 v164, v98, v164
	v_add_f32_e32 v165, v99, v165
	global_store_dwordx4 v244, v[162:165], s[26:27] offset:384
	v_mul_f32_e32 v158, v162, v162
	v_mul_f32_e32 v159, v163, v163
	v_mul_f32_e32 v250, v164, v164
	v_mul_f32_e32 v251, v165, v165
	v_add_f32_e32 v158, v158, v159
	v_add_f32_e32 v250, v250, v251
	v_add_f32_e32 v158, v158, v250
	v_add_f32_e32 v161, v161, v158
	v_mul_f32_e32 v156, v162, v232
	v_mul_f32_e32 v157, v163, v233
	v_mul_f32_e32 v158, v164, v234
	v_mul_f32_e32 v159, v165, v235
	v_cvt_pk_bf16_f32 v156, v156, v157
	v_cvt_pk_bf16_f32 v157, v158, v159
	v_add_f32_e32 v166, v84, v166
	v_add_f32_e32 v167, v85, v167
	v_add_f32_e32 v168, v86, v168
	v_add_f32_e32 v169, v87, v169
	global_store_dwordx4 v244, v[166:169], s[26:27] offset:448
	v_mul_f32_e32 v158, v166, v166
	v_mul_f32_e32 v159, v167, v167
	v_mul_f32_e32 v250, v168, v168
	v_mul_f32_e32 v251, v169, v169
	v_add_f32_e32 v158, v158, v159
	v_add_f32_e32 v250, v250, v251
	v_add_f32_e32 v158, v158, v250
	v_add_f32_e32 v161, v161, v158
	v_mul_f32_e32 v158, v166, v236
	v_mul_f32_e32 v159, v167, v237
	v_mul_f32_e32 v250, v168, v238
	v_mul_f32_e32 v251, v169, v239
	v_cvt_pk_bf16_f32 v158, v158, v159
	v_cvt_pk_bf16_f32 v159, v250, v251
	s_nop 1
	v_permlane16_swap_b32_e32 v156, v158
	v_permlane16_swap_b32_e32 v157, v159
	global_store_dwordx4 v254, v[156:159], s[28:29] offset:192
	ds_bpermute_b32 v158, v248, v161
	s_waitcnt lgkmcnt(0)
	v_add_f32_e32 v161, v161, v158
	ds_bpermute_b32 v158, v249, v161
	s_waitcnt lgkmcnt(0)
	v_add_f32_e32 v161, v161, v158
	global_store_dword v247, v161, s[30:31] offset:4
	s_add_u32 s26, s26, 0x10000
	s_addc_u32 s27, s27, 0
	s_add_u32 s28, s28, 0x8000
	s_addc_u32 s29, s29, 0
	s_add_u32 s30, s30, 0x400
	s_addc_u32 s31, s31, 0
	s_waitcnt vmcnt(25)
	v_add_f32_e32 v170, v132, v170
	v_add_f32_e32 v171, v133, v171
	v_add_f32_e32 v172, v134, v172
	v_add_f32_e32 v173, v135, v173
	global_store_dwordx4 v244, v[170:173], s[26:27]
	v_mul_f32_e32 v158, v170, v170
	v_mul_f32_e32 v159, v171, v171
	v_mul_f32_e32 v250, v172, v172
	v_mul_f32_e32 v251, v173, v173
	v_add_f32_e32 v158, v158, v159
	v_add_f32_e32 v250, v250, v251
	v_add_f32_e32 v161, v158, v250
	v_mul_f32_e32 v156, v170, v208
	v_mul_f32_e32 v157, v171, v209
	v_mul_f32_e32 v158, v172, v210
	v_mul_f32_e32 v159, v173, v211
	v_cvt_pk_bf16_f32 v156, v156, v157
	v_cvt_pk_bf16_f32 v157, v158, v159
	v_add_f32_e32 v174, v136, v174
	v_add_f32_e32 v175, v137, v175
	v_add_f32_e32 v176, v138, v176
	v_add_f32_e32 v177, v139, v177
	global_store_dwordx4 v244, v[174:177], s[26:27] offset:64
	v_mul_f32_e32 v158, v174, v174
	v_mul_f32_e32 v159, v175, v175
	v_mul_f32_e32 v250, v176, v176
	v_mul_f32_e32 v251, v177, v177
	v_add_f32_e32 v158, v158, v159
	v_add_f32_e32 v250, v250, v251
	v_add_f32_e32 v158, v158, v250
	v_add_f32_e32 v161, v161, v158
	v_mul_f32_e32 v158, v174, v212
	v_mul_f32_e32 v159, v175, v213
	v_mul_f32_e32 v250, v176, v214
	v_mul_f32_e32 v251, v177, v215
	v_cvt_pk_bf16_f32 v158, v158, v159
	v_cvt_pk_bf16_f32 v159, v250, v251
	s_nop 1
	v_permlane16_swap_b32_e32 v156, v158
	v_permlane16_swap_b32_e32 v157, v159
	global_store_dwordx4 v254, v[156:159], s[28:29]
	v_add_f32_e32 v178, v140, v178
	v_add_f32_e32 v179, v141, v179
	v_add_f32_e32 v180, v142, v180
	v_add_f32_e32 v181, v143, v181
	global_store_dwordx4 v244, v[178:181], s[26:27] offset:128
	v_mul_f32_e32 v158, v178, v178
	v_mul_f32_e32 v159, v179, v179
	v_mul_f32_e32 v250, v180, v180
	v_mul_f32_e32 v251, v181, v181
	v_add_f32_e32 v158, v158, v159
	v_add_f32_e32 v250, v250, v251
	v_add_f32_e32 v158, v158, v250
	v_add_f32_e32 v161, v161, v158
	v_mul_f32_e32 v156, v178, v216
	v_mul_f32_e32 v157, v179, v217
	v_mul_f32_e32 v158, v180, v218
	v_mul_f32_e32 v159, v181, v219
	v_cvt_pk_bf16_f32 v156, v156, v157
	v_cvt_pk_bf16_f32 v157, v158, v159
	v_add_f32_e32 v182, v144, v182
	v_add_f32_e32 v183, v145, v183
	v_add_f32_e32 v184, v146, v184
	v_add_f32_e32 v185, v147, v185
	global_store_dwordx4 v244, v[182:185], s[26:27] offset:192
	v_mul_f32_e32 v158, v182, v182
	v_mul_f32_e32 v159, v183, v183
	v_mul_f32_e32 v250, v184, v184
	v_mul_f32_e32 v251, v185, v185
	v_add_f32_e32 v158, v158, v159
	v_add_f32_e32 v250, v250, v251
	v_add_f32_e32 v158, v158, v250
	v_add_f32_e32 v161, v161, v158
	v_mul_f32_e32 v158, v182, v220
	v_mul_f32_e32 v159, v183, v221
	v_mul_f32_e32 v250, v184, v222
	v_mul_f32_e32 v251, v185, v223
	v_cvt_pk_bf16_f32 v158, v158, v159
	v_cvt_pk_bf16_f32 v159, v250, v251
	s_nop 1
	v_permlane16_swap_b32_e32 v156, v158
	v_permlane16_swap_b32_e32 v157, v159
	global_store_dwordx4 v254, v[156:159], s[28:29] offset:64
	ds_bpermute_b32 v158, v248, v161
	s_waitcnt lgkmcnt(0)
	v_add_f32_e32 v161, v161, v158
	ds_bpermute_b32 v158, v249, v161
	s_waitcnt lgkmcnt(0)
	v_add_f32_e32 v161, v161, v158
	global_store_dword v247, v161, s[30:31]
	s_waitcnt vmcnt(21)
	v_add_f32_e32 v186, v76, v186
	v_add_f32_e32 v187, v77, v187
	v_add_f32_e32 v188, v78, v188
	v_add_f32_e32 v189, v79, v189
	global_store_dwordx4 v244, v[186:189], s[26:27] offset:256
	v_mul_f32_e32 v158, v186, v186
	v_mul_f32_e32 v159, v187, v187
	v_mul_f32_e32 v250, v188, v188
	v_mul_f32_e32 v251, v189, v189
	v_add_f32_e32 v158, v158, v159
	v_add_f32_e32 v250, v250, v251
	v_add_f32_e32 v161, v158, v250
	v_mul_f32_e32 v156, v186, v224
	v_mul_f32_e32 v157, v187, v225
	v_mul_f32_e32 v158, v188, v226
	v_mul_f32_e32 v159, v189, v227
	v_cvt_pk_bf16_f32 v156, v156, v157
	v_cvt_pk_bf16_f32 v157, v158, v159
	v_add_f32_e32 v190, v52, v190
	v_add_f32_e32 v191, v53, v191
	v_add_f32_e32 v192, v54, v192
	v_add_f32_e32 v193, v55, v193
	global_store_dwordx4 v244, v[190:193], s[26:27] offset:320
	v_mul_f32_e32 v158, v190, v190
	v_mul_f32_e32 v159, v191, v191
	v_mul_f32_e32 v250, v192, v192
	v_mul_f32_e32 v251, v193, v193
	v_add_f32_e32 v158, v158, v159
	v_add_f32_e32 v250, v250, v251
	v_add_f32_e32 v158, v158, v250
	v_add_f32_e32 v161, v161, v158
	v_mul_f32_e32 v158, v190, v228
	v_mul_f32_e32 v159, v191, v229
	v_mul_f32_e32 v250, v192, v230
	v_mul_f32_e32 v251, v193, v231
	v_cvt_pk_bf16_f32 v158, v158, v159
	v_cvt_pk_bf16_f32 v159, v250, v251
	s_nop 1
	v_permlane16_swap_b32_e32 v156, v158
	v_permlane16_swap_b32_e32 v157, v159
	global_store_dwordx4 v254, v[156:159], s[28:29] offset:128
	v_add_f32_e32 v194, v44, v194
	v_add_f32_e32 v195, v45, v195
	v_add_f32_e32 v196, v46, v196
	v_add_f32_e32 v197, v47, v197
	global_store_dwordx4 v244, v[194:197], s[26:27] offset:384
	v_mul_f32_e32 v158, v194, v194
	v_mul_f32_e32 v159, v195, v195
	v_mul_f32_e32 v250, v196, v196
	v_mul_f32_e32 v251, v197, v197
	v_add_f32_e32 v158, v158, v159
	v_add_f32_e32 v250, v250, v251
	v_add_f32_e32 v158, v158, v250
	v_add_f32_e32 v161, v161, v158
	v_mul_f32_e32 v156, v194, v232
	v_mul_f32_e32 v157, v195, v233
	v_mul_f32_e32 v158, v196, v234
	v_mul_f32_e32 v159, v197, v235
	v_cvt_pk_bf16_f32 v156, v156, v157
	v_cvt_pk_bf16_f32 v157, v158, v159
	v_add_f32_e32 v240, v148, v240
	v_add_f32_e32 v241, v149, v241
	v_add_f32_e32 v242, v150, v242
	v_add_f32_e32 v243, v151, v243
	global_store_dwordx4 v244, v[240:243], s[26:27] offset:448
	v_mul_f32_e32 v158, v240, v240
	v_mul_f32_e32 v159, v241, v241
	v_mul_f32_e32 v250, v242, v242
	v_mul_f32_e32 v251, v243, v243
	v_add_f32_e32 v158, v158, v159
	v_add_f32_e32 v250, v250, v251
	v_add_f32_e32 v158, v158, v250
	v_add_f32_e32 v161, v161, v158
	v_mul_f32_e32 v158, v240, v236
	v_mul_f32_e32 v159, v241, v237
	v_mul_f32_e32 v250, v242, v238
	v_mul_f32_e32 v251, v243, v239
	v_cvt_pk_bf16_f32 v158, v158, v159
	v_cvt_pk_bf16_f32 v159, v250, v251
	s_nop 1
	v_permlane16_swap_b32_e32 v156, v158
	v_permlane16_swap_b32_e32 v157, v159
	global_store_dwordx4 v254, v[156:159], s[28:29] offset:192
	ds_bpermute_b32 v158, v248, v161
	s_waitcnt lgkmcnt(0)
	v_add_f32_e32 v161, v161, v158
	ds_bpermute_b32 v158, v249, v161
	s_waitcnt lgkmcnt(0)
	v_add_f32_e32 v161, v161, v158
	global_store_dword v247, v161, s[30:31] offset:4
	s_add_u32 s26, s26, 0x10000
	s_addc_u32 s27, s27, 0
	s_add_u32 s28, s28, 0x8000
	s_addc_u32 s29, s29, 0
	s_add_u32 s30, s30, 0x400
	s_addc_u32 s31, s31, 0
	s_branch .LBB0_23

.LBB0_130:
	s_ashr_i32 s14, s12, 8
	s_lshl_b32 s13, s12, 6
	v_ashrrev_i32_e32 v29, 6, v32
	s_lshl_b32 s5, s14, 12
	s_and_b32 s26, s13, 0xfc0
	s_or_b32 s5, s5, s26
	v_lshlrev_b32_e32 v6, 4, v29
	v_add_u32_e32 v0, s5, v6
	v_mov_b64_e32 v[2:3], s[92:93]
	v_mad_i64_i32 v[2:3], s[16:17], v0, s63, v[2:3]
	s_lshl_b32 s84, s4, 1
	v_lshl_add_u64 v[2:3], v[2:3], 0, s[84:85]
	v_lshlrev_b32_e32 v152, 1, v7
	v_lshl_add_u64 v[4:5], v[2:3], 0, v[152:153]
	s_mul_i32 s30, s5, 0x1800
	s_add_u32 s28, s92, s30
	s_addc_u32 s29, s93, 0
	s_add_u32 s28, s28, s84
	s_addc_u32 s29, s29, 0
	v_mul_u32_u24_e32 v113, 0x1800, v6
	v_add_u32_e32 v112, v113, v152
	global_load_ushort v80, v112, s[28:29]
	global_load_ushort v81, v112, s[28:29] offset:512
	s_add_u32 s28, s28, 0x1800
	s_addc_u32 s29, s29, 0
	global_load_ushort v82, v112, s[28:29]
	global_load_ushort v83, v112, s[28:29] offset:512
	s_add_u32 s28, s28, 0x1800
	s_addc_u32 s29, s29, 0
	global_load_ushort v84, v112, s[28:29]
	global_load_ushort v85, v112, s[28:29] offset:512
	s_add_u32 s28, s28, 0x1800
	s_addc_u32 s29, s29, 0
	global_load_ushort v86, v112, s[28:29]
	global_load_ushort v87, v112, s[28:29] offset:512
	s_add_u32 s28, s28, 0x1800
	s_addc_u32 s29, s29, 0
	global_load_ushort v88, v112, s[28:29]
	global_load_ushort v89, v112, s[28:29] offset:512
	s_add_u32 s28, s28, 0x1800
	s_addc_u32 s29, s29, 0
	global_load_ushort v90, v112, s[28:29]
	global_load_ushort v91, v112, s[28:29] offset:512
	s_add_u32 s28, s28, 0x1800
	s_addc_u32 s29, s29, 0
	global_load_ushort v92, v112, s[28:29]
	global_load_ushort v93, v112, s[28:29] offset:512
	s_add_u32 s28, s28, 0x1800
	s_addc_u32 s29, s29, 0
	global_load_ushort v94, v112, s[28:29]
	global_load_ushort v95, v112, s[28:29] offset:512
	s_add_u32 s28, s28, 0x1800
	s_addc_u32 s29, s29, 0
	global_load_ushort v96, v112, s[28:29]
	global_load_ushort v97, v112, s[28:29] offset:512
	s_add_u32 s28, s28, 0x1800
	s_addc_u32 s29, s29, 0
	global_load_ushort v98, v112, s[28:29]
	global_load_ushort v99, v112, s[28:29] offset:512
	s_add_u32 s28, s28, 0x1800
	s_addc_u32 s29, s29, 0
	global_load_ushort v100, v112, s[28:29]
	global_load_ushort v101, v112, s[28:29] offset:512
	s_add_u32 s28, s28, 0x1800
	s_addc_u32 s29, s29, 0
	global_load_ushort v102, v112, s[28:29]
	global_load_ushort v103, v112, s[28:29] offset:512
	s_add_u32 s28, s28, 0x1800
	s_addc_u32 s29, s29, 0
	global_load_ushort v104, v112, s[28:29]
	global_load_ushort v105, v112, s[28:29] offset:512
	s_add_u32 s28, s28, 0x1800
	s_addc_u32 s29, s29, 0
	global_load_ushort v106, v112, s[28:29]
	global_load_ushort v107, v112, s[28:29] offset:512
	s_add_u32 s28, s28, 0x1800
	s_addc_u32 s29, s29, 0
	global_load_ushort v108, v112, s[28:29]
	global_load_ushort v109, v112, s[28:29] offset:512
	s_add_u32 s28, s28, 0x1800
	s_addc_u32 s29, s29, 0
	global_load_ushort v110, v112, s[28:29]
	global_load_ushort v111, v112, s[28:29] offset:512
	s_add_u32 s28, s28, 0x1800
	s_addc_u32 s29, s29, 0
	s_andn2_b64 vcc, exec, s[6:7]
	s_cbranch_vccnz .Lhc_lb0
	v_or_b32_e32 v114, s4, v7
	v_lshlrev_b32_e32 v114, 2, v114
	global_load_dword v115, v114, s[50:51]
	global_load_dword v114, v114, s[50:51] offset:1024
	s_waitcnt vmcnt(0)
	v_sub_f32_e32 v114, v115, v114
	v_mul_f32_e32 v114, 0x3fb8aa3b, v114
	v_exp_f32_e32 v114, v114
	s_nop 0
	v_add_f32_e32 v114, 1.0, v114
	v_div_scale_f32 v115, vcc, v114, v114, 1.0
	v_rcp_f32_e32 v116, v115
	v_div_scale_f32 v117, vcc, 1.0, v114, 1.0
	v_fma_f32 v118, -v115, v116, 1.0
	v_fmac_f32_e32 v116, v118, v116
	v_mul_f32_e32 v118, v117, v116
	v_fma_f32 v119, -v115, v118, v117
	v_fmac_f32_e32 v118, v119, v116
	v_fma_f32 v115, -v115, v118, v117
	v_div_fmas_f32 v115, v115, v116, v118
	v_div_fixup_f32 v24, v115, v114, 1.0
.Lhc_lb0:
	s_waitcnt vmcnt(0)
	v_mov_b32_e32 v2, v81
	v_sub_f32_e32 v9, 1.0, v24
	v_lshlrev_b32_e32 v0, 2, v7
	s_waitcnt vmcnt(0)
	v_lshlrev_b32_e32 v17, 16, v2
	v_mul_f32_e32 v2, 0xbfb8aa3b, v17
	v_exp_f32_e32 v2, v2
	s_nop 0
	v_add_f32_e32 v2, 1.0, v2
	v_div_scale_f32 v3, s[4:5], v2, v2, 1.0
	v_rcp_f32_e32 v8, v3
	s_nop 0
	v_fma_f32 v10, -v3, v8, 1.0
	v_fmac_f32_e32 v8, v10, v8
	v_div_scale_f32 v10, vcc, 1.0, v2, 1.0
	v_mul_f32_e32 v11, v10, v8
	v_fma_f32 v12, -v3, v11, v10
	v_fmac_f32_e32 v11, v12, v8
	v_fma_f32 v3, -v3, v11, v10
	v_div_fmas_f32 v3, v3, v8, v11
	v_div_fixup_f32 v2, v3, v2, 1.0
	v_fma_f32 v2, v9, v2, v24
	v_max_f32_e32 v2, 0xda24260, v2
	v_log_f32_e32 v2, v2
	v_mul_lo_u32 v8, v29, s80
	v_add_u32_e32 v3, v0, v8
	v_add_f32_e32 v10, 0, v2
	v_mov_b32_e32 v2, v80
	s_waitcnt vmcnt(0)
	v_lshlrev_b32_e32 v2, 16, v2
	v_mul_f32_e32 v2, 0x3e000000, v2
	ds_write_b32 v3, v2 offset:33280
	v_add_co_u32_e32 v2, vcc, s64, v4
	s_nop 1
	v_addc_co_u32_e32 v3, vcc, 0, v5, vcc
	v_mov_b32_e32 v11, v83
	s_waitcnt vmcnt(0)
	v_lshlrev_b32_e32 v18, 16, v11
	v_mov_b32_e32 v2, v82
	v_mul_f32_e32 v11, 0xbfb8aa3b, v18
	v_exp_f32_e32 v11, v11
	s_waitcnt vmcnt(0)
	v_lshlrev_b32_e32 v2, 16, v2
	v_add_f32_e32 v11, 1.0, v11
	v_div_scale_f32 v12, s[4:5], v11, v11, 1.0
	v_rcp_f32_e32 v13, v12
	s_nop 0
	v_fma_f32 v14, -v12, v13, 1.0
	v_fmac_f32_e32 v13, v14, v13
	v_div_scale_f32 v14, vcc, 1.0, v11, 1.0
	v_mul_f32_e32 v15, v14, v13
	v_fma_f32 v16, -v12, v15, v14
	v_fmac_f32_e32 v15, v16, v13
	v_fma_f32 v12, -v12, v15, v14
	v_div_fmas_f32 v12, v12, v13, v15
	v_div_fixup_f32 v11, v12, v11, 1.0
	v_or_b32_e32 v12, 1, v6
	v_mul_f32_e32 v13, 0x3e000000, v2
	v_mad_u64_u32 v[2:3], s[4:5], v12, s81, v[0:1]
	s_movk_i32 s4, 0x3000
	s_nop 0
	v_add_co_u32_e32 v14, vcc, s4, v4
	v_fma_f32 v11, v9, v11, v24
	s_nop 0
	v_addc_co_u32_e32 v15, vcc, 0, v5, vcc
	v_mov_b32_e32 v3, v85
	v_max_f32_e32 v11, 0xda24260, v11
	v_mov_b32_e32 v14, v84
	v_add_u32_e32 v15, 0x8000, v2
	v_log_f32_e32 v11, v11
	s_waitcnt vmcnt(1)
	v_lshlrev_b32_e32 v19, 16, v3
	v_mul_f32_e32 v3, 0xbfb8aa3b, v19
	v_exp_f32_e32 v3, v3
	s_waitcnt vmcnt(0)
	v_lshlrev_b32_e32 v14, 16, v14
	v_mul_f32_e32 v14, 0x3e000000, v14
	ds_write2_b32 v15, v13, v14 offset0:128 offset1:193
	v_add_f32_e32 v3, 1.0, v3
	v_div_scale_f32 v16, s[4:5], v3, v3, 1.0
	v_rcp_f32_e32 v20, v16
	v_add_f32_e32 v11, v10, v11
	v_fma_f32 v21, -v16, v20, 1.0
	v_fmac_f32_e32 v20, v21, v20
	v_div_scale_f32 v21, vcc, 1.0, v3, 1.0
	v_mul_f32_e32 v22, v21, v20
	v_fma_f32 v23, -v16, v22, v21
	v_fmac_f32_e32 v22, v23, v20
	v_fma_f32 v16, -v16, v22, v21
	v_div_fmas_f32 v16, v16, v20, v22
	v_add_co_u32_e32 v14, vcc, s74, v4
	v_div_fixup_f32 v3, v16, v3, 1.0
	s_nop 0
	v_addc_co_u32_e32 v15, vcc, 0, v5, vcc
	v_mov_b32_e32 v13, v87
	v_fma_f32 v3, v9, v3, v24
	v_mov_b32_e32 v14, v86
	v_max_f32_e32 v3, 0xda24260, v3
	v_log_f32_e32 v3, v3
	s_waitcnt vmcnt(1)
	v_lshlrev_b32_e32 v21, 16, v13
	v_mul_f32_e32 v13, 0xbfb8aa3b, v21
	v_exp_f32_e32 v13, v13
	s_waitcnt vmcnt(0)
	v_lshlrev_b32_e32 v14, 16, v14
	v_mul_f32_e32 v15, 0x3e000000, v14
	v_add_f32_e32 v3, v11, v3
	v_add_f32_e32 v13, 1.0, v13
	v_div_scale_f32 v16, s[4:5], v13, v13, 1.0
	v_rcp_f32_e32 v20, v16
	s_movk_i32 s4, 0x6000
	v_fma_f32 v22, -v16, v20, 1.0
	v_fmac_f32_e32 v20, v22, v20
	v_div_scale_f32 v22, vcc, 1.0, v13, 1.0
	v_mul_f32_e32 v23, v22, v20
	v_fma_f32 v25, -v16, v23, v22
	v_fmac_f32_e32 v23, v25, v20
	v_fma_f32 v16, -v16, v23, v22
	v_div_fmas_f32 v16, v16, v20, v23
	v_add_co_u32_e32 v26, vcc, s4, v4
	v_div_fixup_f32 v13, v16, v13, 1.0
	s_nop 0
	v_addc_co_u32_e32 v27, vcc, 0, v5, vcc
	v_mov_b32_e32 v14, v89
	v_fma_f32 v13, v9, v13, v24
	v_max_f32_e32 v13, 0xda24260, v13
	v_log_f32_e32 v13, v13
	s_waitcnt vmcnt(0)
	v_lshlrev_b32_e32 v22, 16, v14
	v_mul_f32_e32 v14, 0xbfb8aa3b, v22
	v_exp_f32_e32 v14, v14
	v_add_f32_e32 v13, v3, v13
	v_add_f32_e32 v14, 1.0, v14
	v_div_scale_f32 v16, s[4:5], v14, v14, 1.0
	v_rcp_f32_e32 v20, v16
	s_movk_i32 s4, 0x7000
	v_fma_f32 v23, -v16, v20, 1.0
	v_fmac_f32_e32 v20, v23, v20
	v_div_scale_f32 v23, vcc, 1.0, v14, 1.0
	v_mul_f32_e32 v25, v23, v20
	v_fma_f32 v28, -v16, v25, v23
	v_fmac_f32_e32 v25, v28, v20
	v_fma_f32 v16, -v16, v25, v23
	v_div_fmas_f32 v16, v16, v20, v25
	v_div_fixup_f32 v14, v16, v14, 1.0
	v_mov_b32_e32 v16, v88
	v_add_co_u32_e32 v26, vcc, s4, v4
	v_add_u32_e32 v20, 0x8400, v2
	s_nop 0
	v_addc_co_u32_e32 v27, vcc, 0, v5, vcc
	v_fma_f32 v14, v9, v14, v24
	v_max_f32_e32 v14, 0xda24260, v14
	v_log_f32_e32 v14, v14
	s_waitcnt vmcnt(0)
	v_lshlrev_b32_e32 v16, 16, v16
	v_mul_f32_e32 v16, 0x3e000000, v16
	ds_write2_b32 v20, v15, v16 offset0:2 offset1:67
	v_mov_b32_e32 v15, v91
	v_add_f32_e32 v14, v13, v14
	s_waitcnt vmcnt(0)
	v_lshlrev_b32_e32 v23, 16, v15
	v_mul_f32_e32 v15, 0xbfb8aa3b, v23
	v_exp_f32_e32 v15, v15
	s_nop 0
	v_add_f32_e32 v15, 1.0, v15
	v_div_scale_f32 v16, s[4:5], v15, v15, 1.0
	v_rcp_f32_e32 v25, v16
	s_mov_b32 s4, 0x9000
	v_fma_f32 v28, -v16, v25, 1.0
	v_fmac_f32_e32 v25, v28, v25
	v_div_scale_f32 v28, vcc, 1.0, v15, 1.0
	v_mul_f32_e32 v30, v28, v25
	v_fma_f32 v31, -v16, v30, v28
	v_fmac_f32_e32 v30, v31, v25
	v_fma_f32 v16, -v16, v30, v28
	v_div_fmas_f32 v16, v16, v25, v30
	v_div_fixup_f32 v15, v16, v15, 1.0
	v_mov_b32_e32 v16, v90
	v_add_co_u32_e32 v26, vcc, s4, v4
	v_fma_f32 v15, v9, v15, v24
	s_nop 0
	v_addc_co_u32_e32 v27, vcc, 0, v5, vcc
	v_max_f32_e32 v15, 0xda24260, v15
	v_log_f32_e32 v15, v15
	s_waitcnt vmcnt(0)
	v_lshlrev_b32_e32 v16, 16, v16
	v_mul_f32_e32 v28, 0x3e000000, v16
	v_mov_b32_e32 v16, v93
	v_add_f32_e32 v15, v14, v15
	v_mov_b32_e32 v26, v92
	s_waitcnt vmcnt(1)
	v_lshlrev_b32_e32 v25, 16, v16
	v_mul_f32_e32 v16, 0xbfb8aa3b, v25
	v_exp_f32_e32 v16, v16
	s_waitcnt vmcnt(0)
	v_lshlrev_b32_e32 v26, 16, v26
	v_mul_f32_e32 v26, 0x3e000000, v26
	ds_write2_b32 v20, v28, v26 offset0:132 offset1:197
	v_add_f32_e32 v16, 1.0, v16
	v_div_scale_f32 v30, s[4:5], v16, v16, 1.0
	v_rcp_f32_e32 v31, v30
	s_mov_b32 s4, 0xa000
	v_fma_f32 v33, -v30, v31, 1.0
	v_fmac_f32_e32 v31, v33, v31
	v_div_scale_f32 v33, vcc, 1.0, v16, 1.0
	v_mul_f32_e32 v34, v33, v31
	v_fma_f32 v35, -v30, v34, v33
	v_fmac_f32_e32 v34, v35, v31
	v_fma_f32 v30, -v30, v34, v33
	v_div_fmas_f32 v30, v30, v31, v34
	v_add_co_u32_e32 v26, vcc, s4, v4
	v_div_fixup_f32 v16, v30, v16, 1.0
	s_nop 0
	v_addc_co_u32_e32 v27, vcc, 0, v5, vcc
	v_mov_b32_e32 v20, v95
	v_fma_f32 v16, v9, v16, v24
	v_mov_b32_e32 v26, v94
	v_max_f32_e32 v16, 0xda24260, v16
	v_log_f32_e32 v16, v16
	s_waitcnt vmcnt(1)
	v_lshlrev_b32_e32 v28, 16, v20
	v_mul_f32_e32 v20, 0xbfb8aa3b, v28
	v_exp_f32_e32 v20, v20
	s_waitcnt vmcnt(0)
	v_lshlrev_b32_e32 v26, 16, v26
	v_mul_f32_e32 v27, 0x3e000000, v26
	v_add_f32_e32 v16, v15, v16
	v_add_f32_e32 v20, 1.0, v20
	v_div_scale_f32 v30, s[4:5], v20, v20, 1.0
	v_rcp_f32_e32 v31, v30
	s_mov_b32 s4, 0xc000
	v_fma_f32 v33, -v30, v31, 1.0
	v_fmac_f32_e32 v31, v33, v31
	v_div_scale_f32 v33, vcc, 1.0, v20, 1.0
	v_mul_f32_e32 v34, v33, v31
	v_fma_f32 v35, -v30, v34, v33
	v_fmac_f32_e32 v34, v35, v31
	v_fma_f32 v30, -v30, v34, v33
	v_div_fmas_f32 v30, v30, v31, v34
	v_div_fixup_f32 v20, v30, v20, 1.0
	v_add_co_u32_e32 v30, vcc, s4, v4
	v_fma_f32 v20, v9, v20, v24
	s_nop 0
	v_addc_co_u32_e32 v31, vcc, 0, v5, vcc
	v_mov_b32_e32 v26, v97
	v_max_f32_e32 v20, 0xda24260, v20
	v_mov_b32_e32 v30, v96
	v_log_f32_e32 v20, v20
	s_waitcnt vmcnt(1)
	v_lshlrev_b32_e32 v33, 16, v26
	v_mul_f32_e32 v26, 0xbfb8aa3b, v33
	v_exp_f32_e32 v26, v26
	s_waitcnt vmcnt(0)
	v_lshlrev_b32_e32 v30, 16, v30
	v_mul_f32_e32 v30, 0x3e000000, v30
	v_add_f32_e32 v20, v16, v20
	v_add_f32_e32 v26, 1.0, v26
	v_div_scale_f32 v34, s[4:5], v26, v26, 1.0
	v_rcp_f32_e32 v35, v34
	s_mov_b32 s4, 0xd000
	v_fma_f32 v36, -v34, v35, 1.0
	v_fmac_f32_e32 v35, v36, v35
	v_div_scale_f32 v36, vcc, 1.0, v26, 1.0
	v_mul_f32_e32 v37, v36, v35
	v_fma_f32 v38, -v34, v37, v36
	v_fmac_f32_e32 v37, v38, v35
	v_fma_f32 v34, -v34, v37, v36
	v_div_fmas_f32 v34, v34, v35, v37
	v_div_fixup_f32 v26, v34, v26, 1.0
	v_add_u32_e32 v34, 0x8800, v2
	ds_write2_b32 v34, v27, v30 offset0:6 offset1:71
	v_add_co_u32_e32 v30, vcc, s4, v4
	v_fma_f32 v26, v9, v26, v24
	s_nop 0
	v_addc_co_u32_e32 v31, vcc, 0, v5, vcc
	v_mov_b32_e32 v27, v99
	v_max_f32_e32 v26, 0xda24260, v26
	v_mov_b32_e32 v30, v98
	v_log_f32_e32 v26, v26
	s_waitcnt vmcnt(1)
	v_lshlrev_b32_e32 v35, 16, v27
	v_mul_f32_e32 v27, 0xbfb8aa3b, v35
	v_exp_f32_e32 v27, v27
	s_waitcnt vmcnt(0)
	v_lshlrev_b32_e32 v30, 16, v30
	v_mul_f32_e32 v31, 0x3e000000, v30
	v_add_f32_e32 v26, v20, v26
	v_add_f32_e32 v27, 1.0, v27
	v_div_scale_f32 v36, s[4:5], v27, v27, 1.0
	v_rcp_f32_e32 v37, v36
	s_mov_b32 s4, 0xf000
	v_fma_f32 v38, -v36, v37, 1.0
	v_fmac_f32_e32 v37, v38, v37
	v_div_scale_f32 v38, vcc, 1.0, v27, 1.0
	v_mul_f32_e32 v39, v38, v37
	v_fma_f32 v40, -v36, v39, v38
	v_fmac_f32_e32 v39, v40, v37
	v_fma_f32 v36, -v36, v39, v38
	v_div_fmas_f32 v36, v36, v37, v39
	v_add_co_u32_e32 v38, vcc, s4, v4
	v_div_fixup_f32 v27, v36, v27, 1.0
	s_nop 0
	v_addc_co_u32_e32 v39, vcc, 0, v5, vcc
	v_mov_b32_e32 v30, v101
	v_fma_f32 v27, v9, v27, v24
	v_max_f32_e32 v27, 0xda24260, v27
	v_log_f32_e32 v27, v27
	s_waitcnt vmcnt(0)
	v_lshlrev_b32_e32 v37, 16, v30
	v_mul_f32_e32 v30, 0xbfb8aa3b, v37
	v_exp_f32_e32 v30, v30
	v_add_f32_e32 v27, v26, v27
	v_add_f32_e32 v30, 1.0, v30
	v_div_scale_f32 v36, s[4:5], v30, v30, 1.0
	v_rcp_f32_e32 v40, v36
	s_mov_b32 s4, 0x10000
	v_fma_f32 v41, -v36, v40, 1.0
	v_fmac_f32_e32 v40, v41, v40
	v_div_scale_f32 v41, vcc, 1.0, v30, 1.0
	v_mul_f32_e32 v42, v41, v40
	v_fma_f32 v43, -v36, v42, v41
	v_fmac_f32_e32 v42, v43, v40
	v_fma_f32 v36, -v36, v42, v41
	v_div_fmas_f32 v36, v36, v40, v42
	v_div_fixup_f32 v30, v36, v30, 1.0
	v_mov_b32_e32 v36, v100
	v_add_co_u32_e32 v40, vcc, s4, v4
	v_fma_f32 v30, v9, v30, v24
	s_nop 0
	v_addc_co_u32_e32 v41, vcc, 0, v5, vcc
	v_max_f32_e32 v30, 0xda24260, v30
	v_log_f32_e32 v30, v30
	s_waitcnt vmcnt(0)
	v_lshlrev_b32_e32 v36, 16, v36
	v_mul_f32_e32 v36, 0x3e000000, v36
	ds_write2_b32 v34, v31, v36 offset0:136 offset1:201
	v_mov_b32_e32 v31, v103
	v_add_f32_e32 v30, v27, v30
	s_waitcnt vmcnt(0)
	v_lshlrev_b32_e32 v39, 16, v31
	v_mul_f32_e32 v31, 0xbfb8aa3b, v39
	v_exp_f32_e32 v31, v31
	s_nop 0
	v_add_f32_e32 v31, 1.0, v31
	v_div_scale_f32 v34, s[4:5], v31, v31, 1.0
	v_rcp_f32_e32 v36, v34
	s_mov_b32 s4, 0x12000
	v_fma_f32 v38, -v34, v36, 1.0
	v_fmac_f32_e32 v36, v38, v36
	v_div_scale_f32 v38, vcc, 1.0, v31, 1.0
	v_mul_f32_e32 v42, v38, v36
	v_fma_f32 v43, -v34, v42, v38
	v_fmac_f32_e32 v42, v43, v36
	v_fma_f32 v34, -v34, v42, v38
	v_div_fmas_f32 v34, v34, v36, v42
	v_div_fixup_f32 v31, v34, v31, 1.0
	v_mov_b32_e32 v34, v102
	v_add_co_u32_e32 v42, vcc, s4, v4
	v_fma_f32 v31, v9, v31, v24
	s_nop 0
	v_addc_co_u32_e32 v43, vcc, 0, v5, vcc
	v_max_f32_e32 v31, 0xda24260, v31
	v_log_f32_e32 v31, v31
	s_waitcnt vmcnt(0)
	v_lshlrev_b32_e32 v34, 16, v34
	v_mul_f32_e32 v36, 0x3e000000, v34
	v_mov_b32_e32 v34, v105
	v_add_f32_e32 v31, v30, v31
	s_waitcnt vmcnt(0)
	v_lshlrev_b32_e32 v40, 16, v34
	v_mul_f32_e32 v34, 0xbfb8aa3b, v40
	v_exp_f32_e32 v34, v34
	s_nop 0
	v_add_f32_e32 v34, 1.0, v34
	v_div_scale_f32 v38, s[4:5], v34, v34, 1.0
	v_rcp_f32_e32 v41, v38
	s_mov_b32 s4, 0x13000
	v_fma_f32 v44, -v38, v41, 1.0
	v_fmac_f32_e32 v41, v44, v41
	v_div_scale_f32 v44, vcc, 1.0, v34, 1.0
	v_mul_f32_e32 v45, v44, v41
	v_fma_f32 v46, -v38, v45, v44
	v_fmac_f32_e32 v45, v46, v41
	v_fma_f32 v38, -v38, v45, v44
	v_div_fmas_f32 v38, v38, v41, v45
	v_div_fixup_f32 v34, v38, v34, 1.0
	v_mov_b32_e32 v38, v104
	v_add_co_u32_e32 v42, vcc, s4, v4
	v_add_u32_e32 v46, 0x8c00, v2
	s_nop 0
	v_addc_co_u32_e32 v43, vcc, 0, v5, vcc
	v_fma_f32 v34, v9, v34, v24
	v_max_f32_e32 v34, 0xda24260, v34
	v_log_f32_e32 v34, v34
	s_waitcnt vmcnt(0)
	v_lshlrev_b32_e32 v38, 16, v38
	v_mul_f32_e32 v38, 0x3e000000, v38
	ds_write2_b32 v46, v36, v38 offset0:10 offset1:75
	v_mov_b32_e32 v36, v107
	v_add_f32_e32 v34, v31, v34
	s_waitcnt vmcnt(0)
	v_lshlrev_b32_e32 v41, 16, v36
	v_mul_f32_e32 v36, 0xbfb8aa3b, v41
	v_exp_f32_e32 v36, v36
	s_nop 0
	v_add_f32_e32 v36, 1.0, v36
	v_div_scale_f32 v38, s[4:5], v36, v36, 1.0
	v_rcp_f32_e32 v44, v38
	s_mov_b32 s4, 0x15000
	v_fma_f32 v45, -v38, v44, 1.0
	v_fmac_f32_e32 v44, v45, v44
	v_div_scale_f32 v45, vcc, 1.0, v36, 1.0
	v_mul_f32_e32 v47, v45, v44
	v_fma_f32 v48, -v38, v47, v45
	v_fmac_f32_e32 v47, v48, v44
	v_fma_f32 v38, -v38, v47, v45
	v_div_fmas_f32 v38, v38, v44, v47
	v_div_fixup_f32 v36, v38, v36, 1.0
	v_mov_b32_e32 v38, v106
	v_add_co_u32_e32 v44, vcc, s4, v4
	v_fma_f32 v36, v9, v36, v24
	s_nop 0
	v_addc_co_u32_e32 v45, vcc, 0, v5, vcc
	v_max_f32_e32 v36, 0xda24260, v36
	v_log_f32_e32 v36, v36
	s_waitcnt vmcnt(0)
	v_lshlrev_b32_e32 v38, 16, v38
	v_mul_f32_e32 v43, 0x3e000000, v38
	v_mov_b32_e32 v38, v109
	v_add_f32_e32 v36, v34, v36
	v_mov_b32_e32 v44, v108
	s_waitcnt vmcnt(1)
	v_lshlrev_b32_e32 v42, 16, v38
	v_mul_f32_e32 v38, 0xbfb8aa3b, v42
	v_exp_f32_e32 v38, v38
	s_waitcnt vmcnt(0)
	v_lshlrev_b32_e32 v44, 16, v44
	v_mul_f32_e32 v44, 0x3e000000, v44
	ds_write2_b32 v46, v43, v44 offset0:140 offset1:205
	v_add_f32_e32 v38, 1.0, v38
	v_div_scale_f32 v47, s[4:5], v38, v38, 1.0
	v_rcp_f32_e32 v48, v47
	s_mov_b32 s4, 0x16000
	v_fma_f32 v49, -v47, v48, 1.0
	v_fmac_f32_e32 v48, v49, v48
	v_div_scale_f32 v49, vcc, 1.0, v38, 1.0
	v_mul_f32_e32 v50, v49, v48
	v_fma_f32 v51, -v47, v50, v49
	v_fmac_f32_e32 v50, v51, v48
	v_fma_f32 v47, -v47, v50, v49
	v_div_fmas_f32 v47, v47, v48, v50
	v_add_co_u32_e32 v44, vcc, s4, v4
	v_div_fixup_f32 v38, v47, v38, 1.0
	s_nop 0
	v_addc_co_u32_e32 v45, vcc, 0, v5, vcc
	v_mov_b32_e32 v4, v111
	v_fma_f32 v38, v9, v38, v24
	v_max_f32_e32 v38, 0xda24260, v38
	v_log_f32_e32 v38, v38
	s_waitcnt vmcnt(0)
	v_lshlrev_b32_e32 v5, 16, v4
	v_mul_f32_e32 v4, 0xbfb8aa3b, v5
	v_exp_f32_e32 v4, v4
	v_add_f32_e32 v38, v36, v38
	v_add_f32_e32 v4, 1.0, v4
	v_div_scale_f32 v43, s[4:5], v4, v4, 1.0
	v_rcp_f32_e32 v46, v43
	s_nop 0
	v_fma_f32 v47, -v43, v46, 1.0
	v_fmac_f32_e32 v46, v47, v46
	v_div_scale_f32 v47, vcc, 1.0, v4, 1.0
	v_mul_f32_e32 v48, v47, v46
	v_fma_f32 v49, -v43, v48, v47
	v_fmac_f32_e32 v48, v49, v46
	v_fma_f32 v43, -v43, v48, v47
	v_div_fmas_f32 v43, v43, v46, v48
	v_div_fixup_f32 v4, v43, v4, 1.0
	v_fmac_f32_e32 v24, v9, v4
	v_max_f32_e32 v4, 0xda24260, v24
	v_mov_b32_e32 v24, v110
	v_log_f32_e32 v4, v4
	v_cmp_lt_i32_e32 vcc, 0, v29
	v_add_f32_e32 v4, v38, v4
	s_waitcnt vmcnt(0)
	v_lshlrev_b32_e32 v24, 16, v24
	v_mul_f32_e32 v24, 0x3e000000, v24
	ds_write_b32 v2, v24 offset:36920
	v_lshlrev_b32_e32 v2, 2, v32
	ds_write_b32 v2, v4 offset:49920
	s_waitcnt lgkmcnt(0)
	s_barrier
	s_and_saveexec_b64 s[4:5], vcc
	s_cbranch_execnz .LBB0_238
	s_or_b64 exec, exec, s[4:5]
	v_cmp_lt_i32_e32 vcc, 1, v29
	s_and_saveexec_b64 s[4:5], vcc
	s_cbranch_execnz .LBB0_239

.LBB0_269:
	s_lshr_b32 s23, s15, 8
	v_ashrrev_i32_e32 v4, 6, v3
	s_lshl_b32 s13, s23, 12
	s_and_b32 s22, s20, 0xfc0
	s_or_b32 s13, s13, s22
	v_lshlrev_b32_e32 v5, 4, v4
	v_add_u32_e32 v6, s13, v5
	v_mov_b64_e32 v[0:1], s[82:83]
	v_mad_i64_i32 v[0:1], s[24:25], v6, s63, v[0:1]
	s_lshl_b32 s84, s12, 1
	v_lshl_add_u64 v[0:1], v[0:1], 0, s[84:85]
	v_lshlrev_b32_e32 v152, 1, v2
	v_lshl_add_u64 v[0:1], v[0:1], 0, v[152:153]
	v_add_co_u32_e32 v6, vcc, s86, v0
	s_nop 0
	v_addc_co_u32_e32 v7, vcc, 0, v1, vcc
	s_mul_i32 s30, s13, 0x1800
	s_add_u32 s28, s82, s30
	s_addc_u32 s29, s83, 0
	s_add_u32 s28, s28, s84
	s_addc_u32 s29, s29, 0
	s_add_u32 s28, s28, s86
	s_addc_u32 s29, s29, 0
	s_add_u32 s28, s28, 0xb00
	s_addc_u32 s29, s29, 0
	v_mul_u32_u24_e32 v97, 0x1800, v5
	v_add_u32_e32 v96, v97, v152
	global_load_ushort v80, v96, s[28:29]
	s_add_u32 s28, s28, 0x1800
	s_addc_u32 s29, s29, 0
	global_load_ushort v81, v96, s[28:29]
	s_add_u32 s28, s28, 0x1800
	s_addc_u32 s29, s29, 0
	global_load_ushort v82, v96, s[28:29]
	s_add_u32 s28, s28, 0x1800
	s_addc_u32 s29, s29, 0
	global_load_ushort v83, v96, s[28:29]
	s_add_u32 s28, s28, 0x1800
	s_addc_u32 s29, s29, 0
	global_load_ushort v84, v96, s[28:29]
	s_add_u32 s28, s28, 0x1800
	s_addc_u32 s29, s29, 0
	global_load_ushort v85, v96, s[28:29]
	s_add_u32 s28, s28, 0x1800
	s_addc_u32 s29, s29, 0
	global_load_ushort v86, v96, s[28:29]
	s_add_u32 s28, s28, 0x1800
	s_addc_u32 s29, s29, 0
	global_load_ushort v87, v96, s[28:29]
	s_add_u32 s28, s28, 0x1800
	s_addc_u32 s29, s29, 0
	global_load_ushort v88, v96, s[28:29]
	s_add_u32 s28, s28, 0x1800
	s_addc_u32 s29, s29, 0
	global_load_ushort v89, v96, s[28:29]
	s_add_u32 s28, s28, 0x1800
	s_addc_u32 s29, s29, 0
	global_load_ushort v90, v96, s[28:29]
	s_add_u32 s28, s28, 0x1800
	s_addc_u32 s29, s29, 0
	global_load_ushort v91, v96, s[28:29]
	s_add_u32 s28, s28, 0x1800
	s_addc_u32 s29, s29, 0
	global_load_ushort v92, v96, s[28:29]
	s_add_u32 s28, s28, 0x1800
	s_addc_u32 s29, s29, 0
	global_load_ushort v93, v96, s[28:29]
	s_add_u32 s28, s28, 0x1800
	s_addc_u32 s29, s29, 0
	global_load_ushort v94, v96, s[28:29]
	s_add_u32 s28, s28, 0x1800
	s_addc_u32 s29, s29, 0
	global_load_ushort v95, v96, s[28:29]
	s_add_u32 s28, s28, 0x1800
	s_addc_u32 s29, s29, 0
	s_andn2_b64 vcc, exec, s[6:7]
	s_cbranch_vccnz .Lha_lb0
	v_or_b32_e32 v114, s12, v2
	v_lshlrev_b32_e32 v114, 2, v114
	global_load_dword v115, v114, s[50:51]
	global_load_dword v114, v114, s[50:51] offset:1024
	s_waitcnt vmcnt(0)
	v_sub_f32_e32 v114, v115, v114
	v_mul_f32_e32 v114, 0x3fb8aa3b, v114
	v_exp_f32_e32 v114, v114
	s_nop 0
	v_add_f32_e32 v114, 1.0, v114
	v_div_scale_f32 v115, vcc, v114, v114, 1.0
	v_rcp_f32_e32 v116, v115
	v_div_scale_f32 v117, vcc, 1.0, v114, 1.0
	v_fma_f32 v118, -v115, v116, 1.0
	v_fmac_f32_e32 v116, v118, v116
	v_mul_f32_e32 v118, v117, v116
	v_fma_f32 v119, -v115, v118, v117
	v_fmac_f32_e32 v118, v119, v116
	v_fma_f32 v115, -v115, v118, v117
	v_div_fmas_f32 v115, v115, v116, v118
	v_div_fixup_f32 v8, v115, v114, 1.0
.Lha_lb0:
	v_sub_f32_e32 v9, 1.0, v8
	s_waitcnt vmcnt(0)
	v_mov_b32_e32 v6, v80
	s_waitcnt vmcnt(0)
	v_lshlrev_b32_e32 v6, 16, v6
	v_mul_f32_e32 v7, 0xbfb8aa3b, v6
	v_exp_f32_e32 v7, v7
	v_mul_f32_e32 v6, 0x3fb8aa3b, v6
	v_exp_f32_e32 v6, v6
	v_add_f32_e32 v7, 1.0, v7
	v_div_scale_f32 v10, s[12:13], v7, v7, 1.0
	v_rcp_f32_e32 v11, v10
	v_add_f32_e32 v6, 1.0, v6
	v_fma_f32 v12, -v10, v11, 1.0
	v_fmac_f32_e32 v11, v12, v11
	v_div_scale_f32 v12, vcc, 1.0, v7, 1.0
	v_mul_f32_e32 v13, v12, v11
	v_fma_f32 v14, -v10, v13, v12
	v_fmac_f32_e32 v13, v14, v11
	v_fma_f32 v10, -v10, v13, v12
	v_div_fmas_f32 v10, v10, v11, v13
	v_div_fixup_f32 v7, v10, v7, 1.0
	v_div_scale_f32 v10, s[12:13], v6, v6, 1.0
	v_rcp_f32_e32 v11, v10
	s_mov_b32 s12, 0xa952000
	v_fma_f32 v7, v9, v7, v8
	v_max_f32_e32 v7, 0xda24260, v7
	v_fma_f32 v12, -v10, v11, 1.0
	v_fmac_f32_e32 v11, v12, v11
	v_div_scale_f32 v12, vcc, 1.0, v6, 1.0
	v_mul_f32_e32 v13, v12, v11
	v_fma_f32 v14, -v10, v13, v12
	v_fmac_f32_e32 v13, v14, v11
	v_fma_f32 v10, -v10, v13, v12
	v_div_fmas_f32 v10, v10, v11, v13
	v_div_fixup_f32 v6, v10, v6, 1.0
	v_add_co_u32_e32 v10, vcc, s12, v0
	v_log_f32_e32 v7, v7
	s_nop 0
	v_addc_co_u32_e32 v11, vcc, 0, v1, vcc
	v_mov_b32_e32 v10, v81
	v_add_f32_e32 v7, 0, v7
	v_mul_f32_e32 v6, v9, v6
	s_waitcnt vmcnt(0)
	v_lshlrev_b32_e32 v10, 16, v10
	v_mul_f32_e32 v11, 0xbfb8aa3b, v10
	v_exp_f32_e32 v11, v11
	v_mul_f32_e32 v10, 0x3fb8aa3b, v10
	v_exp_f32_e32 v10, v10
	v_add_f32_e32 v11, 1.0, v11
	v_div_scale_f32 v12, s[12:13], v11, v11, 1.0
	v_rcp_f32_e32 v13, v12
	v_add_f32_e32 v10, 1.0, v10
	v_fma_f32 v14, -v12, v13, 1.0
	v_fmac_f32_e32 v13, v14, v13
	v_div_scale_f32 v14, vcc, 1.0, v11, 1.0
	v_mul_f32_e32 v15, v14, v13
	v_fma_f32 v16, -v12, v15, v14
	v_fmac_f32_e32 v15, v16, v13
	v_fma_f32 v12, -v12, v15, v14
	v_div_fmas_f32 v12, v12, v13, v15
	v_div_fixup_f32 v11, v12, v11, 1.0
	v_div_scale_f32 v12, s[12:13], v10, v10, 1.0
	v_rcp_f32_e32 v13, v12
	s_mov_b32 s12, 0xa953000
	v_fma_f32 v11, v9, v11, v8
	v_max_f32_e32 v11, 0xda24260, v11
	v_fma_f32 v14, -v12, v13, 1.0
	v_fmac_f32_e32 v13, v14, v13
	v_div_scale_f32 v14, vcc, 1.0, v10, 1.0
	v_mul_f32_e32 v15, v14, v13
	v_fma_f32 v16, -v12, v15, v14
	v_fmac_f32_e32 v15, v16, v13
	v_fma_f32 v12, -v12, v15, v14
	v_div_fmas_f32 v12, v12, v13, v15
	v_div_fixup_f32 v10, v12, v10, 1.0
	v_add_co_u32_e32 v12, vcc, s12, v0
	v_log_f32_e32 v11, v11
	s_nop 0
	v_addc_co_u32_e32 v13, vcc, 0, v1, vcc
	v_mov_b32_e32 v12, v82
	v_add_f32_e32 v11, v7, v11
	v_mul_f32_e32 v10, v9, v10
	s_waitcnt vmcnt(0)
	v_lshlrev_b32_e32 v12, 16, v12
	v_mul_f32_e32 v13, 0xbfb8aa3b, v12
	v_exp_f32_e32 v13, v13
	v_mul_f32_e32 v12, 0x3fb8aa3b, v12
	v_exp_f32_e32 v12, v12
	v_add_f32_e32 v13, 1.0, v13
	v_div_scale_f32 v14, s[12:13], v13, v13, 1.0
	v_rcp_f32_e32 v15, v14
	v_add_f32_e32 v12, 1.0, v12
	v_fma_f32 v16, -v14, v15, 1.0
	v_fmac_f32_e32 v15, v16, v15
	v_div_scale_f32 v16, vcc, 1.0, v13, 1.0
	v_mul_f32_e32 v17, v16, v15
	v_fma_f32 v18, -v14, v17, v16
	v_fmac_f32_e32 v17, v18, v15
	v_fma_f32 v14, -v14, v17, v16
	v_div_fmas_f32 v14, v14, v15, v17
	v_div_fixup_f32 v13, v14, v13, 1.0
	v_div_scale_f32 v14, s[12:13], v12, v12, 1.0
	v_rcp_f32_e32 v15, v14
	s_mov_b32 s12, 0xa955000
	v_fma_f32 v13, v9, v13, v8
	v_max_f32_e32 v13, 0xda24260, v13
	v_fma_f32 v16, -v14, v15, 1.0
	v_fmac_f32_e32 v15, v16, v15
	v_div_scale_f32 v16, vcc, 1.0, v12, 1.0
	v_mul_f32_e32 v17, v16, v15
	v_fma_f32 v18, -v14, v17, v16
	v_fmac_f32_e32 v17, v18, v15
	v_fma_f32 v14, -v14, v17, v16
	v_div_fmas_f32 v14, v14, v15, v17
	v_div_fixup_f32 v12, v14, v12, 1.0
	v_add_co_u32_e32 v14, vcc, s12, v0
	v_log_f32_e32 v13, v13
	s_nop 0
	v_addc_co_u32_e32 v15, vcc, 0, v1, vcc
	v_mov_b32_e32 v14, v83
	v_add_f32_e32 v13, v11, v13
	v_mul_f32_e32 v12, v9, v12
	s_waitcnt vmcnt(0)
	v_lshlrev_b32_e32 v14, 16, v14
	v_mul_f32_e32 v15, 0xbfb8aa3b, v14
	v_exp_f32_e32 v15, v15
	v_mul_f32_e32 v14, 0x3fb8aa3b, v14
	v_exp_f32_e32 v14, v14
	v_add_f32_e32 v15, 1.0, v15
	v_div_scale_f32 v16, s[12:13], v15, v15, 1.0
	v_rcp_f32_e32 v17, v16
	v_add_f32_e32 v14, 1.0, v14
	v_fma_f32 v18, -v16, v17, 1.0
	v_fmac_f32_e32 v17, v18, v17
	v_div_scale_f32 v18, vcc, 1.0, v15, 1.0
	v_mul_f32_e32 v19, v18, v17
	v_fma_f32 v20, -v16, v19, v18
	v_fmac_f32_e32 v19, v20, v17
	v_fma_f32 v16, -v16, v19, v18
	v_div_fmas_f32 v16, v16, v17, v19
	v_div_fixup_f32 v15, v16, v15, 1.0
	v_div_scale_f32 v16, s[12:13], v14, v14, 1.0
	v_rcp_f32_e32 v17, v16
	s_mov_b32 s12, 0xa956000
	v_fma_f32 v15, v9, v15, v8
	v_max_f32_e32 v15, 0xda24260, v15
	v_fma_f32 v18, -v16, v17, 1.0
	v_fmac_f32_e32 v17, v18, v17
	v_div_scale_f32 v18, vcc, 1.0, v14, 1.0
	v_mul_f32_e32 v19, v18, v17
	v_fma_f32 v20, -v16, v19, v18
	v_fmac_f32_e32 v19, v20, v17
	v_fma_f32 v16, -v16, v19, v18
	v_div_fmas_f32 v16, v16, v17, v19
	v_div_fixup_f32 v14, v16, v14, 1.0
	v_add_co_u32_e32 v16, vcc, s12, v0
	v_log_f32_e32 v15, v15
	s_nop 0
	v_addc_co_u32_e32 v17, vcc, 0, v1, vcc
	v_mov_b32_e32 v16, v84
	v_add_f32_e32 v15, v13, v15
	v_mul_f32_e32 v14, v9, v14
	s_waitcnt vmcnt(0)
	v_lshlrev_b32_e32 v16, 16, v16
	v_mul_f32_e32 v17, 0xbfb8aa3b, v16
	v_exp_f32_e32 v17, v17
	v_mul_f32_e32 v16, 0x3fb8aa3b, v16
	v_exp_f32_e32 v16, v16
	v_add_f32_e32 v17, 1.0, v17
	v_div_scale_f32 v18, s[12:13], v17, v17, 1.0
	v_rcp_f32_e32 v19, v18
	v_add_f32_e32 v16, 1.0, v16
	v_fma_f32 v20, -v18, v19, 1.0
	v_fmac_f32_e32 v19, v20, v19
	v_div_scale_f32 v20, vcc, 1.0, v17, 1.0
	v_mul_f32_e32 v21, v20, v19
	v_fma_f32 v22, -v18, v21, v20
	v_fmac_f32_e32 v21, v22, v19
	v_fma_f32 v18, -v18, v21, v20
	v_div_fmas_f32 v18, v18, v19, v21
	v_div_fixup_f32 v17, v18, v17, 1.0
	v_div_scale_f32 v18, s[12:13], v16, v16, 1.0
	v_rcp_f32_e32 v19, v18
	s_mov_b32 s12, 0xa958000
	v_fma_f32 v17, v9, v17, v8
	v_max_f32_e32 v17, 0xda24260, v17
	v_fma_f32 v20, -v18, v19, 1.0
	v_fmac_f32_e32 v19, v20, v19
	v_div_scale_f32 v20, vcc, 1.0, v16, 1.0
	v_mul_f32_e32 v21, v20, v19
	v_fma_f32 v22, -v18, v21, v20
	v_fmac_f32_e32 v21, v22, v19
	v_fma_f32 v18, -v18, v21, v20
	v_div_fmas_f32 v18, v18, v19, v21
	v_div_fixup_f32 v16, v18, v16, 1.0
	v_add_co_u32_e32 v18, vcc, s12, v0
	v_log_f32_e32 v17, v17
	s_nop 0
	v_addc_co_u32_e32 v19, vcc, 0, v1, vcc
	v_mov_b32_e32 v18, v85
	v_add_f32_e32 v17, v15, v17
	v_mul_f32_e32 v16, v9, v16
	s_waitcnt vmcnt(0)
	v_lshlrev_b32_e32 v18, 16, v18
	v_mul_f32_e32 v19, 0xbfb8aa3b, v18
	v_exp_f32_e32 v19, v19
	v_mul_f32_e32 v18, 0x3fb8aa3b, v18
	v_exp_f32_e32 v18, v18
	v_add_f32_e32 v19, 1.0, v19
	v_div_scale_f32 v20, s[12:13], v19, v19, 1.0
	v_rcp_f32_e32 v21, v20
	v_add_f32_e32 v18, 1.0, v18
	v_fma_f32 v22, -v20, v21, 1.0
	v_fmac_f32_e32 v21, v22, v21
	v_div_scale_f32 v22, vcc, 1.0, v19, 1.0
	v_mul_f32_e32 v23, v22, v21
	v_fma_f32 v24, -v20, v23, v22
	v_fmac_f32_e32 v23, v24, v21
	v_fma_f32 v20, -v20, v23, v22
	v_div_fmas_f32 v20, v20, v21, v23
	v_div_fixup_f32 v19, v20, v19, 1.0
	v_div_scale_f32 v20, s[12:13], v18, v18, 1.0
	v_rcp_f32_e32 v21, v20
	s_mov_b32 s12, 0xa959000
	v_fma_f32 v19, v9, v19, v8
	v_max_f32_e32 v19, 0xda24260, v19
	v_fma_f32 v22, -v20, v21, 1.0
	v_fmac_f32_e32 v21, v22, v21
	v_div_scale_f32 v22, vcc, 1.0, v18, 1.0
	v_mul_f32_e32 v23, v22, v21
	v_fma_f32 v24, -v20, v23, v22
	v_fmac_f32_e32 v23, v24, v21
	v_fma_f32 v20, -v20, v23, v22
	v_div_fmas_f32 v20, v20, v21, v23
	v_div_fixup_f32 v18, v20, v18, 1.0
	v_add_co_u32_e32 v20, vcc, s12, v0
	v_log_f32_e32 v19, v19
	s_nop 0
	v_addc_co_u32_e32 v21, vcc, 0, v1, vcc
	v_mov_b32_e32 v20, v86
	v_add_f32_e32 v19, v17, v19
	v_mul_f32_e32 v18, v9, v18
	s_waitcnt vmcnt(0)
	v_lshlrev_b32_e32 v20, 16, v20
	v_mul_f32_e32 v21, 0xbfb8aa3b, v20
	v_exp_f32_e32 v21, v21
	v_mul_f32_e32 v20, 0x3fb8aa3b, v20
	v_exp_f32_e32 v20, v20
	v_add_f32_e32 v21, 1.0, v21
	v_div_scale_f32 v22, s[12:13], v21, v21, 1.0
	v_rcp_f32_e32 v23, v22
	v_add_f32_e32 v20, 1.0, v20
	v_fma_f32 v24, -v22, v23, 1.0
	v_fmac_f32_e32 v23, v24, v23
	v_div_scale_f32 v24, vcc, 1.0, v21, 1.0
	v_mul_f32_e32 v25, v24, v23
	v_fma_f32 v26, -v22, v25, v24
	v_fmac_f32_e32 v25, v26, v23
	v_fma_f32 v22, -v22, v25, v24
	v_div_fmas_f32 v22, v22, v23, v25
	v_div_fixup_f32 v21, v22, v21, 1.0
	v_div_scale_f32 v22, s[12:13], v20, v20, 1.0
	v_rcp_f32_e32 v23, v22
	s_mov_b32 s12, 0xa95b000
	v_fma_f32 v21, v9, v21, v8
	v_max_f32_e32 v21, 0xda24260, v21
	v_fma_f32 v24, -v22, v23, 1.0
	v_fmac_f32_e32 v23, v24, v23
	v_div_scale_f32 v24, vcc, 1.0, v20, 1.0
	v_mul_f32_e32 v25, v24, v23
	v_fma_f32 v26, -v22, v25, v24
	v_fmac_f32_e32 v25, v26, v23
	v_fma_f32 v22, -v22, v25, v24
	v_div_fmas_f32 v22, v22, v23, v25
	v_div_fixup_f32 v20, v22, v20, 1.0
	v_add_co_u32_e32 v22, vcc, s12, v0
	v_log_f32_e32 v21, v21
	s_nop 0
	v_addc_co_u32_e32 v23, vcc, 0, v1, vcc
	v_mov_b32_e32 v22, v87
	v_add_f32_e32 v21, v19, v21
	v_mul_f32_e32 v20, v9, v20
	s_waitcnt vmcnt(0)
	v_lshlrev_b32_e32 v22, 16, v22
	v_mul_f32_e32 v23, 0xbfb8aa3b, v22
	v_exp_f32_e32 v23, v23
	v_mul_f32_e32 v22, 0x3fb8aa3b, v22
	v_exp_f32_e32 v22, v22
	v_add_f32_e32 v23, 1.0, v23
	v_div_scale_f32 v24, s[12:13], v23, v23, 1.0
	v_rcp_f32_e32 v25, v24
	v_add_f32_e32 v22, 1.0, v22
	v_fma_f32 v26, -v24, v25, 1.0
	v_fmac_f32_e32 v25, v26, v25
	v_div_scale_f32 v26, vcc, 1.0, v23, 1.0
	v_mul_f32_e32 v27, v26, v25
	v_fma_f32 v28, -v24, v27, v26
	v_fmac_f32_e32 v27, v28, v25
	v_fma_f32 v24, -v24, v27, v26
	v_div_fmas_f32 v24, v24, v25, v27
	v_div_fixup_f32 v23, v24, v23, 1.0
	v_div_scale_f32 v24, s[12:13], v22, v22, 1.0
	v_rcp_f32_e32 v25, v24
	s_mov_b32 s12, 0xa95c000
	v_fma_f32 v23, v9, v23, v8
	v_max_f32_e32 v23, 0xda24260, v23
	v_fma_f32 v26, -v24, v25, 1.0
	v_fmac_f32_e32 v25, v26, v25
	v_div_scale_f32 v26, vcc, 1.0, v22, 1.0
	v_mul_f32_e32 v27, v26, v25
	v_fma_f32 v28, -v24, v27, v26
	v_fmac_f32_e32 v27, v28, v25
	v_fma_f32 v24, -v24, v27, v26
	v_div_fmas_f32 v24, v24, v25, v27
	v_div_fixup_f32 v22, v24, v22, 1.0
	v_add_co_u32_e32 v24, vcc, s12, v0
	v_log_f32_e32 v23, v23
	s_nop 0
	v_addc_co_u32_e32 v25, vcc, 0, v1, vcc
	v_mov_b32_e32 v24, v88
	v_add_f32_e32 v23, v21, v23
	v_mul_f32_e32 v22, v9, v22
	s_waitcnt vmcnt(0)
	v_lshlrev_b32_e32 v24, 16, v24
	v_mul_f32_e32 v25, 0xbfb8aa3b, v24
	v_exp_f32_e32 v25, v25
	v_mul_f32_e32 v24, 0x3fb8aa3b, v24
	v_exp_f32_e32 v24, v24
	v_add_f32_e32 v25, 1.0, v25
	v_div_scale_f32 v26, s[12:13], v25, v25, 1.0
	v_rcp_f32_e32 v27, v26
	v_add_f32_e32 v24, 1.0, v24
	v_fma_f32 v28, -v26, v27, 1.0
	v_fmac_f32_e32 v27, v28, v27
	v_div_scale_f32 v28, vcc, 1.0, v25, 1.0
	v_mul_f32_e32 v29, v28, v27
	v_fma_f32 v30, -v26, v29, v28
	v_fmac_f32_e32 v29, v30, v27
	v_fma_f32 v26, -v26, v29, v28
	v_div_fmas_f32 v26, v26, v27, v29
	v_div_fixup_f32 v25, v26, v25, 1.0
	v_div_scale_f32 v26, s[12:13], v24, v24, 1.0
	v_rcp_f32_e32 v27, v26
	s_mov_b32 s12, 0xa95e000
	v_fma_f32 v25, v9, v25, v8
	v_max_f32_e32 v25, 0xda24260, v25
	v_fma_f32 v28, -v26, v27, 1.0
	v_fmac_f32_e32 v27, v28, v27
	v_div_scale_f32 v28, vcc, 1.0, v24, 1.0
	v_mul_f32_e32 v29, v28, v27
	v_fma_f32 v30, -v26, v29, v28
	v_fmac_f32_e32 v29, v30, v27
	v_fma_f32 v26, -v26, v29, v28
	v_div_fmas_f32 v26, v26, v27, v29
	v_div_fixup_f32 v24, v26, v24, 1.0
	v_add_co_u32_e32 v26, vcc, s12, v0
	v_log_f32_e32 v25, v25
	s_nop 0
	v_addc_co_u32_e32 v27, vcc, 0, v1, vcc
	v_mov_b32_e32 v26, v89
	v_add_f32_e32 v25, v23, v25
	v_mul_f32_e32 v24, v9, v24
	s_waitcnt vmcnt(0)
	v_lshlrev_b32_e32 v26, 16, v26
	v_mul_f32_e32 v27, 0xbfb8aa3b, v26
	v_exp_f32_e32 v27, v27
	v_mul_f32_e32 v26, 0x3fb8aa3b, v26
	v_exp_f32_e32 v26, v26
	v_add_f32_e32 v27, 1.0, v27
	v_div_scale_f32 v28, s[12:13], v27, v27, 1.0
	v_rcp_f32_e32 v29, v28
	v_add_f32_e32 v26, 1.0, v26
	v_fma_f32 v30, -v28, v29, 1.0
	v_fmac_f32_e32 v29, v30, v29
	v_div_scale_f32 v30, vcc, 1.0, v27, 1.0
	v_mul_f32_e32 v31, v30, v29
	v_fma_f32 v32, -v28, v31, v30
	v_fmac_f32_e32 v31, v32, v29
	v_fma_f32 v28, -v28, v31, v30
	v_div_fmas_f32 v28, v28, v29, v31
	v_div_fixup_f32 v27, v28, v27, 1.0
	v_div_scale_f32 v28, s[12:13], v26, v26, 1.0
	v_rcp_f32_e32 v29, v28
	s_mov_b32 s12, 0xa95f000
	v_fma_f32 v27, v9, v27, v8
	v_max_f32_e32 v27, 0xda24260, v27
	v_fma_f32 v30, -v28, v29, 1.0
	v_fmac_f32_e32 v29, v30, v29
	v_div_scale_f32 v30, vcc, 1.0, v26, 1.0
	v_mul_f32_e32 v31, v30, v29
	v_fma_f32 v32, -v28, v31, v30
	v_fmac_f32_e32 v31, v32, v29
	v_fma_f32 v28, -v28, v31, v30
	v_div_fmas_f32 v28, v28, v29, v31
	v_div_fixup_f32 v26, v28, v26, 1.0
	v_add_co_u32_e32 v28, vcc, s12, v0
	v_log_f32_e32 v27, v27
	s_nop 0
	v_addc_co_u32_e32 v29, vcc, 0, v1, vcc
	v_mov_b32_e32 v28, v90
	v_add_f32_e32 v27, v25, v27
	v_mul_f32_e32 v26, v9, v26
	s_waitcnt vmcnt(0)
	v_lshlrev_b32_e32 v28, 16, v28
	v_mul_f32_e32 v29, 0xbfb8aa3b, v28
	v_exp_f32_e32 v29, v29
	v_mul_f32_e32 v28, 0x3fb8aa3b, v28
	v_exp_f32_e32 v28, v28
	v_add_f32_e32 v29, 1.0, v29
	v_div_scale_f32 v30, s[12:13], v29, v29, 1.0
	v_rcp_f32_e32 v31, v30
	v_add_f32_e32 v28, 1.0, v28
	v_fma_f32 v32, -v30, v31, 1.0
	v_fmac_f32_e32 v31, v32, v31
	v_div_scale_f32 v32, vcc, 1.0, v29, 1.0
	v_mul_f32_e32 v33, v32, v31
	v_fma_f32 v34, -v30, v33, v32
	v_fmac_f32_e32 v33, v34, v31
	v_fma_f32 v30, -v30, v33, v32
	v_div_fmas_f32 v30, v30, v31, v33
	v_div_fixup_f32 v29, v30, v29, 1.0
	v_div_scale_f32 v30, s[12:13], v28, v28, 1.0
	v_rcp_f32_e32 v31, v30
	s_mov_b32 s12, 0xa961000
	v_fma_f32 v29, v9, v29, v8
	v_max_f32_e32 v29, 0xda24260, v29
	v_fma_f32 v32, -v30, v31, 1.0
	v_fmac_f32_e32 v31, v32, v31
	v_div_scale_f32 v32, vcc, 1.0, v28, 1.0
	v_mul_f32_e32 v33, v32, v31
	v_fma_f32 v34, -v30, v33, v32
	v_fmac_f32_e32 v33, v34, v31
	v_fma_f32 v30, -v30, v33, v32
	v_div_fmas_f32 v30, v30, v31, v33
	v_div_fixup_f32 v28, v30, v28, 1.0
	v_add_co_u32_e32 v30, vcc, s12, v0
	v_log_f32_e32 v29, v29
	s_nop 0
	v_addc_co_u32_e32 v31, vcc, 0, v1, vcc
	v_mov_b32_e32 v30, v91
	v_add_f32_e32 v29, v27, v29
	v_mul_f32_e32 v28, v9, v28
	s_waitcnt vmcnt(0)
	v_lshlrev_b32_e32 v30, 16, v30
	v_mul_f32_e32 v31, 0xbfb8aa3b, v30
	v_exp_f32_e32 v31, v31
	v_mul_f32_e32 v30, 0x3fb8aa3b, v30
	v_exp_f32_e32 v30, v30
	v_add_f32_e32 v31, 1.0, v31
	v_div_scale_f32 v32, s[12:13], v31, v31, 1.0
	v_rcp_f32_e32 v33, v32
	v_add_f32_e32 v30, 1.0, v30
	v_fma_f32 v34, -v32, v33, 1.0
	v_fmac_f32_e32 v33, v34, v33
	v_div_scale_f32 v34, vcc, 1.0, v31, 1.0
	v_mul_f32_e32 v35, v34, v33
	v_fma_f32 v36, -v32, v35, v34
	v_fmac_f32_e32 v35, v36, v33
	v_fma_f32 v32, -v32, v35, v34
	v_div_fmas_f32 v32, v32, v33, v35
	v_div_fixup_f32 v31, v32, v31, 1.0
	v_div_scale_f32 v32, s[12:13], v30, v30, 1.0
	v_rcp_f32_e32 v33, v32
	s_mov_b32 s12, 0xa962000
	v_fma_f32 v31, v9, v31, v8
	v_max_f32_e32 v31, 0xda24260, v31
	v_fma_f32 v34, -v32, v33, 1.0
	v_fmac_f32_e32 v33, v34, v33
	v_div_scale_f32 v34, vcc, 1.0, v30, 1.0
	v_mul_f32_e32 v35, v34, v33
	v_fma_f32 v36, -v32, v35, v34
	v_fmac_f32_e32 v35, v36, v33
	v_fma_f32 v32, -v32, v35, v34
	v_div_fmas_f32 v32, v32, v33, v35
	v_div_fixup_f32 v30, v32, v30, 1.0
	v_add_co_u32_e32 v32, vcc, s12, v0
	v_log_f32_e32 v31, v31
	s_nop 0
	v_addc_co_u32_e32 v33, vcc, 0, v1, vcc
	v_mov_b32_e32 v32, v92
	v_add_f32_e32 v31, v29, v31
	v_mul_f32_e32 v30, v9, v30
	s_waitcnt vmcnt(0)
	v_lshlrev_b32_e32 v32, 16, v32
	v_mul_f32_e32 v33, 0xbfb8aa3b, v32
	v_exp_f32_e32 v33, v33
	v_mul_f32_e32 v32, 0x3fb8aa3b, v32
	v_exp_f32_e32 v32, v32
	v_add_f32_e32 v33, 1.0, v33
	v_div_scale_f32 v34, s[12:13], v33, v33, 1.0
	v_rcp_f32_e32 v35, v34
	v_add_f32_e32 v32, 1.0, v32
	v_fma_f32 v36, -v34, v35, 1.0
	v_fmac_f32_e32 v35, v36, v35
	v_div_scale_f32 v36, vcc, 1.0, v33, 1.0
	v_mul_f32_e32 v37, v36, v35
	v_fma_f32 v38, -v34, v37, v36
	v_fmac_f32_e32 v37, v38, v35
	v_fma_f32 v34, -v34, v37, v36
	v_div_fmas_f32 v34, v34, v35, v37
	v_div_fixup_f32 v33, v34, v33, 1.0
	v_div_scale_f32 v34, s[12:13], v32, v32, 1.0
	v_rcp_f32_e32 v35, v34
	s_mov_b32 s12, 0xa964000
	v_fma_f32 v33, v9, v33, v8
	v_max_f32_e32 v33, 0xda24260, v33
	v_fma_f32 v36, -v34, v35, 1.0
	v_fmac_f32_e32 v35, v36, v35
	v_div_scale_f32 v36, vcc, 1.0, v32, 1.0
	v_mul_f32_e32 v37, v36, v35
	v_fma_f32 v38, -v34, v37, v36
	v_fmac_f32_e32 v37, v38, v35
	v_fma_f32 v34, -v34, v37, v36
	v_div_fmas_f32 v34, v34, v35, v37
	v_div_fixup_f32 v32, v34, v32, 1.0
	v_add_co_u32_e32 v34, vcc, s12, v0
	v_log_f32_e32 v33, v33
	s_nop 0
	v_addc_co_u32_e32 v35, vcc, 0, v1, vcc
	v_mov_b32_e32 v34, v93
	v_add_f32_e32 v33, v31, v33
	v_mul_f32_e32 v32, v9, v32
	s_waitcnt vmcnt(0)
	v_lshlrev_b32_e32 v34, 16, v34
	v_mul_f32_e32 v35, 0xbfb8aa3b, v34
	v_exp_f32_e32 v35, v35
	v_mul_f32_e32 v34, 0x3fb8aa3b, v34
	v_exp_f32_e32 v34, v34
	v_add_f32_e32 v35, 1.0, v35
	v_div_scale_f32 v36, s[12:13], v35, v35, 1.0
	v_rcp_f32_e32 v37, v36
	v_add_f32_e32 v34, 1.0, v34
	v_fma_f32 v38, -v36, v37, 1.0
	v_fmac_f32_e32 v37, v38, v37
	v_div_scale_f32 v38, vcc, 1.0, v35, 1.0
	v_mul_f32_e32 v39, v38, v37
	v_fma_f32 v40, -v36, v39, v38
	v_fmac_f32_e32 v39, v40, v37
	v_fma_f32 v36, -v36, v39, v38
	v_div_fmas_f32 v36, v36, v37, v39
	v_div_fixup_f32 v35, v36, v35, 1.0
	v_div_scale_f32 v36, s[12:13], v34, v34, 1.0
	v_rcp_f32_e32 v37, v36
	s_mov_b32 s12, 0xa965000
	v_fma_f32 v35, v9, v35, v8
	v_max_f32_e32 v35, 0xda24260, v35
	v_fma_f32 v38, -v36, v37, 1.0
	v_fmac_f32_e32 v37, v38, v37
	v_div_scale_f32 v38, vcc, 1.0, v34, 1.0
	v_mul_f32_e32 v39, v38, v37
	v_fma_f32 v40, -v36, v39, v38
	v_fmac_f32_e32 v39, v40, v37
	v_fma_f32 v36, -v36, v39, v38
	v_div_fmas_f32 v36, v36, v37, v39
	v_div_fixup_f32 v34, v36, v34, 1.0
	v_add_co_u32_e32 v36, vcc, s12, v0
	v_log_f32_e32 v35, v35
	s_nop 0
	v_addc_co_u32_e32 v37, vcc, 0, v1, vcc
	v_mov_b32_e32 v36, v94
	v_add_f32_e32 v35, v33, v35
	v_mul_f32_e32 v34, v9, v34
	s_waitcnt vmcnt(0)
	v_lshlrev_b32_e32 v36, 16, v36
	v_mul_f32_e32 v37, 0xbfb8aa3b, v36
	v_exp_f32_e32 v37, v37
	v_mul_f32_e32 v36, 0x3fb8aa3b, v36
	v_exp_f32_e32 v36, v36
	v_add_f32_e32 v37, 1.0, v37
	v_div_scale_f32 v38, s[12:13], v37, v37, 1.0
	v_rcp_f32_e32 v39, v38
	v_add_f32_e32 v36, 1.0, v36
	v_fma_f32 v40, -v38, v39, 1.0
	v_fmac_f32_e32 v39, v40, v39
	v_div_scale_f32 v40, vcc, 1.0, v37, 1.0
	v_mul_f32_e32 v41, v40, v39
	v_fma_f32 v42, -v38, v41, v40
	v_fmac_f32_e32 v41, v42, v39
	v_fma_f32 v38, -v38, v41, v40
	v_div_fmas_f32 v38, v38, v39, v41
	v_div_fixup_f32 v37, v38, v37, 1.0
	v_div_scale_f32 v38, s[12:13], v36, v36, 1.0
	v_rcp_f32_e32 v39, v38
	s_mov_b32 s12, 0xa967000
	v_fma_f32 v37, v9, v37, v8
	v_max_f32_e32 v37, 0xda24260, v37
	v_fma_f32 v40, -v38, v39, 1.0
	v_fmac_f32_e32 v39, v40, v39
	v_div_scale_f32 v40, vcc, 1.0, v36, 1.0
	v_mul_f32_e32 v41, v40, v39
	v_fma_f32 v42, -v38, v41, v40
	v_fmac_f32_e32 v41, v42, v39
	v_fma_f32 v38, -v38, v41, v40
	v_div_fmas_f32 v38, v38, v39, v41
	v_add_co_u32_e32 v0, vcc, s12, v0
	v_div_fixup_f32 v36, v38, v36, 1.0
	s_nop 0
	v_addc_co_u32_e32 v1, vcc, 0, v1, vcc
	v_mov_b32_e32 v0, v95
	v_log_f32_e32 v37, v37
	v_mul_f32_e32 v36, v9, v36
	v_add_f32_e32 v37, v35, v37
	s_waitcnt vmcnt(0)
	v_lshlrev_b32_e32 v0, 16, v0
	v_mul_f32_e32 v1, 0xbfb8aa3b, v0
	v_exp_f32_e32 v1, v1
	v_mul_f32_e32 v0, 0x3fb8aa3b, v0
	v_exp_f32_e32 v0, v0
	v_add_f32_e32 v1, 1.0, v1
	v_div_scale_f32 v38, s[12:13], v1, v1, 1.0
	v_rcp_f32_e32 v39, v38
	v_add_f32_e32 v0, 1.0, v0
	v_fma_f32 v40, -v38, v39, 1.0
	v_fmac_f32_e32 v39, v40, v39
	v_div_scale_f32 v40, vcc, 1.0, v1, 1.0
	v_mul_f32_e32 v41, v40, v39
	v_fma_f32 v42, -v38, v41, v40
	v_fmac_f32_e32 v41, v42, v39
	v_fma_f32 v38, -v38, v41, v40
	v_div_fmas_f32 v38, v38, v39, v41
	v_div_fixup_f32 v1, v38, v1, 1.0
	v_div_scale_f32 v38, s[12:13], v0, v0, 1.0
	v_rcp_f32_e32 v39, v38
	v_fmac_f32_e32 v8, v9, v1
	v_max_f32_e32 v1, 0xda24260, v8
	v_log_f32_e32 v1, v1
	v_fma_f32 v40, -v38, v39, 1.0
	v_fmac_f32_e32 v39, v40, v39
	v_div_scale_f32 v40, vcc, 1.0, v0, 1.0
	v_mul_f32_e32 v41, v40, v39
	v_fma_f32 v42, -v38, v41, v40
	v_fmac_f32_e32 v41, v42, v39
	v_fma_f32 v38, -v38, v41, v40
	v_div_fmas_f32 v38, v38, v39, v41
	v_div_fixup_f32 v0, v38, v0, 1.0
	v_add_f32_e32 v38, v37, v1
	v_mul_f32_e32 v39, v9, v0
	v_lshlrev_b32_e32 v0, 2, v3
	v_lshlrev_b32_e32 v40, 2, v2
	ds_write_b32 v0, v38
	s_waitcnt lgkmcnt(0)
	s_barrier
	ds_read2st64_b32 v[0:1], v40 offset1:1
	v_cmp_lt_i32_e32 vcc, 0, v4
	s_waitcnt lgkmcnt(0)
	v_add_f32_e32 v0, 0, v0
	v_cndmask_b32_e32 v8, 0, v0, vcc
	v_add_f32_e32 v9, v0, v1
	v_cmp_lt_i32_e32 vcc, 1, v4
	v_add_f32_e32 v0, v1, v8
	s_nop 0
	v_cndmask_b32_e32 v8, v8, v0, vcc
	ds_read2st64_b32 v[0:1], v40 offset0:2 offset1:3
	v_cmp_lt_i32_e32 vcc, 2, v4
	s_waitcnt lgkmcnt(0)
	v_add_f32_e32 v9, v9, v0
	v_add_f32_e32 v0, v0, v8
	v_cndmask_b32_e32 v8, v8, v0, vcc
	v_add_f32_e32 v0, v9, v1
	v_cmp_lt_i32_e32 vcc, 3, v4
	v_add_f32_e32 v1, v1, v8
	s_nop 0
	v_cndmask_b32_e32 v1, v8, v1, vcc
	v_add_f32_e32 v7, v7, v1
	v_sub_f32_e32 v7, v0, v7
	v_exp_f32_e32 v7, v7
	v_add_f32_e32 v8, v15, v1
	v_sub_f32_e32 v8, v0, v8
	v_exp_f32_e32 v8, v8
	v_mul_f32_e32 v6, v6, v7
	v_add_f32_e32 v7, v11, v1
	v_sub_f32_e32 v7, v0, v7
	v_exp_f32_e32 v7, v7
	v_mul_f32_e32 v8, v14, v8
	v_add_f32_e32 v9, v19, v1
	v_sub_f32_e32 v9, v0, v9
	v_mul_f32_e32 v7, v10, v7
	v_cvt_pk_bf16_f32 v6, v6, v7
	v_add_f32_e32 v7, v13, v1
	v_sub_f32_e32 v7, v0, v7
	v_exp_f32_e32 v7, v7
	v_exp_f32_e32 v9, v9
	v_add_f32_e32 v10, v23, v1
	v_sub_f32_e32 v10, v0, v10
	v_mul_f32_e32 v7, v12, v7
	v_cvt_pk_bf16_f32 v7, v7, v8
	v_add_f32_e32 v8, v17, v1
	v_sub_f32_e32 v8, v0, v8
	v_exp_f32_e32 v8, v8
	v_mul_f32_e32 v9, v18, v9
	v_exp_f32_e32 v10, v10
	v_add_f32_e32 v11, v27, v1
	v_mul_f32_e32 v8, v16, v8
	v_cvt_pk_bf16_f32 v8, v8, v9
	v_add_f32_e32 v9, v21, v1
	v_sub_f32_e32 v9, v0, v9
	v_exp_f32_e32 v9, v9
	v_mul_f32_e32 v10, v22, v10
	v_sub_f32_e32 v11, v0, v11
	v_exp_f32_e32 v11, v11
	v_mul_f32_e32 v9, v20, v9
	v_cvt_pk_bf16_f32 v9, v9, v10
	v_add_f32_e32 v10, v25, v1
	v_sub_f32_e32 v10, v0, v10
	v_exp_f32_e32 v10, v10
	v_mul_f32_e32 v11, v26, v11
	v_add_f32_e32 v12, v31, v1
	v_sub_f32_e32 v12, v0, v12
	v_mul_f32_e32 v10, v24, v10
	v_cvt_pk_bf16_f32 v10, v10, v11
	v_add_f32_e32 v11, v29, v1
	v_sub_f32_e32 v11, v0, v11
	v_exp_f32_e32 v11, v11
	v_exp_f32_e32 v12, v12
	v_add_f32_e32 v13, v35, v1
	v_sub_f32_e32 v13, v0, v13
	v_mul_f32_e32 v11, v28, v11
	v_mul_f32_e32 v12, v30, v12
	v_cvt_pk_bf16_f32 v11, v11, v12
	v_add_f32_e32 v12, v33, v1
	v_sub_f32_e32 v12, v0, v12
	v_exp_f32_e32 v12, v12
	v_exp_f32_e32 v13, v13
	v_lshlrev_b32_e32 v14, 5, v4
	v_cmp_gt_u32_e32 vcc, 64, v3
	v_mul_f32_e32 v12, v32, v12
	v_mul_f32_e32 v13, v34, v13
	v_cvt_pk_bf16_f32 v12, v12, v13
	v_add_f32_e32 v13, v37, v1
	v_add_f32_e32 v1, v38, v1
	v_sub_f32_e32 v13, v0, v13
	v_sub_f32_e32 v1, v0, v1
	v_exp_f32_e32 v13, v13
	v_exp_f32_e32 v1, v1
	v_mul_f32_e32 v13, v36, v13
	v_mul_f32_e32 v1, v39, v1
	v_cvt_pk_bf16_f32 v13, v13, v1
	v_mul_u32_u24_e32 v1, 0x8c, v2
	v_add3_u32 v1, v40, v1, v14
	ds_write_b128 v1, v[6:9] offset:1024
	ds_write_b128 v1, v[10:13] offset:1040
	s_and_saveexec_b64 s[12:13], vcc
	s_cbranch_execz .LBB0_266
	v_exp_f32_e32 v6, v0
	v_add_u32_e32 v152, s20, v3
	v_lshl_add_u64 v[0:1], v[152:153], 2, s[2:3]
	global_store_dword v[0:1], v6, off
	s_branch .LBB0_266

.Lgm2_loop:
	v_add_u32_e32 v248, s30, v155
	v_add_u32_e32 v249, s30, v160
	v_mfma_f32_16x16x32_bf16 v[128:131], v[212:215], v[186:189], v[128:131]
	ds_read_b128 v[0:3], v248
	v_mfma_f32_16x16x32_bf16 v[68:71], v[212:215], v[190:193], v[68:71]
	ds_read_b128 v[16:19], v249 offset:8192
	v_mfma_f32_16x16x32_bf16 v[108:111], v[212:215], v[194:197], v[108:111]
	ds_read_b128 v[4:7], v248 offset:1024
	v_mfma_f32_16x16x32_bf16 v[132:135], v[212:215], v[208:211], v[132:135]
	ds_read_b128 v[20:23], v249 offset:9216
	v_mfma_f32_16x16x32_bf16 v[120:123], v[216:219], v[186:189], v[120:123]
	ds_read_b128 v[8:11], v248 offset:2048
	v_mfma_f32_16x16x32_bf16 v[64:67], v[216:219], v[190:193], v[64:67]
	ds_read_b128 v[162:165], v249 offset:10240
	v_mfma_f32_16x16x32_bf16 v[112:115], v[216:219], v[194:197], v[112:115]
	ds_read_b128 v[12:15], v248 offset:3072
	v_mfma_f32_16x16x32_bf16 v[136:139], v[216:219], v[208:211], v[136:139]
	ds_read_b128 v[166:169], v249 offset:11264
	v_mfma_f32_16x16x32_bf16 v[104:107], v[220:223], v[186:189], v[104:107]
	ds_read_b128 v[170:173], v249 offset:12288
	v_mfma_f32_16x16x32_bf16 v[56:59], v[220:223], v[190:193], v[56:59]
	ds_read_b128 v[174:177], v249 offset:13312
	v_mfma_f32_16x16x32_bf16 v[116:119], v[220:223], v[194:197], v[116:119]
	ds_read_b128 v[178:181], v249 offset:14336
	v_mfma_f32_16x16x32_bf16 v[140:143], v[220:223], v[208:211], v[140:143]
	ds_read_b128 v[182:185], v249 offset:15360
	s_add_u32 m0, s25, s24
	v_mfma_f32_16x16x32_bf16 v[100:103], v[224:227], v[186:189], v[100:103]
	global_load_lds_dwordx4 v244, s[26:27]
	v_mfma_f32_16x16x32_bf16 v[52:55], v[224:227], v[190:193], v[52:55]
	v_mfma_f32_16x16x32_bf16 v[124:127], v[224:227], v[194:197], v[124:127]
	s_add_u32 m0, m0, 0x1000
	v_mfma_f32_16x16x32_bf16 v[144:147], v[224:227], v[208:211], v[144:147]
	global_load_lds_dwordx4 v245, s[26:27]
	v_mfma_f32_16x16x32_bf16 v[60:63], v[228:231], v[186:189], v[60:63]
	v_mfma_f32_16x16x32_bf16 v[36:39], v[228:231], v[190:193], v[36:39]
	s_add_u32 m0, m0, 0x1000
	v_mfma_f32_16x16x32_bf16 v[80:83], v[228:231], v[194:197], v[80:83]
	global_load_lds_dwordx4 v244, s[28:29]
	v_mfma_f32_16x16x32_bf16 v[92:95], v[228:231], v[208:211], v[92:95]
	v_mfma_f32_16x16x32_bf16 v[48:51], v[232:235], v[186:189], v[48:51]
	s_add_u32 m0, m0, 0x1000
	v_mfma_f32_16x16x32_bf16 v[32:35], v[232:235], v[190:193], v[32:35]
	global_load_lds_dwordx4 v245, s[28:29]
	v_mfma_f32_16x16x32_bf16 v[84:87], v[232:235], v[194:197], v[84:87]
	v_mfma_f32_16x16x32_bf16 v[88:91], v[232:235], v[208:211], v[88:91]
	s_add_u32 m0, m0, 0x1000
	v_mfma_f32_16x16x32_bf16 v[44:47], v[236:239], v[186:189], v[44:47]
	global_load_lds_dwordx4 v246, s[28:29]
	v_mfma_f32_16x16x32_bf16 v[28:31], v[236:239], v[190:193], v[28:31]
	v_mfma_f32_16x16x32_bf16 v[96:99], v[236:239], v[194:197], v[96:99]
	s_add_u32 m0, m0, 0x1000
	v_mfma_f32_16x16x32_bf16 v[76:79], v[236:239], v[208:211], v[76:79]
	global_load_lds_dwordx4 v247, s[28:29]
	v_mfma_f32_16x16x32_bf16 v[40:43], v[240:243], v[186:189], v[40:43]
	v_mfma_f32_16x16x32_bf16 v[24:27], v[240:243], v[190:193], v[24:27]
	v_mfma_f32_16x16x32_bf16 v[72:75], v[240:243], v[194:197], v[72:75]
	v_mfma_f32_16x16x32_bf16 v[148:151], v[240:243], v[208:211], v[148:151]
	s_add_u32 s26, s26, 64
	s_addc_u32 s27, s27, 0
	s_add_u32 s28, s28, 64
	s_addc_u32 s29, s29, 0
	s_add_u32 s25, s25, 24576
	s_cmp_eq_u32 s25, 73728
	s_cselect_b32 s25, 0, s25
	s_add_u32 s30, s30, 24576
	s_cmp_eq_u32 s30, 73728
	s_cselect_b32 s30, 0, s30
	s_waitcnt vmcnt(6)
	s_waitcnt lgkmcnt(0)
	s_barrier
	v_add_u32_e32 v248, s30, v155
	v_add_u32_e32 v249, s30, v160
	v_mfma_f32_16x16x32_bf16 v[128:131], v[16:19], v[0:3], v[128:131]
	ds_read_b128 v[186:189], v248
	v_mfma_f32_16x16x32_bf16 v[68:71], v[16:19], v[4:7], v[68:71]
	ds_read_b128 v[212:215], v249 offset:8192
	v_mfma_f32_16x16x32_bf16 v[108:111], v[16:19], v[8:11], v[108:111]
	ds_read_b128 v[190:193], v248 offset:1024
	v_mfma_f32_16x16x32_bf16 v[132:135], v[16:19], v[12:15], v[132:135]
	ds_read_b128 v[216:219], v249 offset:9216
	v_mfma_f32_16x16x32_bf16 v[120:123], v[20:23], v[0:3], v[120:123]
	ds_read_b128 v[194:197], v248 offset:2048
	v_mfma_f32_16x16x32_bf16 v[64:67], v[20:23], v[4:7], v[64:67]
	ds_read_b128 v[220:223], v249 offset:10240
	v_mfma_f32_16x16x32_bf16 v[112:115], v[20:23], v[8:11], v[112:115]
	ds_read_b128 v[208:211], v248 offset:3072
	v_mfma_f32_16x16x32_bf16 v[136:139], v[20:23], v[12:15], v[136:139]
	ds_read_b128 v[224:227], v249 offset:11264
	v_mfma_f32_16x16x32_bf16 v[104:107], v[162:165], v[0:3], v[104:107]
	ds_read_b128 v[228:231], v249 offset:12288
	v_mfma_f32_16x16x32_bf16 v[56:59], v[162:165], v[4:7], v[56:59]
	ds_read_b128 v[232:235], v249 offset:13312
	v_mfma_f32_16x16x32_bf16 v[116:119], v[162:165], v[8:11], v[116:119]
	ds_read_b128 v[236:239], v249 offset:14336
	v_mfma_f32_16x16x32_bf16 v[140:143], v[162:165], v[12:15], v[140:143]
	ds_read_b128 v[240:243], v249 offset:15360
	s_add_u32 m0, s25, s24
	v_mfma_f32_16x16x32_bf16 v[100:103], v[166:169], v[0:3], v[100:103]
	global_load_lds_dwordx4 v244, s[26:27]
	v_mfma_f32_16x16x32_bf16 v[52:55], v[166:169], v[4:7], v[52:55]
	v_mfma_f32_16x16x32_bf16 v[124:127], v[166:169], v[8:11], v[124:127]
	s_add_u32 m0, m0, 0x1000
	v_mfma_f32_16x16x32_bf16 v[144:147], v[166:169], v[12:15], v[144:147]
	global_load_lds_dwordx4 v245, s[26:27]
	v_mfma_f32_16x16x32_bf16 v[60:63], v[170:173], v[0:3], v[60:63]
	v_mfma_f32_16x16x32_bf16 v[36:39], v[170:173], v[4:7], v[36:39]
	s_add_u32 m0, m0, 0x1000
	v_mfma_f32_16x16x32_bf16 v[80:83], v[170:173], v[8:11], v[80:83]
	global_load_lds_dwordx4 v244, s[28:29]
	v_mfma_f32_16x16x32_bf16 v[92:95], v[170:173], v[12:15], v[92:95]
	v_mfma_f32_16x16x32_bf16 v[48:51], v[174:177], v[0:3], v[48:51]
	s_add_u32 m0, m0, 0x1000
	v_mfma_f32_16x16x32_bf16 v[32:35], v[174:177], v[4:7], v[32:35]
	global_load_lds_dwordx4 v245, s[28:29]
	v_mfma_f32_16x16x32_bf16 v[84:87], v[174:177], v[8:11], v[84:87]
	v_mfma_f32_16x16x32_bf16 v[88:91], v[174:177], v[12:15], v[88:91]
	s_add_u32 m0, m0, 0x1000
	v_mfma_f32_16x16x32_bf16 v[44:47], v[178:181], v[0:3], v[44:47]
	global_load_lds_dwordx4 v246, s[28:29]
	v_mfma_f32_16x16x32_bf16 v[28:31], v[178:181], v[4:7], v[28:31]
	v_mfma_f32_16x16x32_bf16 v[96:99], v[178:181], v[8:11], v[96:99]
	s_add_u32 m0, m0, 0x1000
	v_mfma_f32_16x16x32_bf16 v[76:79], v[178:181], v[12:15], v[76:79]
	global_load_lds_dwordx4 v247, s[28:29]
	v_mfma_f32_16x16x32_bf16 v[40:43], v[182:185], v[0:3], v[40:43]
	v_mfma_f32_16x16x32_bf16 v[24:27], v[182:185], v[4:7], v[24:27]
	v_mfma_f32_16x16x32_bf16 v[72:75], v[182:185], v[8:11], v[72:75]
	v_mfma_f32_16x16x32_bf16 v[148:151], v[182:185], v[12:15], v[148:151]
	s_add_u32 s26, s26, 64
	s_addc_u32 s27, s27, 0
	s_add_u32 s28, s28, 64
	s_addc_u32 s29, s29, 0
	s_add_u32 s25, s25, 24576
	s_cmp_eq_u32 s25, 73728
	s_cselect_b32 s25, 0, s25
	s_add_u32 s30, s30, 24576
	s_cmp_eq_u32 s30, 73728
	s_cselect_b32 s30, 0, s30
	s_waitcnt vmcnt(6)
	s_waitcnt lgkmcnt(0)
	s_barrier
	s_sub_u32 s31, s31, 1
	s_cmp_lg_u32 s31, 0
	s_cbranch_scc1 .Lgm2_loop
	v_add_u32_e32 v248, s30, v155
	v_add_u32_e32 v249, s30, v160
	v_mfma_f32_16x16x32_bf16 v[128:131], v[212:215], v[186:189], v[128:131]
	ds_read_b128 v[0:3], v248
	v_mfma_f32_16x16x32_bf16 v[68:71], v[212:215], v[190:193], v[68:71]
	ds_read_b128 v[16:19], v249 offset:8192
	v_mfma_f32_16x16x32_bf16 v[108:111], v[212:215], v[194:197], v[108:111]
	ds_read_b128 v[4:7], v248 offset:1024
	v_mfma_f32_16x16x32_bf16 v[132:135], v[212:215], v[208:211], v[132:135]
	ds_read_b128 v[20:23], v249 offset:9216
	v_mfma_f32_16x16x32_bf16 v[120:123], v[216:219], v[186:189], v[120:123]
	ds_read_b128 v[8:11], v248 offset:2048
	v_mfma_f32_16x16x32_bf16 v[64:67], v[216:219], v[190:193], v[64:67]
	ds_read_b128 v[162:165], v249 offset:10240
	v_mfma_f32_16x16x32_bf16 v[112:115], v[216:219], v[194:197], v[112:115]
	ds_read_b128 v[12:15], v248 offset:3072
	v_mfma_f32_16x16x32_bf16 v[136:139], v[216:219], v[208:211], v[136:139]
	ds_read_b128 v[166:169], v249 offset:11264
	v_mfma_f32_16x16x32_bf16 v[104:107], v[220:223], v[186:189], v[104:107]
	ds_read_b128 v[170:173], v249 offset:12288
	v_mfma_f32_16x16x32_bf16 v[56:59], v[220:223], v[190:193], v[56:59]
	ds_read_b128 v[174:177], v249 offset:13312
	v_mfma_f32_16x16x32_bf16 v[116:119], v[220:223], v[194:197], v[116:119]
	ds_read_b128 v[178:181], v249 offset:14336
	v_mfma_f32_16x16x32_bf16 v[140:143], v[220:223], v[208:211], v[140:143]
	ds_read_b128 v[182:185], v249 offset:15360
	s_add_u32 m0, s25, s24
	v_mfma_f32_16x16x32_bf16 v[100:103], v[224:227], v[186:189], v[100:103]
	global_load_lds_dwordx4 v244, s[26:27]
	v_mfma_f32_16x16x32_bf16 v[52:55], v[224:227], v[190:193], v[52:55]
	v_mfma_f32_16x16x32_bf16 v[124:127], v[224:227], v[194:197], v[124:127]
	s_add_u32 m0, m0, 0x1000
	v_mfma_f32_16x16x32_bf16 v[144:147], v[224:227], v[208:211], v[144:147]
	global_load_lds_dwordx4 v245, s[26:27]
	v_mfma_f32_16x16x32_bf16 v[60:63], v[228:231], v[186:189], v[60:63]
	v_mfma_f32_16x16x32_bf16 v[36:39], v[228:231], v[190:193], v[36:39]
	s_add_u32 m0, m0, 0x1000
	v_mfma_f32_16x16x32_bf16 v[80:83], v[228:231], v[194:197], v[80:83]
	global_load_lds_dwordx4 v244, s[28:29]
	v_mfma_f32_16x16x32_bf16 v[92:95], v[228:231], v[208:211], v[92:95]
	v_mfma_f32_16x16x32_bf16 v[48:51], v[232:235], v[186:189], v[48:51]
	s_add_u32 m0, m0, 0x1000
	v_mfma_f32_16x16x32_bf16 v[32:35], v[232:235], v[190:193], v[32:35]
	global_load_lds_dwordx4 v245, s[28:29]
	v_mfma_f32_16x16x32_bf16 v[84:87], v[232:235], v[194:197], v[84:87]
	v_mfma_f32_16x16x32_bf16 v[88:91], v[232:235], v[208:211], v[88:91]
	s_add_u32 m0, m0, 0x1000
	v_mfma_f32_16x16x32_bf16 v[44:47], v[236:239], v[186:189], v[44:47]
	global_load_lds_dwordx4 v246, s[28:29]
	v_mfma_f32_16x16x32_bf16 v[28:31], v[236:239], v[190:193], v[28:31]
	v_mfma_f32_16x16x32_bf16 v[96:99], v[236:239], v[194:197], v[96:99]
	s_add_u32 m0, m0, 0x1000
	v_mfma_f32_16x16x32_bf16 v[76:79], v[236:239], v[208:211], v[76:79]
	global_load_lds_dwordx4 v247, s[28:29]
	v_mfma_f32_16x16x32_bf16 v[40:43], v[240:243], v[186:189], v[40:43]
	v_mfma_f32_16x16x32_bf16 v[24:27], v[240:243], v[190:193], v[24:27]
	v_mfma_f32_16x16x32_bf16 v[72:75], v[240:243], v[194:197], v[72:75]
	v_mfma_f32_16x16x32_bf16 v[148:151], v[240:243], v[208:211], v[148:151]
	s_add_u32 s26, s26, 64
	s_addc_u32 s27, s27, 0
	s_add_u32 s28, s28, 64
	s_addc_u32 s29, s29, 0
	s_add_u32 s25, s25, 24576
	s_cmp_eq_u32 s25, 73728
	s_cselect_b32 s25, 0, s25
	s_add_u32 s30, s30, 24576
	s_cmp_eq_u32 s30, 73728
	s_cselect_b32 s30, 0, s30
	s_waitcnt vmcnt(6)
	s_waitcnt lgkmcnt(0)
	s_barrier
	v_add_u32_e32 v248, s30, v155
	v_add_u32_e32 v249, s30, v160
	v_mfma_f32_16x16x32_bf16 v[128:131], v[16:19], v[0:3], v[128:131]
	ds_read_b128 v[186:189], v248
	v_mfma_f32_16x16x32_bf16 v[68:71], v[16:19], v[4:7], v[68:71]
	ds_read_b128 v[212:215], v249 offset:8192
	v_mfma_f32_16x16x32_bf16 v[108:111], v[16:19], v[8:11], v[108:111]
	ds_read_b128 v[190:193], v248 offset:1024
	v_mfma_f32_16x16x32_bf16 v[132:135], v[16:19], v[12:15], v[132:135]
	ds_read_b128 v[216:219], v249 offset:9216
	v_mfma_f32_16x16x32_bf16 v[120:123], v[20:23], v[0:3], v[120:123]
	ds_read_b128 v[194:197], v248 offset:2048
	v_mfma_f32_16x16x32_bf16 v[64:67], v[20:23], v[4:7], v[64:67]
	ds_read_b128 v[220:223], v249 offset:10240
	v_mfma_f32_16x16x32_bf16 v[112:115], v[20:23], v[8:11], v[112:115]
	ds_read_b128 v[208:211], v248 offset:3072
	v_mfma_f32_16x16x32_bf16 v[136:139], v[20:23], v[12:15], v[136:139]
	ds_read_b128 v[224:227], v249 offset:11264
	v_mfma_f32_16x16x32_bf16 v[104:107], v[162:165], v[0:3], v[104:107]
	ds_read_b128 v[228:231], v249 offset:12288
	v_mfma_f32_16x16x32_bf16 v[56:59], v[162:165], v[4:7], v[56:59]
	ds_read_b128 v[232:235], v249 offset:13312
	v_mfma_f32_16x16x32_bf16 v[116:119], v[162:165], v[8:11], v[116:119]
	ds_read_b128 v[236:239], v249 offset:14336
	v_mfma_f32_16x16x32_bf16 v[140:143], v[162:165], v[12:15], v[140:143]
	ds_read_b128 v[240:243], v249 offset:15360
	v_mfma_f32_16x16x32_bf16 v[100:103], v[166:169], v[0:3], v[100:103]
	v_mfma_f32_16x16x32_bf16 v[52:55], v[166:169], v[4:7], v[52:55]
	v_mfma_f32_16x16x32_bf16 v[124:127], v[166:169], v[8:11], v[124:127]
	v_mfma_f32_16x16x32_bf16 v[144:147], v[166:169], v[12:15], v[144:147]
	v_mfma_f32_16x16x32_bf16 v[60:63], v[170:173], v[0:3], v[60:63]
	v_mfma_f32_16x16x32_bf16 v[36:39], v[170:173], v[4:7], v[36:39]
	v_mfma_f32_16x16x32_bf16 v[80:83], v[170:173], v[8:11], v[80:83]
	v_mfma_f32_16x16x32_bf16 v[92:95], v[170:173], v[12:15], v[92:95]
	v_mfma_f32_16x16x32_bf16 v[48:51], v[174:177], v[0:3], v[48:51]
	v_mfma_f32_16x16x32_bf16 v[32:35], v[174:177], v[4:7], v[32:35]
	v_mfma_f32_16x16x32_bf16 v[84:87], v[174:177], v[8:11], v[84:87]
	v_mfma_f32_16x16x32_bf16 v[88:91], v[174:177], v[12:15], v[88:91]
	v_mfma_f32_16x16x32_bf16 v[44:47], v[178:181], v[0:3], v[44:47]
	v_mfma_f32_16x16x32_bf16 v[28:31], v[178:181], v[4:7], v[28:31]
	v_mfma_f32_16x16x32_bf16 v[96:99], v[178:181], v[8:11], v[96:99]
	v_mfma_f32_16x16x32_bf16 v[76:79], v[178:181], v[12:15], v[76:79]
	v_mfma_f32_16x16x32_bf16 v[40:43], v[182:185], v[0:3], v[40:43]
	v_mfma_f32_16x16x32_bf16 v[24:27], v[182:185], v[4:7], v[24:27]
	v_mfma_f32_16x16x32_bf16 v[72:75], v[182:185], v[8:11], v[72:75]
	v_mfma_f32_16x16x32_bf16 v[148:151], v[182:185], v[12:15], v[148:151]
	s_add_u32 s30, s30, 24576
	s_cmp_eq_u32 s30, 73728
	s_cselect_b32 s30, 0, s30
	s_waitcnt vmcnt(0)
	s_waitcnt lgkmcnt(0)
	s_barrier
	v_add_u32_e32 v248, s30, v155
	v_add_u32_e32 v249, s30, v160
	v_mfma_f32_16x16x32_bf16 v[128:131], v[212:215], v[186:189], v[128:131]
	ds_read_b128 v[0:3], v248
	v_mfma_f32_16x16x32_bf16 v[68:71], v[212:215], v[190:193], v[68:71]
	ds_read_b128 v[16:19], v249 offset:8192
	v_mfma_f32_16x16x32_bf16 v[108:111], v[212:215], v[194:197], v[108:111]
	ds_read_b128 v[4:7], v248 offset:1024
	v_mfma_f32_16x16x32_bf16 v[132:135], v[212:215], v[208:211], v[132:135]
	ds_read_b128 v[20:23], v249 offset:9216
	v_mfma_f32_16x16x32_bf16 v[120:123], v[216:219], v[186:189], v[120:123]
	ds_read_b128 v[8:11], v248 offset:2048
	v_mfma_f32_16x16x32_bf16 v[64:67], v[216:219], v[190:193], v[64:67]
	ds_read_b128 v[162:165], v249 offset:10240
	v_mfma_f32_16x16x32_bf16 v[112:115], v[216:219], v[194:197], v[112:115]
	ds_read_b128 v[12:15], v248 offset:3072
	v_mfma_f32_16x16x32_bf16 v[136:139], v[216:219], v[208:211], v[136:139]
	ds_read_b128 v[166:169], v249 offset:11264
	v_mfma_f32_16x16x32_bf16 v[104:107], v[220:223], v[186:189], v[104:107]
	ds_read_b128 v[170:173], v249 offset:12288
	v_mfma_f32_16x16x32_bf16 v[56:59], v[220:223], v[190:193], v[56:59]
	ds_read_b128 v[174:177], v249 offset:13312
	v_mfma_f32_16x16x32_bf16 v[116:119], v[220:223], v[194:197], v[116:119]
	ds_read_b128 v[178:181], v249 offset:14336
	v_mfma_f32_16x16x32_bf16 v[140:143], v[220:223], v[208:211], v[140:143]
	ds_read_b128 v[182:185], v249 offset:15360
	v_mfma_f32_16x16x32_bf16 v[100:103], v[224:227], v[186:189], v[100:103]
	v_mfma_f32_16x16x32_bf16 v[52:55], v[224:227], v[190:193], v[52:55]
	v_mfma_f32_16x16x32_bf16 v[124:127], v[224:227], v[194:197], v[124:127]
	v_mfma_f32_16x16x32_bf16 v[144:147], v[224:227], v[208:211], v[144:147]
	v_mfma_f32_16x16x32_bf16 v[60:63], v[228:231], v[186:189], v[60:63]
	v_mfma_f32_16x16x32_bf16 v[36:39], v[228:231], v[190:193], v[36:39]
	v_mfma_f32_16x16x32_bf16 v[80:83], v[228:231], v[194:197], v[80:83]
	v_mfma_f32_16x16x32_bf16 v[92:95], v[228:231], v[208:211], v[92:95]
	v_mfma_f32_16x16x32_bf16 v[48:51], v[232:235], v[186:189], v[48:51]
	v_mfma_f32_16x16x32_bf16 v[32:35], v[232:235], v[190:193], v[32:35]
	v_mfma_f32_16x16x32_bf16 v[84:87], v[232:235], v[194:197], v[84:87]
	v_mfma_f32_16x16x32_bf16 v[88:91], v[232:235], v[208:211], v[88:91]
	v_mfma_f32_16x16x32_bf16 v[44:47], v[236:239], v[186:189], v[44:47]
	v_mfma_f32_16x16x32_bf16 v[28:31], v[236:239], v[190:193], v[28:31]
	v_mfma_f32_16x16x32_bf16 v[96:99], v[236:239], v[194:197], v[96:99]
	v_mfma_f32_16x16x32_bf16 v[76:79], v[236:239], v[208:211], v[76:79]
	v_mfma_f32_16x16x32_bf16 v[40:43], v[240:243], v[186:189], v[40:43]
	v_mfma_f32_16x16x32_bf16 v[24:27], v[240:243], v[190:193], v[24:27]
	v_mfma_f32_16x16x32_bf16 v[72:75], v[240:243], v[194:197], v[72:75]
	v_mfma_f32_16x16x32_bf16 v[148:151], v[240:243], v[208:211], v[148:151]
	s_add_u32 s30, s30, 24576
	s_cmp_eq_u32 s30, 73728
	s_cselect_b32 s30, 0, s30
	s_waitcnt lgkmcnt(0)
	s_barrier
	v_mfma_f32_16x16x32_bf16 v[128:131], v[16:19], v[0:3], v[128:131]
	v_mfma_f32_16x16x32_bf16 v[68:71], v[16:19], v[4:7], v[68:71]
	v_mfma_f32_16x16x32_bf16 v[108:111], v[16:19], v[8:11], v[108:111]
	v_mfma_f32_16x16x32_bf16 v[132:135], v[16:19], v[12:15], v[132:135]
	v_mfma_f32_16x16x32_bf16 v[120:123], v[20:23], v[0:3], v[120:123]
	v_mfma_f32_16x16x32_bf16 v[64:67], v[20:23], v[4:7], v[64:67]
	v_mfma_f32_16x16x32_bf16 v[112:115], v[20:23], v[8:11], v[112:115]
	v_mfma_f32_16x16x32_bf16 v[136:139], v[20:23], v[12:15], v[136:139]
	v_mfma_f32_16x16x32_bf16 v[104:107], v[162:165], v[0:3], v[104:107]
	v_mfma_f32_16x16x32_bf16 v[56:59], v[162:165], v[4:7], v[56:59]
	v_mfma_f32_16x16x32_bf16 v[116:119], v[162:165], v[8:11], v[116:119]
	v_mfma_f32_16x16x32_bf16 v[140:143], v[162:165], v[12:15], v[140:143]
	v_mfma_f32_16x16x32_bf16 v[100:103], v[166:169], v[0:3], v[100:103]
	v_mfma_f32_16x16x32_bf16 v[52:55], v[166:169], v[4:7], v[52:55]
	v_mfma_f32_16x16x32_bf16 v[124:127], v[166:169], v[8:11], v[124:127]
	v_mfma_f32_16x16x32_bf16 v[144:147], v[166:169], v[12:15], v[144:147]
	v_mfma_f32_16x16x32_bf16 v[60:63], v[170:173], v[0:3], v[60:63]
	v_mfma_f32_16x16x32_bf16 v[36:39], v[170:173], v[4:7], v[36:39]
	v_mfma_f32_16x16x32_bf16 v[80:83], v[170:173], v[8:11], v[80:83]
	v_mfma_f32_16x16x32_bf16 v[92:95], v[170:173], v[12:15], v[92:95]
	v_mfma_f32_16x16x32_bf16 v[48:51], v[174:177], v[0:3], v[48:51]
	v_mfma_f32_16x16x32_bf16 v[32:35], v[174:177], v[4:7], v[32:35]
	v_mfma_f32_16x16x32_bf16 v[84:87], v[174:177], v[8:11], v[84:87]
	v_mfma_f32_16x16x32_bf16 v[88:91], v[174:177], v[12:15], v[88:91]
	v_mfma_f32_16x16x32_bf16 v[44:47], v[178:181], v[0:3], v[44:47]
	v_mfma_f32_16x16x32_bf16 v[28:31], v[178:181], v[4:7], v[28:31]
	v_mfma_f32_16x16x32_bf16 v[96:99], v[178:181], v[8:11], v[96:99]
	v_mfma_f32_16x16x32_bf16 v[76:79], v[178:181], v[12:15], v[76:79]
	v_mfma_f32_16x16x32_bf16 v[40:43], v[182:185], v[0:3], v[40:43]
	v_mfma_f32_16x16x32_bf16 v[24:27], v[182:185], v[4:7], v[24:27]
	v_mfma_f32_16x16x32_bf16 v[72:75], v[182:185], v[8:11], v[72:75]
	v_mfma_f32_16x16x32_bf16 v[148:151], v[182:185], v[12:15], v[148:151]
	v_mov_b32 v250, v198
	s_nop 0
	v_and_b32_e32 v251, 15, v250
	v_bfe_u32 v156, v250, 4, 2
	v_bfe_u32 v157, v250, 6, 1
	v_bfe_u32 v158, v250, 7, 1
	v_lshl_add_u32 v158, v158, 6, s4
	v_add_u32_e32 v158, v158, v251
	v_lshl_add_u32 v157, v157, 7, s5
	v_lshl_add_u32 v159, v156, 2, v157
	v_lshlrev_b32_e32 v246, 2, v159
	v_lshl_add_u32 v244, v158, 12, v246
	v_lshlrev_b32_e32 v161, 1, v159
	v_lshl_add_u32 v245, v158, 11, v161
	v_and_b32_e32 v254, 1, v156
	v_mul_u32_u24_e32 v254, 24, v254
	v_add_u32_e32 v254, v254, v245
	v_lshrrev_b32_e32 v161, 6, v157
	v_lshlrev_b32_e32 v161, 2, v161
	v_lshl_add_u32 v247, v158, 6, v161
	v_xor_b32_e32 v248, 16, v200
	v_lshlrev_b32_e32 v248, 2, v248
	v_xor_b32_e32 v249, 32, v200
	v_lshlrev_b32_e32 v249, 2, v249
	s_mov_b32 s24, s78
	s_mov_b32 s25, s79
	s_mov_b32 s26, s78
	s_mov_b32 s27, s79
	s_mov_b32 s28, s96
	s_mov_b32 s29, s97
	s_mov_b32 s30, s94
	s_mov_b32 s31, s95
	s_cmp_lg_u64 s[8:9], 0
	s_cbranch_scc0 .Lgm2_noemit
	global_load_dwordx4 v[208:211], v246, s[10:11]
	global_load_dwordx4 v[212:215], v246, s[10:11] offset:64
	global_load_dwordx4 v[216:219], v246, s[10:11] offset:128
	global_load_dwordx4 v[220:223], v246, s[10:11] offset:192
	global_load_dwordx4 v[224:227], v246, s[10:11] offset:256
	global_load_dwordx4 v[228:231], v246, s[10:11] offset:320
	global_load_dwordx4 v[232:235], v246, s[10:11] offset:384
	global_load_dwordx4 v[236:239], v246, s[10:11] offset:448
	global_load_dwordx4 v[0:3], v244, s[24:25]
	global_load_dwordx4 v[4:7], v244, s[24:25] offset:64
	global_load_dwordx4 v[8:11], v244, s[24:25] offset:128
	global_load_dwordx4 v[12:15], v244, s[24:25] offset:192
	global_load_dwordx4 v[16:19], v244, s[24:25] offset:256
	global_load_dwordx4 v[20:23], v244, s[24:25] offset:320
	global_load_dwordx4 v[162:165], v244, s[24:25] offset:384
	global_load_dwordx4 v[166:169], v244, s[24:25] offset:448
	s_add_u32 s24, s24, 0x10000
	s_addc_u32 s25, s25, 0
	global_load_dwordx4 v[170:173], v244, s[24:25]
	global_load_dwordx4 v[174:177], v244, s[24:25] offset:64
	global_load_dwordx4 v[178:181], v244, s[24:25] offset:128
	global_load_dwordx4 v[182:185], v244, s[24:25] offset:192
	global_load_dwordx4 v[186:189], v244, s[24:25] offset:256
	global_load_dwordx4 v[190:193], v244, s[24:25] offset:320
	global_load_dwordx4 v[194:197], v244, s[24:25] offset:384
	global_load_dwordx4 v[240:243], v244, s[24:25] offset:448
	s_add_u32 s24, s24, 0x10000
	s_addc_u32 s25, s25, 0
	s_waitcnt vmcnt(12)
	v_add_f32_e32 v0, v128, v0
	v_add_f32_e32 v1, v129, v1
	v_add_f32_e32 v2, v130, v2
	v_add_f32_e32 v3, v131, v3
	global_store_dwordx4 v244, v[0:3], s[26:27]
	v_mul_f32_e32 v158, v0, v0
	v_mul_f32_e32 v159, v1, v1
	v_mul_f32_e32 v250, v2, v2
	v_mul_f32_e32 v251, v3, v3
	v_add_f32_e32 v158, v158, v159
	v_add_f32_e32 v250, v250, v251
	v_add_f32_e32 v161, v158, v250
	v_mul_f32_e32 v156, v0, v208
	v_mul_f32_e32 v157, v1, v209
	v_mul_f32_e32 v158, v2, v210
	v_mul_f32_e32 v159, v3, v211
	v_cvt_pk_bf16_f32 v156, v156, v157
	v_cvt_pk_bf16_f32 v157, v158, v159
	v_add_f32_e32 v4, v120, v4
	v_add_f32_e32 v5, v121, v5
	v_add_f32_e32 v6, v122, v6
	v_add_f32_e32 v7, v123, v7
	global_store_dwordx4 v244, v[4:7], s[26:27] offset:64
	v_mul_f32_e32 v158, v4, v4
	v_mul_f32_e32 v159, v5, v5
	v_mul_f32_e32 v250, v6, v6
	v_mul_f32_e32 v251, v7, v7
	v_add_f32_e32 v158, v158, v159
	v_add_f32_e32 v250, v250, v251
	v_add_f32_e32 v158, v158, v250
	v_add_f32_e32 v161, v161, v158
	v_mul_f32_e32 v158, v4, v212
	v_mul_f32_e32 v159, v5, v213
	v_mul_f32_e32 v250, v6, v214
	v_mul_f32_e32 v251, v7, v215
	v_cvt_pk_bf16_f32 v158, v158, v159
	v_cvt_pk_bf16_f32 v159, v250, v251
	s_nop 1
	v_permlane16_swap_b32_e32 v156, v158
	v_permlane16_swap_b32_e32 v157, v159
	global_store_dwordx4 v254, v[156:159], s[28:29]
	v_add_f32_e32 v8, v104, v8
	v_add_f32_e32 v9, v105, v9
	v_add_f32_e32 v10, v106, v10
	v_add_f32_e32 v11, v107, v11
	global_store_dwordx4 v244, v[8:11], s[26:27] offset:128
	v_mul_f32_e32 v158, v8, v8
	v_mul_f32_e32 v159, v9, v9
	v_mul_f32_e32 v250, v10, v10
	v_mul_f32_e32 v251, v11, v11
	v_add_f32_e32 v158, v158, v159
	v_add_f32_e32 v250, v250, v251
	v_add_f32_e32 v158, v158, v250
	v_add_f32_e32 v161, v161, v158
	v_mul_f32_e32 v156, v8, v216
	v_mul_f32_e32 v157, v9, v217
	v_mul_f32_e32 v158, v10, v218
	v_mul_f32_e32 v159, v11, v219
	v_cvt_pk_bf16_f32 v156, v156, v157
	v_cvt_pk_bf16_f32 v157, v158, v159
	v_add_f32_e32 v12, v100, v12
	v_add_f32_e32 v13, v101, v13
	v_add_f32_e32 v14, v102, v14
	v_add_f32_e32 v15, v103, v15
	global_store_dwordx4 v244, v[12:15], s[26:27] offset:192
	v_mul_f32_e32 v158, v12, v12
	v_mul_f32_e32 v159, v13, v13
	v_mul_f32_e32 v250, v14, v14
	v_mul_f32_e32 v251, v15, v15
	v_add_f32_e32 v158, v158, v159
	v_add_f32_e32 v250, v250, v251
	v_add_f32_e32 v158, v158, v250
	v_add_f32_e32 v161, v161, v158
	v_mul_f32_e32 v158, v12, v220
	v_mul_f32_e32 v159, v13, v221
	v_mul_f32_e32 v250, v14, v222
	v_mul_f32_e32 v251, v15, v223
	v_cvt_pk_bf16_f32 v158, v158, v159
	v_cvt_pk_bf16_f32 v159, v250, v251
	s_nop 1
	v_permlane16_swap_b32_e32 v156, v158
	v_permlane16_swap_b32_e32 v157, v159
	global_store_dwordx4 v254, v[156:159], s[28:29] offset:64
	ds_bpermute_b32 v158, v248, v161
	s_waitcnt lgkmcnt(0)
	v_add_f32_e32 v161, v161, v158
	ds_bpermute_b32 v158, v249, v161
	s_waitcnt lgkmcnt(0)
	v_add_f32_e32 v161, v161, v158
	global_store_dword v247, v161, s[30:31]
	global_load_dwordx4 v[0:3], v244, s[24:25]
	global_load_dwordx4 v[4:7], v244, s[24:25] offset:64
	global_load_dwordx4 v[8:11], v244, s[24:25] offset:128
	global_load_dwordx4 v[12:15], v244, s[24:25] offset:192
	s_waitcnt vmcnt(19)
	v_add_f32_e32 v16, v60, v16
	v_add_f32_e32 v17, v61, v17
	v_add_f32_e32 v18, v62, v18
	v_add_f32_e32 v19, v63, v19
	global_store_dwordx4 v244, v[16:19], s[26:27] offset:256
	v_mul_f32_e32 v158, v16, v16
	v_mul_f32_e32 v159, v17, v17
	v_mul_f32_e32 v250, v18, v18
	v_mul_f32_e32 v251, v19, v19
	v_add_f32_e32 v158, v158, v159
	v_add_f32_e32 v250, v250, v251
	v_add_f32_e32 v161, v158, v250
	v_mul_f32_e32 v156, v16, v224
	v_mul_f32_e32 v157, v17, v225
	v_mul_f32_e32 v158, v18, v226
	v_mul_f32_e32 v159, v19, v227
	v_cvt_pk_bf16_f32 v156, v156, v157
	v_cvt_pk_bf16_f32 v157, v158, v159
	v_add_f32_e32 v20, v48, v20
	v_add_f32_e32 v21, v49, v21
	v_add_f32_e32 v22, v50, v22
	v_add_f32_e32 v23, v51, v23
	global_store_dwordx4 v244, v[20:23], s[26:27] offset:320
	v_mul_f32_e32 v158, v20, v20
	v_mul_f32_e32 v159, v21, v21
	v_mul_f32_e32 v250, v22, v22
	v_mul_f32_e32 v251, v23, v23
	v_add_f32_e32 v158, v158, v159
	v_add_f32_e32 v250, v250, v251
	v_add_f32_e32 v158, v158, v250
	v_add_f32_e32 v161, v161, v158
	v_mul_f32_e32 v158, v20, v228
	v_mul_f32_e32 v159, v21, v229
	v_mul_f32_e32 v250, v22, v230
	v_mul_f32_e32 v251, v23, v231
	v_cvt_pk_bf16_f32 v158, v158, v159
	v_cvt_pk_bf16_f32 v159, v250, v251
	s_nop 1
	v_permlane16_swap_b32_e32 v156, v158
	v_permlane16_swap_b32_e32 v157, v159
	global_store_dwordx4 v254, v[156:159], s[28:29] offset:128
	v_add_f32_e32 v162, v44, v162
	v_add_f32_e32 v163, v45, v163
	v_add_f32_e32 v164, v46, v164
	v_add_f32_e32 v165, v47, v165
	global_store_dwordx4 v244, v[162:165], s[26:27] offset:384
	v_mul_f32_e32 v158, v162, v162
	v_mul_f32_e32 v159, v163, v163
	v_mul_f32_e32 v250, v164, v164
	v_mul_f32_e32 v251, v165, v165
	v_add_f32_e32 v158, v158, v159
	v_add_f32_e32 v250, v250, v251
	v_add_f32_e32 v158, v158, v250
	v_add_f32_e32 v161, v161, v158
	v_mul_f32_e32 v156, v162, v232
	v_mul_f32_e32 v157, v163, v233
	v_mul_f32_e32 v158, v164, v234
	v_mul_f32_e32 v159, v165, v235
	v_cvt_pk_bf16_f32 v156, v156, v157
	v_cvt_pk_bf16_f32 v157, v158, v159
	v_add_f32_e32 v166, v40, v166
	v_add_f32_e32 v167, v41, v167
	v_add_f32_e32 v168, v42, v168
	v_add_f32_e32 v169, v43, v169
	global_store_dwordx4 v244, v[166:169], s[26:27] offset:448
	v_mul_f32_e32 v158, v166, v166
	v_mul_f32_e32 v159, v167, v167
	v_mul_f32_e32 v250, v168, v168
	v_mul_f32_e32 v251, v169, v169
	v_add_f32_e32 v158, v158, v159
	v_add_f32_e32 v250, v250, v251
	v_add_f32_e32 v158, v158, v250
	v_add_f32_e32 v161, v161, v158
	v_mul_f32_e32 v158, v166, v236
	v_mul_f32_e32 v159, v167, v237
	v_mul_f32_e32 v250, v168, v238
	v_mul_f32_e32 v251, v169, v239
	v_cvt_pk_bf16_f32 v158, v158, v159
	v_cvt_pk_bf16_f32 v159, v250, v251
	s_nop 1
	v_permlane16_swap_b32_e32 v156, v158
	v_permlane16_swap_b32_e32 v157, v159
	global_store_dwordx4 v254, v[156:159], s[28:29] offset:192
	ds_bpermute_b32 v158, v248, v161
	s_waitcnt lgkmcnt(0)
	v_add_f32_e32 v161, v161, v158
	ds_bpermute_b32 v158, v249, v161
	s_waitcnt lgkmcnt(0)
	v_add_f32_e32 v161, v161, v158
	global_store_dword v247, v161, s[30:31] offset:4
	s_add_u32 s26, s26, 0x10000
	s_addc_u32 s27, s27, 0
	s_add_u32 s28, s28, 0x8000
	s_addc_u32 s29, s29, 0
	s_add_u32 s30, s30, 0x400
	s_addc_u32 s31, s31, 0
	global_load_dwordx4 v[16:19], v244, s[24:25] offset:256
	global_load_dwordx4 v[20:23], v244, s[24:25] offset:320
	global_load_dwordx4 v[162:165], v244, s[24:25] offset:384
	global_load_dwordx4 v[166:169], v244, s[24:25] offset:448
	s_add_u32 s24, s24, 0x10000
	s_addc_u32 s25, s25, 0
	s_waitcnt vmcnt(26)
	v_add_f32_e32 v170, v68, v170
	v_add_f32_e32 v171, v69, v171
	v_add_f32_e32 v172, v70, v172
	v_add_f32_e32 v173, v71, v173
	global_store_dwordx4 v244, v[170:173], s[26:27]
	v_mul_f32_e32 v158, v170, v170
	v_mul_f32_e32 v159, v171, v171
	v_mul_f32_e32 v250, v172, v172
	v_mul_f32_e32 v251, v173, v173
	v_add_f32_e32 v158, v158, v159
	v_add_f32_e32 v250, v250, v251
	v_add_f32_e32 v161, v158, v250
	v_mul_f32_e32 v156, v170, v208
	v_mul_f32_e32 v157, v171, v209
	v_mul_f32_e32 v158, v172, v210
	v_mul_f32_e32 v159, v173, v211
	v_cvt_pk_bf16_f32 v156, v156, v157
	v_cvt_pk_bf16_f32 v157, v158, v159
	v_add_f32_e32 v174, v64, v174
	v_add_f32_e32 v175, v65, v175
	v_add_f32_e32 v176, v66, v176
	v_add_f32_e32 v177, v67, v177
	global_store_dwordx4 v244, v[174:177], s[26:27] offset:64
	v_mul_f32_e32 v158, v174, v174
	v_mul_f32_e32 v159, v175, v175
	v_mul_f32_e32 v250, v176, v176
	v_mul_f32_e32 v251, v177, v177
	v_add_f32_e32 v158, v158, v159
	v_add_f32_e32 v250, v250, v251
	v_add_f32_e32 v158, v158, v250
	v_add_f32_e32 v161, v161, v158
	v_mul_f32_e32 v158, v174, v212
	v_mul_f32_e32 v159, v175, v213
	v_mul_f32_e32 v250, v176, v214
	v_mul_f32_e32 v251, v177, v215
	v_cvt_pk_bf16_f32 v158, v158, v159
	v_cvt_pk_bf16_f32 v159, v250, v251
	s_nop 1
	v_permlane16_swap_b32_e32 v156, v158
	v_permlane16_swap_b32_e32 v157, v159
	global_store_dwordx4 v254, v[156:159], s[28:29]
	v_add_f32_e32 v178, v56, v178
	v_add_f32_e32 v179, v57, v179
	v_add_f32_e32 v180, v58, v180
	v_add_f32_e32 v181, v59, v181
	global_store_dwordx4 v244, v[178:181], s[26:27] offset:128
	v_mul_f32_e32 v158, v178, v178
	v_mul_f32_e32 v159, v179, v179
	v_mul_f32_e32 v250, v180, v180
	v_mul_f32_e32 v251, v181, v181
	v_add_f32_e32 v158, v158, v159
	v_add_f32_e32 v250, v250, v251
	v_add_f32_e32 v158, v158, v250
	v_add_f32_e32 v161, v161, v158
	v_mul_f32_e32 v156, v178, v216
	v_mul_f32_e32 v157, v179, v217
	v_mul_f32_e32 v158, v180, v218
	v_mul_f32_e32 v159, v181, v219
	v_cvt_pk_bf16_f32 v156, v156, v157
	v_cvt_pk_bf16_f32 v157, v158, v159
	v_add_f32_e32 v182, v52, v182
	v_add_f32_e32 v183, v53, v183
	v_add_f32_e32 v184, v54, v184
	v_add_f32_e32 v185, v55, v185
	global_store_dwordx4 v244, v[182:185], s[26:27] offset:192
	v_mul_f32_e32 v158, v182, v182
	v_mul_f32_e32 v159, v183, v183
	v_mul_f32_e32 v250, v184, v184
	v_mul_f32_e32 v251, v185, v185
	v_add_f32_e32 v158, v158, v159
	v_add_f32_e32 v250, v250, v251
	v_add_f32_e32 v158, v158, v250
	v_add_f32_e32 v161, v161, v158
	v_mul_f32_e32 v158, v182, v220
	v_mul_f32_e32 v159, v183, v221
	v_mul_f32_e32 v250, v184, v222
	v_mul_f32_e32 v251, v185, v223
	v_cvt_pk_bf16_f32 v158, v158, v159
	v_cvt_pk_bf16_f32 v159, v250, v251
	s_nop 1
	v_permlane16_swap_b32_e32 v156, v158
	v_permlane16_swap_b32_e32 v157, v159
	global_store_dwordx4 v254, v[156:159], s[28:29] offset:64
	ds_bpermute_b32 v158, v248, v161
	s_waitcnt lgkmcnt(0)
	v_add_f32_e32 v161, v161, v158
	ds_bpermute_b32 v158, v249, v161
	s_waitcnt lgkmcnt(0)
	v_add_f32_e32 v161, v161, v158
	global_store_dword v247, v161, s[30:31]
	global_load_dwordx4 v[170:173], v244, s[24:25]
	global_load_dwordx4 v[174:177], v244, s[24:25] offset:64
	global_load_dwordx4 v[178:181], v244, s[24:25] offset:128
	global_load_dwordx4 v[182:185], v244, s[24:25] offset:192
	s_waitcnt vmcnt(33)
	v_add_f32_e32 v186, v36, v186
	v_add_f32_e32 v187, v37, v187
	v_add_f32_e32 v188, v38, v188
	v_add_f32_e32 v189, v39, v189
	global_store_dwordx4 v244, v[186:189], s[26:27] offset:256
	v_mul_f32_e32 v158, v186, v186
	v_mul_f32_e32 v159, v187, v187
	v_mul_f32_e32 v250, v188, v188
	v_mul_f32_e32 v251, v189, v189
	v_add_f32_e32 v158, v158, v159
	v_add_f32_e32 v250, v250, v251
	v_add_f32_e32 v161, v158, v250
	v_mul_f32_e32 v156, v186, v224
	v_mul_f32_e32 v157, v187, v225
	v_mul_f32_e32 v158, v188, v226
	v_mul_f32_e32 v159, v189, v227
	v_cvt_pk_bf16_f32 v156, v156, v157
	v_cvt_pk_bf16_f32 v157, v158, v159
	v_add_f32_e32 v190, v32, v190
	v_add_f32_e32 v191, v33, v191
	v_add_f32_e32 v192, v34, v192
	v_add_f32_e32 v193, v35, v193
	global_store_dwordx4 v244, v[190:193], s[26:27] offset:320
	v_mul_f32_e32 v158, v190, v190
	v_mul_f32_e32 v159, v191, v191
	v_mul_f32_e32 v250, v192, v192
	v_mul_f32_e32 v251, v193, v193
	v_add_f32_e32 v158, v158, v159
	v_add_f32_e32 v250, v250, v251
	v_add_f32_e32 v158, v158, v250
	v_add_f32_e32 v161, v161, v158
	v_mul_f32_e32 v158, v190, v228
	v_mul_f32_e32 v159, v191, v229
	v_mul_f32_e32 v250, v192, v230
	v_mul_f32_e32 v251, v193, v231
	v_cvt_pk_bf16_f32 v158, v158, v159
	v_cvt_pk_bf16_f32 v159, v250, v251
	s_nop 1
	v_permlane16_swap_b32_e32 v156, v158
	v_permlane16_swap_b32_e32 v157, v159
	global_store_dwordx4 v254, v[156:159], s[28:29] offset:128
	v_add_f32_e32 v194, v28, v194
	v_add_f32_e32 v195, v29, v195
	v_add_f32_e32 v196, v30, v196
	v_add_f32_e32 v197, v31, v197
	global_store_dwordx4 v244, v[194:197], s[26:27] offset:384
	v_mul_f32_e32 v158, v194, v194
	v_mul_f32_e32 v159, v195, v195
	v_mul_f32_e32 v250, v196, v196
	v_mul_f32_e32 v251, v197, v197
	v_add_f32_e32 v158, v158, v159
	v_add_f32_e32 v250, v250, v251
	v_add_f32_e32 v158, v158, v250
	v_add_f32_e32 v161, v161, v158
	v_mul_f32_e32 v156, v194, v232
	v_mul_f32_e32 v157, v195, v233
	v_mul_f32_e32 v158, v196, v234
	v_mul_f32_e32 v159, v197, v235
	v_cvt_pk_bf16_f32 v156, v156, v157
	v_cvt_pk_bf16_f32 v157, v158, v159
	v_add_f32_e32 v240, v24, v240
	v_add_f32_e32 v241, v25, v241
	v_add_f32_e32 v242, v26, v242
	v_add_f32_e32 v243, v27, v243
	global_store_dwordx4 v244, v[240:243], s[26:27] offset:448
	v_mul_f32_e32 v158, v240, v240
	v_mul_f32_e32 v159, v241, v241
	v_mul_f32_e32 v250, v242, v242
	v_mul_f32_e32 v251, v243, v243
	v_add_f32_e32 v158, v158, v159
	v_add_f32_e32 v250, v250, v251
	v_add_f32_e32 v158, v158, v250
	v_add_f32_e32 v161, v161, v158
	v_mul_f32_e32 v158, v240, v236
	v_mul_f32_e32 v159, v241, v237
	v_mul_f32_e32 v250, v242, v238
	v_mul_f32_e32 v251, v243, v239
	v_cvt_pk_bf16_f32 v158, v158, v159
	v_cvt_pk_bf16_f32 v159, v250, v251
	s_nop 1
	v_permlane16_swap_b32_e32 v156, v158
	v_permlane16_swap_b32_e32 v157, v159
	global_store_dwordx4 v254, v[156:159], s[28:29] offset:192
	ds_bpermute_b32 v158, v248, v161
	s_waitcnt lgkmcnt(0)
	v_add_f32_e32 v161, v161, v158
	ds_bpermute_b32 v158, v249, v161
	s_waitcnt lgkmcnt(0)
	v_add_f32_e32 v161, v161, v158
	global_store_dword v247, v161, s[30:31] offset:4
	s_add_u32 s26, s26, 0x10000
	s_addc_u32 s27, s27, 0
	s_add_u32 s28, s28, 0x8000
	s_addc_u32 s29, s29, 0
	s_add_u32 s30, s30, 0x400
	s_addc_u32 s31, s31, 0
	global_load_dwordx4 v[186:189], v244, s[24:25] offset:256
	global_load_dwordx4 v[190:193], v244, s[24:25] offset:320
	global_load_dwordx4 v[194:197], v244, s[24:25] offset:384
	global_load_dwordx4 v[240:243], v244, s[24:25] offset:448
	s_add_u32 s24, s24, 0x10000
	s_addc_u32 s25, s25, 0
	s_waitcnt vmcnt(33)
	v_add_f32_e32 v0, v108, v0
	v_add_f32_e32 v1, v109, v1
	v_add_f32_e32 v2, v110, v2
	v_add_f32_e32 v3, v111, v3
	global_store_dwordx4 v244, v[0:3], s[26:27]
	v_mul_f32_e32 v158, v0, v0
	v_mul_f32_e32 v159, v1, v1
	v_mul_f32_e32 v250, v2, v2
	v_mul_f32_e32 v251, v3, v3
	v_add_f32_e32 v158, v158, v159
	v_add_f32_e32 v250, v250, v251
	v_add_f32_e32 v161, v158, v250
	v_mul_f32_e32 v156, v0, v208
	v_mul_f32_e32 v157, v1, v209
	v_mul_f32_e32 v158, v2, v210
	v_mul_f32_e32 v159, v3, v211
	v_cvt_pk_bf16_f32 v156, v156, v157
	v_cvt_pk_bf16_f32 v157, v158, v159
	v_add_f32_e32 v4, v112, v4
	v_add_f32_e32 v5, v113, v5
	v_add_f32_e32 v6, v114, v6
	v_add_f32_e32 v7, v115, v7
	global_store_dwordx4 v244, v[4:7], s[26:27] offset:64
	v_mul_f32_e32 v158, v4, v4
	v_mul_f32_e32 v159, v5, v5
	v_mul_f32_e32 v250, v6, v6
	v_mul_f32_e32 v251, v7, v7
	v_add_f32_e32 v158, v158, v159
	v_add_f32_e32 v250, v250, v251
	v_add_f32_e32 v158, v158, v250
	v_add_f32_e32 v161, v161, v158
	v_mul_f32_e32 v158, v4, v212
	v_mul_f32_e32 v159, v5, v213
	v_mul_f32_e32 v250, v6, v214
	v_mul_f32_e32 v251, v7, v215
	v_cvt_pk_bf16_f32 v158, v158, v159
	v_cvt_pk_bf16_f32 v159, v250, v251
	s_nop 1
	v_permlane16_swap_b32_e32 v156, v158
	v_permlane16_swap_b32_e32 v157, v159
	global_store_dwordx4 v254, v[156:159], s[28:29]
	v_add_f32_e32 v8, v116, v8
	v_add_f32_e32 v9, v117, v9
	v_add_f32_e32 v10, v118, v10
	v_add_f32_e32 v11, v119, v11
	global_store_dwordx4 v244, v[8:11], s[26:27] offset:128
	v_mul_f32_e32 v158, v8, v8
	v_mul_f32_e32 v159, v9, v9
	v_mul_f32_e32 v250, v10, v10
	v_mul_f32_e32 v251, v11, v11
	v_add_f32_e32 v158, v158, v159
	v_add_f32_e32 v250, v250, v251
	v_add_f32_e32 v158, v158, v250
	v_add_f32_e32 v161, v161, v158
	v_mul_f32_e32 v156, v8, v216
	v_mul_f32_e32 v157, v9, v217
	v_mul_f32_e32 v158, v10, v218
	v_mul_f32_e32 v159, v11, v219
	v_cvt_pk_bf16_f32 v156, v156, v157
	v_cvt_pk_bf16_f32 v157, v158, v159
	v_add_f32_e32 v12, v124, v12
	v_add_f32_e32 v13, v125, v13
	v_add_f32_e32 v14, v126, v14
	v_add_f32_e32 v15, v127, v15
	global_store_dwordx4 v244, v[12:15], s[26:27] offset:192
	v_mul_f32_e32 v158, v12, v12
	v_mul_f32_e32 v159, v13, v13
	v_mul_f32_e32 v250, v14, v14
	v_mul_f32_e32 v251, v15, v15
	v_add_f32_e32 v158, v158, v159
	v_add_f32_e32 v250, v250, v251
	v_add_f32_e32 v158, v158, v250
	v_add_f32_e32 v161, v161, v158
	v_mul_f32_e32 v158, v12, v220
	v_mul_f32_e32 v159, v13, v221
	v_mul_f32_e32 v250, v14, v222
	v_mul_f32_e32 v251, v15, v223
	v_cvt_pk_bf16_f32 v158, v158, v159
	v_cvt_pk_bf16_f32 v159, v250, v251
	s_nop 1
	v_permlane16_swap_b32_e32 v156, v158
	v_permlane16_swap_b32_e32 v157, v159
	global_store_dwordx4 v254, v[156:159], s[28:29] offset:64
	ds_bpermute_b32 v158, v248, v161
	s_waitcnt lgkmcnt(0)
	v_add_f32_e32 v161, v161, v158
	ds_bpermute_b32 v158, v249, v161
	s_waitcnt lgkmcnt(0)
	v_add_f32_e32 v161, v161, v158
	global_store_dword v247, v161, s[30:31]
	s_waitcnt vmcnt(29)
	v_add_f32_e32 v16, v80, v16
	v_add_f32_e32 v17, v81, v17
	v_add_f32_e32 v18, v82, v18
	v_add_f32_e32 v19, v83, v19
	global_store_dwordx4 v244, v[16:19], s[26:27] offset:256
	v_mul_f32_e32 v158, v16, v16
	v_mul_f32_e32 v159, v17, v17
	v_mul_f32_e32 v250, v18, v18
	v_mul_f32_e32 v251, v19, v19
	v_add_f32_e32 v158, v158, v159
	v_add_f32_e32 v250, v250, v251
	v_add_f32_e32 v161, v158, v250
	v_mul_f32_e32 v156, v16, v224
	v_mul_f32_e32 v157, v17, v225
	v_mul_f32_e32 v158, v18, v226
	v_mul_f32_e32 v159, v19, v227
	v_cvt_pk_bf16_f32 v156, v156, v157
	v_cvt_pk_bf16_f32 v157, v158, v159
	v_add_f32_e32 v20, v84, v20
	v_add_f32_e32 v21, v85, v21
	v_add_f32_e32 v22, v86, v22
	v_add_f32_e32 v23, v87, v23
	global_store_dwordx4 v244, v[20:23], s[26:27] offset:320
	v_mul_f32_e32 v158, v20, v20
	v_mul_f32_e32 v159, v21, v21
	v_mul_f32_e32 v250, v22, v22
	v_mul_f32_e32 v251, v23, v23
	v_add_f32_e32 v158, v158, v159
	v_add_f32_e32 v250, v250, v251
	v_add_f32_e32 v158, v158, v250
	v_add_f32_e32 v161, v161, v158
	v_mul_f32_e32 v158, v20, v228
	v_mul_f32_e32 v159, v21, v229
	v_mul_f32_e32 v250, v22, v230
	v_mul_f32_e32 v251, v23, v231
	v_cvt_pk_bf16_f32 v158, v158, v159
	v_cvt_pk_bf16_f32 v159, v250, v251
	s_nop 1
	v_permlane16_swap_b32_e32 v156, v158
	v_permlane16_swap_b32_e32 v157, v159
	global_store_dwordx4 v254, v[156:159], s[28:29] offset:128
	v_add_f32_e32 v162, v96, v162
	v_add_f32_e32 v163, v97, v163
	v_add_f32_e32 v164, v98, v164
	v_add_f32_e32 v165, v99, v165
	global_store_dwordx4 v244, v[162:165], s[26:27] offset:384
	v_mul_f32_e32 v158, v162, v162
	v_mul_f32_e32 v159, v163, v163
	v_mul_f32_e32 v250, v164, v164
	v_mul_f32_e32 v251, v165, v165
	v_add_f32_e32 v158, v158, v159
	v_add_f32_e32 v250, v250, v251
	v_add_f32_e32 v158, v158, v250
	v_add_f32_e32 v161, v161, v158
	v_mul_f32_e32 v156, v162, v232
	v_mul_f32_e32 v157, v163, v233
	v_mul_f32_e32 v158, v164, v234
	v_mul_f32_e32 v159, v165, v235
	v_cvt_pk_bf16_f32 v156, v156, v157
	v_cvt_pk_bf16_f32 v157, v158, v159
	v_add_f32_e32 v166, v72, v166
	v_add_f32_e32 v167, v73, v167
	v_add_f32_e32 v168, v74, v168
	v_add_f32_e32 v169, v75, v169
	global_store_dwordx4 v244, v[166:169], s[26:27] offset:448
	v_mul_f32_e32 v158, v166, v166
	v_mul_f32_e32 v159, v167, v167
	v_mul_f32_e32 v250, v168, v168
	v_mul_f32_e32 v251, v169, v169
	v_add_f32_e32 v158, v158, v159
	v_add_f32_e32 v250, v250, v251
	v_add_f32_e32 v158, v158, v250
	v_add_f32_e32 v161, v161, v158
	v_mul_f32_e32 v158, v166, v236
	v_mul_f32_e32 v159, v167, v237
	v_mul_f32_e32 v250, v168, v238
	v_mul_f32_e32 v251, v169, v239
	v_cvt_pk_bf16_f32 v158, v158, v159
	v_cvt_pk_bf16_f32 v159, v250, v251
	s_nop 1
	v_permlane16_swap_b32_e32 v156, v158
	v_permlane16_swap_b32_e32 v157, v159
	global_store_dwordx4 v254, v[156:159], s[28:29] offset:192
	ds_bpermute_b32 v158, v248, v161
	s_waitcnt lgkmcnt(0)
	v_add_f32_e32 v161, v161, v158
	ds_bpermute_b32 v158, v249, v161
	s_waitcnt lgkmcnt(0)
	v_add_f32_e32 v161, v161, v158
	global_store_dword v247, v161, s[30:31] offset:4
	s_add_u32 s26, s26, 0x10000
	s_addc_u32 s27, s27, 0
	s_add_u32 s28, s28, 0x8000
	s_addc_u32 s29, s29, 0
	s_add_u32 s30, s30, 0x400
	s_addc_u32 s31, s31, 0
	s_waitcnt vmcnt(25)
	v_add_f32_e32 v170, v132, v170
	v_add_f32_e32 v171, v133, v171
	v_add_f32_e32 v172, v134, v172
	v_add_f32_e32 v173, v135, v173
	global_store_dwordx4 v244, v[170:173], s[26:27]
	v_mul_f32_e32 v158, v170, v170
	v_mul_f32_e32 v159, v171, v171
	v_mul_f32_e32 v250, v172, v172
	v_mul_f32_e32 v251, v173, v173
	v_add_f32_e32 v158, v158, v159
	v_add_f32_e32 v250, v250, v251
	v_add_f32_e32 v161, v158, v250
	v_mul_f32_e32 v156, v170, v208
	v_mul_f32_e32 v157, v171, v209
	v_mul_f32_e32 v158, v172, v210
	v_mul_f32_e32 v159, v173, v211
	v_cvt_pk_bf16_f32 v156, v156, v157
	v_cvt_pk_bf16_f32 v157, v158, v159
	v_add_f32_e32 v174, v136, v174
	v_add_f32_e32 v175, v137, v175
	v_add_f32_e32 v176, v138, v176
	v_add_f32_e32 v177, v139, v177
	global_store_dwordx4 v244, v[174:177], s[26:27] offset:64
	v_mul_f32_e32 v158, v174, v174
	v_mul_f32_e32 v159, v175, v175
	v_mul_f32_e32 v250, v176, v176
	v_mul_f32_e32 v251, v177, v177
	v_add_f32_e32 v158, v158, v159
	v_add_f32_e32 v250, v250, v251
	v_add_f32_e32 v158, v158, v250
	v_add_f32_e32 v161, v161, v158
	v_mul_f32_e32 v158, v174, v212
	v_mul_f32_e32 v159, v175, v213
	v_mul_f32_e32 v250, v176, v214
	v_mul_f32_e32 v251, v177, v215
	v_cvt_pk_bf16_f32 v158, v158, v159
	v_cvt_pk_bf16_f32 v159, v250, v251
	s_nop 1
	v_permlane16_swap_b32_e32 v156, v158
	v_permlane16_swap_b32_e32 v157, v159
	global_store_dwordx4 v254, v[156:159], s[28:29]
	v_add_f32_e32 v178, v140, v178
	v_add_f32_e32 v179, v141, v179
	v_add_f32_e32 v180, v142, v180
	v_add_f32_e32 v181, v143, v181
	global_store_dwordx4 v244, v[178:181], s[26:27] offset:128
	v_mul_f32_e32 v158, v178, v178
	v_mul_f32_e32 v159, v179, v179
	v_mul_f32_e32 v250, v180, v180
	v_mul_f32_e32 v251, v181, v181
	v_add_f32_e32 v158, v158, v159
	v_add_f32_e32 v250, v250, v251
	v_add_f32_e32 v158, v158, v250
	v_add_f32_e32 v161, v161, v158
	v_mul_f32_e32 v156, v178, v216
	v_mul_f32_e32 v157, v179, v217
	v_mul_f32_e32 v158, v180, v218
	v_mul_f32_e32 v159, v181, v219
	v_cvt_pk_bf16_f32 v156, v156, v157
	v_cvt_pk_bf16_f32 v157, v158, v159
	v_add_f32_e32 v182, v144, v182
	v_add_f32_e32 v183, v145, v183
	v_add_f32_e32 v184, v146, v184
	v_add_f32_e32 v185, v147, v185
	global_store_dwordx4 v244, v[182:185], s[26:27] offset:192
	v_mul_f32_e32 v158, v182, v182
	v_mul_f32_e32 v159, v183, v183
	v_mul_f32_e32 v250, v184, v184
	v_mul_f32_e32 v251, v185, v185
	v_add_f32_e32 v158, v158, v159
	v_add_f32_e32 v250, v250, v251
	v_add_f32_e32 v158, v158, v250
	v_add_f32_e32 v161, v161, v158
	v_mul_f32_e32 v158, v182, v220
	v_mul_f32_e32 v159, v183, v221
	v_mul_f32_e32 v250, v184, v222
	v_mul_f32_e32 v251, v185, v223
	v_cvt_pk_bf16_f32 v158, v158, v159
	v_cvt_pk_bf16_f32 v159, v250, v251
	s_nop 1
	v_permlane16_swap_b32_e32 v156, v158
	v_permlane16_swap_b32_e32 v157, v159
	global_store_dwordx4 v254, v[156:159], s[28:29] offset:64
	ds_bpermute_b32 v158, v248, v161
	s_waitcnt lgkmcnt(0)
	v_add_f32_e32 v161, v161, v158
	ds_bpermute_b32 v158, v249, v161
	s_waitcnt lgkmcnt(0)
	v_add_f32_e32 v161, v161, v158
	global_store_dword v247, v161, s[30:31]
	s_waitcnt vmcnt(21)
	v_add_f32_e32 v186, v92, v186
	v_add_f32_e32 v187, v93, v187
	v_add_f32_e32 v188, v94, v188
	v_add_f32_e32 v189, v95, v189
	global_store_dwordx4 v244, v[186:189], s[26:27] offset:256
	v_mul_f32_e32 v158, v186, v186
	v_mul_f32_e32 v159, v187, v187
	v_mul_f32_e32 v250, v188, v188
	v_mul_f32_e32 v251, v189, v189
	v_add_f32_e32 v158, v158, v159
	v_add_f32_e32 v250, v250, v251
	v_add_f32_e32 v161, v158, v250
	v_mul_f32_e32 v156, v186, v224
	v_mul_f32_e32 v157, v187, v225
	v_mul_f32_e32 v158, v188, v226
	v_mul_f32_e32 v159, v189, v227
	v_cvt_pk_bf16_f32 v156, v156, v157
	v_cvt_pk_bf16_f32 v157, v158, v159
	v_add_f32_e32 v190, v88, v190
	v_add_f32_e32 v191, v89, v191
	v_add_f32_e32 v192, v90, v192
	v_add_f32_e32 v193, v91, v193
	global_store_dwordx4 v244, v[190:193], s[26:27] offset:320
	v_mul_f32_e32 v158, v190, v190
	v_mul_f32_e32 v159, v191, v191
	v_mul_f32_e32 v250, v192, v192
	v_mul_f32_e32 v251, v193, v193
	v_add_f32_e32 v158, v158, v159
	v_add_f32_e32 v250, v250, v251
	v_add_f32_e32 v158, v158, v250
	v_add_f32_e32 v161, v161, v158
	v_mul_f32_e32 v158, v190, v228
	v_mul_f32_e32 v159, v191, v229
	v_mul_f32_e32 v250, v192, v230
	v_mul_f32_e32 v251, v193, v231
	v_cvt_pk_bf16_f32 v158, v158, v159
	v_cvt_pk_bf16_f32 v159, v250, v251
	s_nop 1
	v_permlane16_swap_b32_e32 v156, v158
	v_permlane16_swap_b32_e32 v157, v159
	global_store_dwordx4 v254, v[156:159], s[28:29] offset:128
	v_add_f32_e32 v194, v76, v194
	v_add_f32_e32 v195, v77, v195
	v_add_f32_e32 v196, v78, v196
	v_add_f32_e32 v197, v79, v197
	global_store_dwordx4 v244, v[194:197], s[26:27] offset:384
	v_mul_f32_e32 v158, v194, v194
	v_mul_f32_e32 v159, v195, v195
	v_mul_f32_e32 v250, v196, v196
	v_mul_f32_e32 v251, v197, v197
	v_add_f32_e32 v158, v158, v159
	v_add_f32_e32 v250, v250, v251
	v_add_f32_e32 v158, v158, v250
	v_add_f32_e32 v161, v161, v158
	v_mul_f32_e32 v156, v194, v232
	v_mul_f32_e32 v157, v195, v233
	v_mul_f32_e32 v158, v196, v234
	v_mul_f32_e32 v159, v197, v235
	v_cvt_pk_bf16_f32 v156, v156, v157
	v_cvt_pk_bf16_f32 v157, v158, v159
	v_add_f32_e32 v240, v148, v240
	v_add_f32_e32 v241, v149, v241
	v_add_f32_e32 v242, v150, v242
	v_add_f32_e32 v243, v151, v243
	global_store_dwordx4 v244, v[240:243], s[26:27] offset:448
	v_mul_f32_e32 v158, v240, v240
	v_mul_f32_e32 v159, v241, v241
	v_mul_f32_e32 v250, v242, v242
	v_mul_f32_e32 v251, v243, v243
	v_add_f32_e32 v158, v158, v159
	v_add_f32_e32 v250, v250, v251
	v_add_f32_e32 v158, v158, v250
	v_add_f32_e32 v161, v161, v158
	v_mul_f32_e32 v158, v240, v236
	v_mul_f32_e32 v159, v241, v237
	v_mul_f32_e32 v250, v242, v238
	v_mul_f32_e32 v251, v243, v239
	v_cvt_pk_bf16_f32 v158, v158, v159
	v_cvt_pk_bf16_f32 v159, v250, v251
	s_nop 1
	v_permlane16_swap_b32_e32 v156, v158
	v_permlane16_swap_b32_e32 v157, v159
	global_store_dwordx4 v254, v[156:159], s[28:29] offset:192
	ds_bpermute_b32 v158, v248, v161
	s_waitcnt lgkmcnt(0)
	v_add_f32_e32 v161, v161, v158
	ds_bpermute_b32 v158, v249, v161
	s_waitcnt lgkmcnt(0)
	v_add_f32_e32 v161, v161, v158
	global_store_dword v247, v161, s[30:31] offset:4
	s_add_u32 s26, s26, 0x10000
	s_addc_u32 s27, s27, 0
	s_add_u32 s28, s28, 0x8000
	s_addc_u32 s29, s29, 0
	s_add_u32 s30, s30, 0x400
	s_addc_u32 s31, s31, 0
	s_branch .LBB0_360
